# H1/H3: SIMD-partner work balancing by wave relabel (waves 4-7 take sub-chunks 7..4) + H3 load hoisting; plus nosync+cvt4
# speedup vs baseline: 1.0008x; 1.0008x over previous
; __device__ __forceinline__ void h1_phase(unsigned char* lds, unsigned char* ws, bf16_t* SF, int G, int blk) {
;     int tid_l = threadIdx.x; asm volatile("" : "+v"(tid_l)); const int tid = tid_l, lane = tid & 63, wid = __builtin_amdgcn_readfirstlane(tid >> 6), r = lane & 15, kq = lane >> 4;
;     const bf16_t* Z = (const bf16_t*)(ws + WS_Z); bf16_t* VT = (bf16_t*)(lds + L_VT);
;     for (int unit = blk; unit < 2048; unit += G) {
;         const int b = unit >> 10, c = (unit >> 3) & 127, h = unit & 7, chain = b * 8 + h;
;         const bf16_t* zrow = Z + ((size_t)h * M + (size_t)b * SEQ + c * 128 + 16 * wid + r) * 128;
.LBB0_941:
	s_or_b64 exec, exec, s[4:5]
	s_mov_b64 s[4:5], s[0:1]
	s_mov_b32 s20, s2
	s_mov_b32 s21, s74
	s_waitcnt lgkmcnt(0)
	v_readfirstlane_b32 s62, v254
	s_lshr_b32 s62, s62, 6
	s_sub_u32 s63, 11, s62
	s_cmp_lt_u32 s62, 4
	s_cselect_b32 s62, s62, s63
	s_lshl_b32 s62, s62, 6
	v_and_b32_e32 v0, 63, v254
	v_or_b32_e32 v0, s62, v0
	s_barrier
	s_cmpk_gt_i32 s20, 0x7ff
	v_readfirstlane_b32 s3, v0
	s_cbranch_scc1 .LBB0_988
	s_load_dwordx4 s[8:11], s[4:5], 0x88
	v_and_b32_e32 v1, 15, v0
	v_lshrrev_b32_e32 v0, 1, v0
	v_and_b32_e32 v0, 24, v0
	v_lshlrev_b32_e32 v2, 1, v1
	s_waitcnt lgkmcnt(0)
	s_add_u32 s22, s8, 0x4000000
	s_addc_u32 s23, s9, 0
	s_add_u32 s6, s10, 0x6800000
	s_addc_u32 s7, s11, 0
	s_ashr_i32 s3, s3, 2
	s_and_b32 s3, s3, -16
	s_lshl_b32 s8, s3, 1
	s_add_i32 s8, s8, 0
	s_ashr_i32 s9, s3, 31
	s_add_u32 s24, s10, 0x1fa00000
	s_addc_u32 s25, s11, 0
	v_or_b32_e32 v32, s3, v1
	s_add_u32 s26, s10, 0x1a800000
	v_mul_u32_u24_e32 v1, 0x88, v0
	s_addc_u32 s27, s11, 0
	v_lshlrev_b32_e32 v1, 1, v1
	s_add_i32 s8, s8, 0x13000
	v_mov_b32_e32 v35, 0
	v_add3_u32 v81, v1, s8, v2
	s_mov_b64 s[4:5], 0x4000000
	v_mov_b32_e32 v33, s9
	v_add3_u32 v80, s8, v2, v1
	v_add_u32_e32 v82, 0x220, v81
	v_add_u32_e32 v83, 0x440, v81
	v_add_u32_e32 v84, 0x660, v81
	v_add_u32_e32 v85, 0x2200, v81
	v_add_u32_e32 v86, 0x2420, v81
	v_add_u32_e32 v87, 0x2640, v81
	v_add_u32_e32 v88, 0x2860, v81
	v_add_u32_e32 v89, 0x4400, v81
	v_add_u32_e32 v90, 0x4620, v81
	v_add_u32_e32 v91, 0x4840, v81
	v_add_u32_e32 v92, 0x4a60, v81
	v_add_u32_e32 v93, 0x6600, v81
	v_add_u32_e32 v94, 0x6820, v81
	v_add_u32_e32 v95, 0x6a40, v81
	v_add_u32_e32 v96, 0x6c60, v81
	v_lshlrev_b32_e32 v36, 1, v0
	v_mov_b32_e32 v37, v35
	s_mov_b64 s[8:9], 0xc000000
	s_brev_b32 s28, 48
	s_brev_b32 s29, 32
	s_movk_i32 s30, 0x110
	s_mov_b64 s[10:11], 0x8000000
	s_brev_b32 s31, 16
	s_mov_b64 s[12:13], 0x100000
	s_mov_b32 s34, 0x100000
	s_add_i32 s35, 0, 0x13000
	s_branch .LBB0_944

; template <int DIR> __device__ __forceinline__ void h1_dir(unsigned char* lds, const bf16_t* zrow, int h, bf16_t* slot, float* decp) {
;     int tid_l = threadIdx.x; asm volatile("" : "+v"(tid_l)); const int tid = tid_l, lane = tid & 63, wid = __builtin_amdgcn_readfirstlane(tid >> 6), r = lane & 15, kq = lane >> 4;
;     float* TOT = (float*)(lds + L_TOT); bf16_t* KS = (bf16_t*)(lds + L_KO); bf16_t* VT = (bf16_t*)(lds + L_VT); bf16_t* STG = (bf16_t*)(lds + L_ST);
;     float bl[32], kk[32];
;     load32(zrow + (size_t)(1 + DIR) * ZSEG + 8 * kq, bl);
; #pragma unroll
;     for (int i = 0; i < 32; ++i) kk[i] = 1.0f - __builtin_amdgcn_exp2f(bl[i]);
;         scan16x8<DIR>(bl); scan16x8<DIR>(bl + 8); scan16x8<DIR>(bl + 16); scan16x8<DIR>(bl + 24);
; __device__ __forceinline__ void h1_phase(unsigned char* lds, unsigned char* ws, bf16_t* SF, int G, int blk) {
;     ...
;     for (int unit = blk; unit < 2048; unit += G) {
;         const int b = unit >> 10, c = (unit >> 3) & 127, h = unit & 7, chain = b * 8 + h;
;         const bf16_t* zrow = Z + ((size_t)h * M + (size_t)b * SEQ + c * 128 + 16 * wid + r) * 128;
;         {
; #pragma unroll
;           for (int ks = 0; ks < 4; ++ks) { const u32x4 w = *(const u32x4*)(zrow + 3 * ZSEG + 8 * kq + 32 * ks);
; #pragma unroll
;               for (int e = 0; e < 4; ++e) { VT[(32 * ks + 8 * kq + 2 * e) * HP + 16 * wid + r] = (bf16_t)(w[e] & 0xffffu); VT[(32 * ks + 8 * kq + 2 * e + 1) * HP + 16 * wid + r] = (bf16_t)(w[e] >> 16); } } }
.LBB0_944:
	s_ashr_i32 s14, s20, 10
	s_bfe_u32 s36, s20, 0x70003
	s_ashr_i32 s15, s14, 31
	s_and_b32 s38, s20, 7
	s_lshl_b64 s[16:17], s[14:15], 14
	s_lshl_b32 s15, s36, 7
	s_lshl_b32 s3, s38, 15
	s_or_b32 s15, s16, s15
	s_add_u32 s16, s15, s3
	s_addc_u32 s17, s17, 0
	v_lshl_add_u64 v[0:1], s[16:17], 0, v[32:33]
	v_lshlrev_b64 v[0:1], 8, v[0:1]
	v_lshl_add_u64 v[38:39], s[6:7], 0, v[0:1]
	v_lshl_add_u64 v[4:5], v[38:39], 0, v[36:37]
	v_add_co_u32_e32 v0, vcc, s28, v4
	v_lshl_add_u64 v[16:17], v[4:5], 0, s[8:9]
	s_nop 0
	v_addc_co_u32_e32 v1, vcc, 0, v5, vcc
	global_load_dwordx4 v[0:3], v[0:1], off
	s_nop 0
	global_load_dwordx4 v[4:7], v[16:17], off offset:64
	global_load_dwordx4 v[8:11], v[16:17], off offset:128
	global_load_dwordx4 v[12:15], v[16:17], off offset:192
	v_and_b32_e32 v97, 63, v254
	v_or_b32_e32 v97, s62, v97
	s_waitcnt vmcnt(3)
	ds_write_b16 v80, v0
	ds_write_b16_d16_hi v81, v0 offset:272
	ds_write_b16 v80, v1 offset:544
	ds_write_b16_d16_hi v82, v1 offset:272
	ds_write_b16 v80, v2 offset:1088
	ds_write_b16_d16_hi v83, v2 offset:272
	ds_write_b16 v80, v3 offset:1632
	ds_write_b16_d16_hi v84, v3 offset:272
	s_waitcnt vmcnt(2)
	ds_write_b16 v80, v4 offset:8704
	ds_write_b16_d16_hi v85, v4 offset:272
	ds_write_b16 v80, v5 offset:9248
	ds_write_b16_d16_hi v86, v5 offset:272
	ds_write_b16 v80, v6 offset:9792
	ds_write_b16_d16_hi v87, v6 offset:272
	ds_write_b16 v80, v7 offset:10336
	ds_write_b16_d16_hi v88, v7 offset:272
	s_waitcnt vmcnt(1)
	ds_write_b16 v80, v8 offset:17408
	ds_write_b16_d16_hi v89, v8 offset:272
	ds_write_b16 v80, v9 offset:17952
	ds_write_b16_d16_hi v90, v9 offset:272
	ds_write_b16 v80, v10 offset:18496
	ds_write_b16_d16_hi v91, v10 offset:272
	ds_write_b16 v80, v11 offset:19040
	ds_write_b16_d16_hi v92, v11 offset:272
	s_waitcnt vmcnt(0)
	ds_write_b16 v80, v12 offset:26112
	ds_write_b16_d16_hi v93, v12 offset:272
	ds_write_b16 v80, v13 offset:26656
	ds_write_b16_d16_hi v94, v13 offset:272
	ds_write_b16 v80, v14 offset:27200
	ds_write_b16_d16_hi v95, v14 offset:272
	ds_write_b16 v80, v15 offset:27744
	ds_write_b16_d16_hi v96, v15 offset:272
	s_nop 0
	v_bfe_u32 v98, v97, 4, 2
	v_lshlrev_b32_e32 v34, 4, v98
	v_lshl_add_u64 v[4:5], v[38:39], 0, v[34:35]
	v_add_co_u32_e32 v0, vcc, s29, v4
	v_lshl_add_u64 v[16:17], v[4:5], 0, s[4:5]
	s_nop 0
	v_addc_co_u32_e32 v1, vcc, 0, v5, vcc
	global_load_dwordx4 v[0:3], v[0:1], off
	s_nop 0
	global_load_dwordx4 v[4:7], v[16:17], off offset:64
	global_load_dwordx4 v[8:11], v[16:17], off offset:128
	global_load_dwordx4 v[12:15], v[16:17], off offset:192
	v_readfirstlane_b32 s3, v97
	v_and_b32_e32 v99, 15, v97
	s_ashr_i32 s37, s3, 6
	v_lshlrev_b32_e32 v100, 3, v98
	v_cmp_eq_u32_e32 vcc, 15, v99
	s_waitcnt vmcnt(2)
	v_lshlrev_b32_e32 v109, 16, v4
	v_lshlrev_b32_e32 v101, 16, v0
	v_and_b32_e32 v102, 0xffff0000, v0
	v_lshlrev_b32_e32 v103, 16, v1
	v_and_b32_e32 v104, 0xffff0000, v1
	v_lshlrev_b32_e32 v105, 16, v2
	v_and_b32_e32 v106, 0xffff0000, v2
	v_lshlrev_b32_e32 v107, 16, v3
	v_and_b32_e32 v108, 0xffff0000, v3
	v_mov_b32_e32 v21, v106
	v_mov_b32_e32 v28, v101
	v_mov_b32_e32 v23, v108
	v_mov_b32_e32 v30, v103
	v_mov_b32_e32 v20, v105
	v_mov_b32_e32 v22, v107
	v_mov_b32_e32 v29, v102
	v_mov_b32_e32 v31, v104
	s_nop 1
	v_add_f32_dpp v28, v28, v28 row_shr:1 row_mask:0xf bank_mask:0xf bound_ctrl:1
	v_add_f32_dpp v29, v29, v29 row_shr:1 row_mask:0xf bank_mask:0xf bound_ctrl:1
	v_add_f32_dpp v30, v30, v30 row_shr:1 row_mask:0xf bank_mask:0xf bound_ctrl:1
	v_add_f32_dpp v31, v31, v31 row_shr:1 row_mask:0xf bank_mask:0xf bound_ctrl:1
	v_add_f32_dpp v20, v20, v20 row_shr:1 row_mask:0xf bank_mask:0xf bound_ctrl:1
	v_add_f32_dpp v21, v21, v21 row_shr:1 row_mask:0xf bank_mask:0xf bound_ctrl:1
	v_add_f32_dpp v22, v22, v22 row_shr:1 row_mask:0xf bank_mask:0xf bound_ctrl:1
	v_add_f32_dpp v23, v23, v23 row_shr:1 row_mask:0xf bank_mask:0xf bound_ctrl:1
	v_and_b32_e32 v110, 0xffff0000, v4
	v_lshlrev_b32_e32 v111, 16, v5
	v_and_b32_e32 v112, 0xffff0000, v5
	v_lshlrev_b32_e32 v113, 16, v6
	v_and_b32_e32 v114, 0xffff0000, v6
	v_lshlrev_b32_e32 v115, 16, v7
	v_and_b32_e32 v116, 0xffff0000, v7
	s_nop 1
	v_add_f32_dpp v28, v28, v28 row_shr:2 row_mask:0xf bank_mask:0xf bound_ctrl:1
	v_add_f32_dpp v29, v29, v29 row_shr:2 row_mask:0xf bank_mask:0xf bound_ctrl:1
	v_add_f32_dpp v30, v30, v30 row_shr:2 row_mask:0xf bank_mask:0xf bound_ctrl:1
	v_add_f32_dpp v31, v31, v31 row_shr:2 row_mask:0xf bank_mask:0xf bound_ctrl:1
	v_add_f32_dpp v20, v20, v20 row_shr:2 row_mask:0xf bank_mask:0xf bound_ctrl:1
	v_add_f32_dpp v21, v21, v21 row_shr:2 row_mask:0xf bank_mask:0xf bound_ctrl:1
	v_add_f32_dpp v22, v22, v22 row_shr:2 row_mask:0xf bank_mask:0xf bound_ctrl:1
	v_add_f32_dpp v23, v23, v23 row_shr:2 row_mask:0xf bank_mask:0xf bound_ctrl:1
	s_waitcnt vmcnt(0)
; template <int DIR> __device__ __forceinline__ void scan16x8(float* v) {
;     if (DIR == 0) { SCAN_STEP("row_shr:", 1); SCAN_STEP("row_shr:", 2); SCAN_STEP("row_shr:", 4); SCAN_STEP("row_shr:", 8); }
;     else          { SCAN_STEP("row_shl:", 1); SCAN_STEP("row_shl:", 2); SCAN_STEP("row_shl:", 4); SCAN_STEP("row_shl:", 8); }
; }
; template <int DIR> __device__ __forceinline__ void h1_dir(unsigned char* lds, const bf16_t* zrow, int h, bf16_t* slot, float* decp) {
;     ...
;         scan16x8<DIR>(bl); scan16x8<DIR>(bl + 8); scan16x8<DIR>(bl + 16); scan16x8<DIR>(bl + 24);
	v_lshlrev_b32_e32 v78, 16, v12
	v_and_b32_e32 v79, 0xffff0000, v12
	v_lshlrev_b32_e32 v76, 16, v13
	v_and_b32_e32 v77, 0xffff0000, v13
	v_lshlrev_b32_e32 v74, 16, v14
	v_and_b32_e32 v75, 0xffff0000, v14
	v_lshlrev_b32_e32 v72, 16, v15
	v_and_b32_e32 v73, 0xffff0000, v15
	v_mov_b32_e32 v13, v114
	v_mov_b32_e32 v24, v109
	v_mov_b32_e32 v15, v116
	v_mov_b32_e32 v26, v111
	v_mov_b32_e32 v12, v113
	v_mov_b32_e32 v14, v115
	v_mov_b32_e32 v25, v110
	v_mov_b32_e32 v27, v112
	s_nop 1
	v_add_f32_dpp v28, v28, v28 row_shr:4 row_mask:0xf bank_mask:0xf bound_ctrl:1
	v_add_f32_dpp v29, v29, v29 row_shr:4 row_mask:0xf bank_mask:0xf bound_ctrl:1
	v_add_f32_dpp v30, v30, v30 row_shr:4 row_mask:0xf bank_mask:0xf bound_ctrl:1
	v_add_f32_dpp v31, v31, v31 row_shr:4 row_mask:0xf bank_mask:0xf bound_ctrl:1
	v_add_f32_dpp v20, v20, v20 row_shr:4 row_mask:0xf bank_mask:0xf bound_ctrl:1
	v_add_f32_dpp v21, v21, v21 row_shr:4 row_mask:0xf bank_mask:0xf bound_ctrl:1
	v_add_f32_dpp v22, v22, v22 row_shr:4 row_mask:0xf bank_mask:0xf bound_ctrl:1
	v_add_f32_dpp v23, v23, v23 row_shr:4 row_mask:0xf bank_mask:0xf bound_ctrl:1
	v_lshlrev_b32_e32 v117, 16, v8
	s_nop 1
	v_add_f32_dpp v28, v28, v28 row_shr:8 row_mask:0xf bank_mask:0xf bound_ctrl:1
	v_add_f32_dpp v29, v29, v29 row_shr:8 row_mask:0xf bank_mask:0xf bound_ctrl:1
	v_add_f32_dpp v30, v30, v30 row_shr:8 row_mask:0xf bank_mask:0xf bound_ctrl:1
	v_add_f32_dpp v31, v31, v31 row_shr:8 row_mask:0xf bank_mask:0xf bound_ctrl:1
	v_add_f32_dpp v20, v20, v20 row_shr:8 row_mask:0xf bank_mask:0xf bound_ctrl:1
	v_add_f32_dpp v21, v21, v21 row_shr:8 row_mask:0xf bank_mask:0xf bound_ctrl:1
	v_add_f32_dpp v22, v22, v22 row_shr:8 row_mask:0xf bank_mask:0xf bound_ctrl:1
	v_add_f32_dpp v23, v23, v23 row_shr:8 row_mask:0xf bank_mask:0xf bound_ctrl:1
	s_nop 1
	v_add_f32_dpp v24, v24, v24 row_shr:1 row_mask:0xf bank_mask:0xf bound_ctrl:1
	v_add_f32_dpp v25, v25, v25 row_shr:1 row_mask:0xf bank_mask:0xf bound_ctrl:1
	v_add_f32_dpp v26, v26, v26 row_shr:1 row_mask:0xf bank_mask:0xf bound_ctrl:1
	v_add_f32_dpp v27, v27, v27 row_shr:1 row_mask:0xf bank_mask:0xf bound_ctrl:1
	v_add_f32_dpp v12, v12, v12 row_shr:1 row_mask:0xf bank_mask:0xf bound_ctrl:1
	v_add_f32_dpp v13, v13, v13 row_shr:1 row_mask:0xf bank_mask:0xf bound_ctrl:1
	v_add_f32_dpp v14, v14, v14 row_shr:1 row_mask:0xf bank_mask:0xf bound_ctrl:1
	v_add_f32_dpp v15, v15, v15 row_shr:1 row_mask:0xf bank_mask:0xf bound_ctrl:1
	v_and_b32_e32 v118, 0xffff0000, v8
	v_lshlrev_b32_e32 v119, 16, v9
	v_and_b32_e32 v120, 0xffff0000, v9
	v_lshlrev_b32_e32 v121, 16, v10
	v_and_b32_e32 v122, 0xffff0000, v10
	v_lshlrev_b32_e32 v123, 16, v11
	v_and_b32_e32 v124, 0xffff0000, v11
	s_nop 1
	v_add_f32_dpp v24, v24, v24 row_shr:2 row_mask:0xf bank_mask:0xf bound_ctrl:1
	v_add_f32_dpp v25, v25, v25 row_shr:2 row_mask:0xf bank_mask:0xf bound_ctrl:1
	v_add_f32_dpp v26, v26, v26 row_shr:2 row_mask:0xf bank_mask:0xf bound_ctrl:1
	v_add_f32_dpp v27, v27, v27 row_shr:2 row_mask:0xf bank_mask:0xf bound_ctrl:1
	v_add_f32_dpp v12, v12, v12 row_shr:2 row_mask:0xf bank_mask:0xf bound_ctrl:1
	v_add_f32_dpp v13, v13, v13 row_shr:2 row_mask:0xf bank_mask:0xf bound_ctrl:1
	v_add_f32_dpp v14, v14, v14 row_shr:2 row_mask:0xf bank_mask:0xf bound_ctrl:1
	v_add_f32_dpp v15, v15, v15 row_shr:2 row_mask:0xf bank_mask:0xf bound_ctrl:1
	v_mov_b32_e32 v5, v122
	v_mov_b32_e32 v16, v117
	v_mov_b32_e32 v7, v124
	v_mov_b32_e32 v18, v119
	v_mov_b32_e32 v4, v121
	v_mov_b32_e32 v6, v123
	v_mov_b32_e32 v17, v118
	v_mov_b32_e32 v19, v120
	s_nop 1
	v_add_f32_dpp v24, v24, v24 row_shr:4 row_mask:0xf bank_mask:0xf bound_ctrl:1
	v_add_f32_dpp v25, v25, v25 row_shr:4 row_mask:0xf bank_mask:0xf bound_ctrl:1
	v_add_f32_dpp v26, v26, v26 row_shr:4 row_mask:0xf bank_mask:0xf bound_ctrl:1
	v_add_f32_dpp v27, v27, v27 row_shr:4 row_mask:0xf bank_mask:0xf bound_ctrl:1
	v_add_f32_dpp v12, v12, v12 row_shr:4 row_mask:0xf bank_mask:0xf bound_ctrl:1
	v_add_f32_dpp v13, v13, v13 row_shr:4 row_mask:0xf bank_mask:0xf bound_ctrl:1
	v_add_f32_dpp v14, v14, v14 row_shr:4 row_mask:0xf bank_mask:0xf bound_ctrl:1
	v_add_f32_dpp v15, v15, v15 row_shr:4 row_mask:0xf bank_mask:0xf bound_ctrl:1
	v_mov_b32_e32 v1, v75
	s_nop 1
	v_add_f32_dpp v24, v24, v24 row_shr:8 row_mask:0xf bank_mask:0xf bound_ctrl:1
	v_add_f32_dpp v25, v25, v25 row_shr:8 row_mask:0xf bank_mask:0xf bound_ctrl:1
	v_add_f32_dpp v26, v26, v26 row_shr:8 row_mask:0xf bank_mask:0xf bound_ctrl:1
	v_add_f32_dpp v27, v27, v27 row_shr:8 row_mask:0xf bank_mask:0xf bound_ctrl:1
	v_add_f32_dpp v12, v12, v12 row_shr:8 row_mask:0xf bank_mask:0xf bound_ctrl:1
	v_add_f32_dpp v13, v13, v13 row_shr:8 row_mask:0xf bank_mask:0xf bound_ctrl:1
	v_add_f32_dpp v14, v14, v14 row_shr:8 row_mask:0xf bank_mask:0xf bound_ctrl:1
	v_add_f32_dpp v15, v15, v15 row_shr:8 row_mask:0xf bank_mask:0xf bound_ctrl:1
	s_nop 1
	v_add_f32_dpp v16, v16, v16 row_shr:1 row_mask:0xf bank_mask:0xf bound_ctrl:1
	v_add_f32_dpp v17, v17, v17 row_shr:1 row_mask:0xf bank_mask:0xf bound_ctrl:1
	v_add_f32_dpp v18, v18, v18 row_shr:1 row_mask:0xf bank_mask:0xf bound_ctrl:1
	v_add_f32_dpp v19, v19, v19 row_shr:1 row_mask:0xf bank_mask:0xf bound_ctrl:1
	v_add_f32_dpp v4, v4, v4 row_shr:1 row_mask:0xf bank_mask:0xf bound_ctrl:1
; template <int DIR> __device__ __forceinline__ void h1_dir(unsigned char* lds, const bf16_t* zrow, int h, bf16_t* slot, float* decp) {
;     ...
;         scan16x8<DIR>(bl); scan16x8<DIR>(bl + 8); scan16x8<DIR>(bl + 16); scan16x8<DIR>(bl + 24);
;     if (r == (DIR ? 0 : 15)) {
; #pragma unroll
;         for (int ks = 0; ks < 4; ++ks) { *(f32x4*)(TOT + wid * 128 + 32 * ks + 8 * kq) = (f32x4){bl[8 * ks], bl[8 * ks + 1], bl[8 * ks + 2], bl[8 * ks + 3]}; *(f32x4*)(TOT + wid * 128 + 32 * ks + 8 * kq + 4) = (f32x4){bl[8 * ks + 4], bl[8 * ks + 5], bl[8 * ks + 6], bl[8 * ks + 7]}; }
;     }
	v_add_f32_dpp v5, v5, v5 row_shr:1 row_mask:0xf bank_mask:0xf bound_ctrl:1
	v_add_f32_dpp v6, v6, v6 row_shr:1 row_mask:0xf bank_mask:0xf bound_ctrl:1
	v_add_f32_dpp v7, v7, v7 row_shr:1 row_mask:0xf bank_mask:0xf bound_ctrl:1
	v_mov_b32_e32 v8, v78
	s_nop 1
	v_add_f32_dpp v16, v16, v16 row_shr:2 row_mask:0xf bank_mask:0xf bound_ctrl:1
	v_add_f32_dpp v17, v17, v17 row_shr:2 row_mask:0xf bank_mask:0xf bound_ctrl:1
	v_add_f32_dpp v18, v18, v18 row_shr:2 row_mask:0xf bank_mask:0xf bound_ctrl:1
	v_add_f32_dpp v19, v19, v19 row_shr:2 row_mask:0xf bank_mask:0xf bound_ctrl:1
	v_add_f32_dpp v4, v4, v4 row_shr:2 row_mask:0xf bank_mask:0xf bound_ctrl:1
	v_add_f32_dpp v5, v5, v5 row_shr:2 row_mask:0xf bank_mask:0xf bound_ctrl:1
	v_add_f32_dpp v6, v6, v6 row_shr:2 row_mask:0xf bank_mask:0xf bound_ctrl:1
	v_add_f32_dpp v7, v7, v7 row_shr:2 row_mask:0xf bank_mask:0xf bound_ctrl:1
	v_mov_b32_e32 v3, v73
	v_mov_b32_e32 v10, v76
	v_mov_b32_e32 v0, v74
	v_mov_b32_e32 v2, v72
	v_mov_b32_e32 v9, v79
	v_mov_b32_e32 v11, v77
	s_nop 1
	v_add_f32_dpp v16, v16, v16 row_shr:4 row_mask:0xf bank_mask:0xf bound_ctrl:1
	v_add_f32_dpp v17, v17, v17 row_shr:4 row_mask:0xf bank_mask:0xf bound_ctrl:1
	v_add_f32_dpp v18, v18, v18 row_shr:4 row_mask:0xf bank_mask:0xf bound_ctrl:1
	v_add_f32_dpp v19, v19, v19 row_shr:4 row_mask:0xf bank_mask:0xf bound_ctrl:1
	v_add_f32_dpp v4, v4, v4 row_shr:4 row_mask:0xf bank_mask:0xf bound_ctrl:1
	v_add_f32_dpp v5, v5, v5 row_shr:4 row_mask:0xf bank_mask:0xf bound_ctrl:1
	v_add_f32_dpp v6, v6, v6 row_shr:4 row_mask:0xf bank_mask:0xf bound_ctrl:1
	v_add_f32_dpp v7, v7, v7 row_shr:4 row_mask:0xf bank_mask:0xf bound_ctrl:1
	s_nop 0
	s_nop 1
	v_add_f32_dpp v16, v16, v16 row_shr:8 row_mask:0xf bank_mask:0xf bound_ctrl:1
	v_add_f32_dpp v17, v17, v17 row_shr:8 row_mask:0xf bank_mask:0xf bound_ctrl:1
	v_add_f32_dpp v18, v18, v18 row_shr:8 row_mask:0xf bank_mask:0xf bound_ctrl:1
	v_add_f32_dpp v19, v19, v19 row_shr:8 row_mask:0xf bank_mask:0xf bound_ctrl:1
	v_add_f32_dpp v4, v4, v4 row_shr:8 row_mask:0xf bank_mask:0xf bound_ctrl:1
	v_add_f32_dpp v5, v5, v5 row_shr:8 row_mask:0xf bank_mask:0xf bound_ctrl:1
	v_add_f32_dpp v6, v6, v6 row_shr:8 row_mask:0xf bank_mask:0xf bound_ctrl:1
	v_add_f32_dpp v7, v7, v7 row_shr:8 row_mask:0xf bank_mask:0xf bound_ctrl:1
	s_nop 1
	v_add_f32_dpp v8, v8, v8 row_shr:1 row_mask:0xf bank_mask:0xf bound_ctrl:1
	v_add_f32_dpp v9, v9, v9 row_shr:1 row_mask:0xf bank_mask:0xf bound_ctrl:1
	v_add_f32_dpp v10, v10, v10 row_shr:1 row_mask:0xf bank_mask:0xf bound_ctrl:1
	v_add_f32_dpp v11, v11, v11 row_shr:1 row_mask:0xf bank_mask:0xf bound_ctrl:1
	v_add_f32_dpp v0, v0, v0 row_shr:1 row_mask:0xf bank_mask:0xf bound_ctrl:1
	v_add_f32_dpp v1, v1, v1 row_shr:1 row_mask:0xf bank_mask:0xf bound_ctrl:1
	v_add_f32_dpp v2, v2, v2 row_shr:1 row_mask:0xf bank_mask:0xf bound_ctrl:1
	v_add_f32_dpp v3, v3, v3 row_shr:1 row_mask:0xf bank_mask:0xf bound_ctrl:1
	s_nop 0
	s_nop 1
	v_add_f32_dpp v8, v8, v8 row_shr:2 row_mask:0xf bank_mask:0xf bound_ctrl:1
	v_add_f32_dpp v9, v9, v9 row_shr:2 row_mask:0xf bank_mask:0xf bound_ctrl:1
	v_add_f32_dpp v10, v10, v10 row_shr:2 row_mask:0xf bank_mask:0xf bound_ctrl:1
	v_add_f32_dpp v11, v11, v11 row_shr:2 row_mask:0xf bank_mask:0xf bound_ctrl:1
	v_add_f32_dpp v0, v0, v0 row_shr:2 row_mask:0xf bank_mask:0xf bound_ctrl:1
	v_add_f32_dpp v1, v1, v1 row_shr:2 row_mask:0xf bank_mask:0xf bound_ctrl:1
	v_add_f32_dpp v2, v2, v2 row_shr:2 row_mask:0xf bank_mask:0xf bound_ctrl:1
	v_add_f32_dpp v3, v3, v3 row_shr:2 row_mask:0xf bank_mask:0xf bound_ctrl:1
	s_nop 0
	s_nop 1
	v_add_f32_dpp v8, v8, v8 row_shr:4 row_mask:0xf bank_mask:0xf bound_ctrl:1
	v_add_f32_dpp v9, v9, v9 row_shr:4 row_mask:0xf bank_mask:0xf bound_ctrl:1
	v_add_f32_dpp v10, v10, v10 row_shr:4 row_mask:0xf bank_mask:0xf bound_ctrl:1
	v_add_f32_dpp v11, v11, v11 row_shr:4 row_mask:0xf bank_mask:0xf bound_ctrl:1
	v_add_f32_dpp v0, v0, v0 row_shr:4 row_mask:0xf bank_mask:0xf bound_ctrl:1
	v_add_f32_dpp v1, v1, v1 row_shr:4 row_mask:0xf bank_mask:0xf bound_ctrl:1
	v_add_f32_dpp v2, v2, v2 row_shr:4 row_mask:0xf bank_mask:0xf bound_ctrl:1
	v_add_f32_dpp v3, v3, v3 row_shr:4 row_mask:0xf bank_mask:0xf bound_ctrl:1
	s_nop 0
	s_nop 1
	v_add_f32_dpp v8, v8, v8 row_shr:8 row_mask:0xf bank_mask:0xf bound_ctrl:1
	v_add_f32_dpp v9, v9, v9 row_shr:8 row_mask:0xf bank_mask:0xf bound_ctrl:1
	v_add_f32_dpp v10, v10, v10 row_shr:8 row_mask:0xf bank_mask:0xf bound_ctrl:1
	v_add_f32_dpp v11, v11, v11 row_shr:8 row_mask:0xf bank_mask:0xf bound_ctrl:1
	v_add_f32_dpp v0, v0, v0 row_shr:8 row_mask:0xf bank_mask:0xf bound_ctrl:1
	v_add_f32_dpp v1, v1, v1 row_shr:8 row_mask:0xf bank_mask:0xf bound_ctrl:1
	v_add_f32_dpp v2, v2, v2 row_shr:8 row_mask:0xf bank_mask:0xf bound_ctrl:1
	v_add_f32_dpp v3, v3, v3 row_shr:8 row_mask:0xf bank_mask:0xf bound_ctrl:1
	s_and_saveexec_b64 s[16:17], vcc
	s_cbranch_execz .LBB0_946
	s_lshl_b32 s15, s37, 9
	s_add_i32 s15, s15, 0
	v_lshl_add_u32 v34, v100, 2, s15
	ds_write_b128 v34, v[28:31]
	ds_write_b128 v34, v[20:23] offset:16
	ds_write_b128 v34, v[24:27] offset:128
	ds_write_b128 v34, v[12:15] offset:144
	ds_write_b128 v34, v[16:19] offset:256
	ds_write_b128 v34, v[4:7] offset:272
	ds_write_b128 v34, v[8:11] offset:384
	ds_write_b128 v34, v[0:3] offset:400

; __device__ __forceinline__ unsigned cvt_pk_c(float lo, float hi) { const f32x2_cv v = {lo, hi}; const bf16x2_cv b = __builtin_convertvector(v, bf16x2_cv); return __builtin_bit_cast(unsigned, b); }
; template <int DIR> __device__ __forceinline__ void h1_dir(unsigned char* lds, const bf16_t* zrow, int h, bf16_t* slot, float* decp) {
;     ...
;         for (int ks = 0; ks < 4; ++ks)
; #pragma unroll
;             for (int e = 0; e < 8; e += 2) { const unsigned w = cvt_pk_c(kk[8 * ks + e] * __builtin_amdgcn_exp2f(aft[8 * ks + e] - bl[8 * ks + e]), kk[8 * ks + e + 1] * __builtin_amdgcn_exp2f(aft[8 * ks + e + 1] - bl[8 * ks + e + 1]));
;                 KS[(32 * ks + 8 * kq + e) * HP + 16 * wid + r] = (bf16_t)(w & 0xffffu); KS[(32 * ks + 8 * kq + e + 1) * HP + 16 * wid + r] = (bf16_t)(w >> 16); }
.LBB0_966:
	s_or_b64 exec, exec, s[18:19]
	v_exp_f32_e32 v140, v123
	v_exp_f32_e32 v123, v122
	v_exp_f32_e32 v122, v121
	v_exp_f32_e32 v121, v120
	v_exp_f32_e32 v120, v119
	v_exp_f32_e32 v119, v118
	v_exp_f32_e32 v118, v117
	v_exp_f32_e32 v117, v116
	v_exp_f32_e32 v116, v115
	v_exp_f32_e32 v115, v114
	v_exp_f32_e32 v114, v113
	v_exp_f32_e32 v113, v112
	v_exp_f32_e32 v112, v111
	v_exp_f32_e32 v111, v110
	v_exp_f32_e32 v110, v109
	v_exp_f32_e32 v109, v108
	v_exp_f32_e32 v108, v107
	v_exp_f32_e32 v107, v106
	v_exp_f32_e32 v106, v105
	v_exp_f32_e32 v105, v104
	v_exp_f32_e32 v104, v103
	v_exp_f32_e32 v103, v102
	v_exp_f32_e32 v102, v101
	v_sub_f32_e32 v28, v70, v28
	v_sub_f32_e32 v29, v71, v29
	v_exp_f32_e32 v28, v28
	v_exp_f32_e32 v29, v29
	s_lshl_b64 s[18:19], s[14:15], 15
	s_add_u32 s18, s22, s18
	v_pk_add_f32 v[70:71], v[102:103], 1.0 op_sel_hi:[1,0] neg_lo:[1,0] neg_hi:[1,0]
	s_addc_u32 s19, s23, s19
	s_lshl_b32 s3, s37, 4
	s_lshl_b32 s37, s37, 5
	v_pk_mul_f32 v[28:29], v[70:71], v[28:29]
	v_exp_f32_e32 v141, v124
	s_add_i32 s37, s37, 0
	v_lshlrev_b32_e32 v124, 1, v99
	v_cvt_pk_bf16_f32 v70, v28, v29
	v_mul_u32_u24_e32 v28, 0x440, v98
	v_add_u32_e32 v101, s37, v124
	v_lshlrev_b32_e32 v71, 1, v28
	v_add_u32_e32 v28, v101, v71
	ds_write_b16 v28, v70 offset:8192
	v_sub_f32_e32 v28, v68, v30
	v_sub_f32_e32 v29, v69, v31
	v_exp_f32_e32 v28, v28
	v_exp_f32_e32 v29, v29
	v_add3_u32 v30, s37, v71, v124
	ds_write_b16_d16_hi v30, v70 offset:8464
	v_pk_add_f32 v[30:31], v[104:105], 1.0 op_sel_hi:[1,0] neg_lo:[1,0] neg_hi:[1,0]
	v_sub_f32_e32 v20, v66, v20
	v_pk_mul_f32 v[28:29], v[30:31], v[28:29]
	v_sub_f32_e32 v21, v67, v21
	v_cvt_pk_bf16_f32 v28, v28, v29
	v_mul_i32_i24_e32 v29, 0x88, v138
	v_exp_f32_e32 v20, v20
	v_exp_f32_e32 v21, v21
	v_lshlrev_b32_e32 v29, 1, v29
	v_add_u32_e32 v30, v101, v29
	v_add3_u32 v29, s37, v29, v124
	ds_write_b16 v30, v28 offset:8192
	ds_write_b16_d16_hi v29, v28 offset:8464
	v_pk_add_f32 v[28:29], v[106:107], 1.0 op_sel_hi:[1,0] neg_lo:[1,0] neg_hi:[1,0]
	v_sub_f32_e32 v12, v58, v12
	v_pk_mul_f32 v[20:21], v[28:29], v[20:21]
	v_sub_f32_e32 v13, v59, v13
	v_cvt_pk_bf16_f32 v28, v20, v21
	v_mul_i32_i24_e32 v20, 0x88, v137
	v_lshlrev_b32_e32 v29, 1, v20
	v_add_u32_e32 v20, v101, v29
	ds_write_b16 v20, v28 offset:8192
	v_sub_f32_e32 v20, v64, v22
	v_sub_f32_e32 v21, v65, v23
	v_exp_f32_e32 v20, v20
	v_exp_f32_e32 v21, v21
	v_add3_u32 v22, s37, v29, v124
	ds_write_b16_d16_hi v22, v28 offset:8464
	v_pk_add_f32 v[22:23], v[108:109], 1.0 op_sel_hi:[1,0] neg_lo:[1,0] neg_hi:[1,0]
	v_exp_f32_e32 v12, v12
	v_pk_mul_f32 v[20:21], v[22:23], v[20:21]
	v_exp_f32_e32 v13, v13
	v_cvt_pk_bf16_f32 v22, v20, v21
	v_mul_i32_i24_e32 v20, 0x88, v136
	v_lshlrev_b32_e32 v23, 1, v20
	v_add_u32_e32 v20, v101, v23
	ds_write_b16 v20, v22 offset:8192
	v_sub_f32_e32 v20, v62, v24
	v_sub_f32_e32 v21, v63, v25
	v_exp_f32_e32 v20, v20
	v_exp_f32_e32 v21, v21
	v_add3_u32 v23, s37, v23, v124
	ds_write_b16_d16_hi v23, v22 offset:8464
	v_pk_add_f32 v[22:23], v[110:111], 1.0 op_sel_hi:[1,0] neg_lo:[1,0] neg_hi:[1,0]
	v_sub_f32_e32 v4, v50, v4
	v_pk_mul_f32 v[20:21], v[22:23], v[20:21]
	v_sub_f32_e32 v5, v51, v5
	v_cvt_pk_bf16_f32 v22, v20, v21
	v_mul_i32_i24_e32 v20, 0x88, v135
	v_lshlrev_b32_e32 v23, 1, v20
	v_add_u32_e32 v20, v101, v23
	ds_write_b16 v20, v22 offset:8192
	v_sub_f32_e32 v20, v60, v26
	v_sub_f32_e32 v21, v61, v27
	v_exp_f32_e32 v20, v20
	v_exp_f32_e32 v21, v21
	v_add3_u32 v23, s37, v23, v124
	ds_write_b16_d16_hi v23, v22 offset:8464
	v_pk_add_f32 v[22:23], v[112:113], 1.0 op_sel_hi:[1,0] neg_lo:[1,0] neg_hi:[1,0]
	v_exp_f32_e32 v4, v4
	v_pk_mul_f32 v[20:21], v[22:23], v[20:21]
	v_exp_f32_e32 v5, v5
	v_cvt_pk_bf16_f32 v20, v20, v21
	v_mul_i32_i24_e32 v21, 0x88, v134
	v_lshlrev_b32_e32 v21, 1, v21
	v_add_u32_e32 v22, v101, v21
	v_add3_u32 v21, s37, v21, v124
	ds_write_b16 v22, v20 offset:8192
	ds_write_b16_d16_hi v21, v20 offset:8464
	v_pk_add_f32 v[20:21], v[114:115], 1.0 op_sel_hi:[1,0] neg_lo:[1,0] neg_hi:[1,0]
	v_exp_f32_e32 v79, v79
	v_pk_mul_f32 v[12:13], v[20:21], v[12:13]
	v_exp_f32_e32 v78, v78
	v_cvt_pk_bf16_f32 v20, v12, v13
	v_mul_i32_i24_e32 v12, 0x88, v133
	v_lshlrev_b32_e32 v21, 1, v12
	v_add_u32_e32 v12, v101, v21
	ds_write_b16 v12, v20 offset:8192
	v_sub_f32_e32 v12, v56, v14
	v_sub_f32_e32 v13, v57, v15
	v_exp_f32_e32 v12, v12
	v_exp_f32_e32 v13, v13
	v_add3_u32 v14, s37, v21, v124
	ds_write_b16_d16_hi v14, v20 offset:8464
	v_pk_add_f32 v[14:15], v[116:117], 1.0 op_sel_hi:[1,0] neg_lo:[1,0] neg_hi:[1,0]
	v_exp_f32_e32 v77, v77
	v_pk_mul_f32 v[12:13], v[14:15], v[12:13]
	v_exp_f32_e32 v76, v76
	v_cvt_pk_bf16_f32 v14, v12, v13
	v_mul_i32_i24_e32 v12, 0x88, v132
	v_lshlrev_b32_e32 v15, 1, v12
	v_add_u32_e32 v12, v101, v15
	ds_write_b16 v12, v14 offset:8192
	v_sub_f32_e32 v12, v54, v16
	v_sub_f32_e32 v13, v55, v17
	v_exp_f32_e32 v12, v12
	v_exp_f32_e32 v13, v13
	v_add3_u32 v15, s37, v15, v124
	ds_write_b16_d16_hi v15, v14 offset:8464
	v_pk_add_f32 v[14:15], v[118:119], 1.0 op_sel_hi:[1,0] neg_lo:[1,0] neg_hi:[1,0]
	v_exp_f32_e32 v75, v75
	v_pk_mul_f32 v[12:13], v[14:15], v[12:13]
	v_exp_f32_e32 v74, v74
	v_cvt_pk_bf16_f32 v14, v12, v13
	v_mul_i32_i24_e32 v12, 0x88, v131
	v_lshlrev_b32_e32 v15, 1, v12
	v_add_u32_e32 v12, v101, v15
	ds_write_b16 v12, v14 offset:8192
	v_sub_f32_e32 v12, v52, v18
	v_sub_f32_e32 v13, v53, v19
	v_exp_f32_e32 v12, v12
	v_exp_f32_e32 v13, v13
	v_add3_u32 v15, s37, v15, v124
	ds_write_b16_d16_hi v15, v14 offset:8464
	v_pk_add_f32 v[14:15], v[120:121], 1.0 op_sel_hi:[1,0] neg_lo:[1,0] neg_hi:[1,0]
	v_sub_f32_e32 v0, v42, v0
	v_pk_mul_f32 v[12:13], v[14:15], v[12:13]
	v_sub_f32_e32 v1, v43, v1
; __device__ __forceinline__ unsigned cvt_pk_c(float lo, float hi) { const f32x2_cv v = {lo, hi}; const bf16x2_cv b = __builtin_convertvector(v, bf16x2_cv); return __builtin_bit_cast(unsigned, b); }
; template <int DIR> __device__ __forceinline__ void h1_dir(unsigned char* lds, const bf16_t* zrow, int h, bf16_t* slot, float* decp) {
;     ...
;         for (int ks = 0; ks < 4; ++ks)
; #pragma unroll
;             for (int e = 0; e < 8; e += 2) { const unsigned w = cvt_pk_c(kk[8 * ks + e] * __builtin_amdgcn_exp2f(aft[8 * ks + e] - bl[8 * ks + e]), kk[8 * ks + e + 1] * __builtin_amdgcn_exp2f(aft[8 * ks + e + 1] - bl[8 * ks + e + 1]));
;                 KS[(32 * ks + 8 * kq + e) * HP + 16 * wid + r] = (bf16_t)(w & 0xffffu); KS[(32 * ks + 8 * kq + e + 1) * HP + 16 * wid + r] = (bf16_t)(w >> 16); }
;     }
;     __syncthreads();
;     f32x4 acc[8];
; #pragma unroll
;     for (int nt = 0; nt < 8; ++nt) acc[nt] = (f32x4){0.f, 0.f, 0.f, 0.f};
; #pragma unroll
;     for (int ks = 0; ks < 4; ++ks) {
;         const bf16x8 a = *(const bf16x8*)(VT + (16 * wid + r) * HP + 32 * ks + 8 * kq);
; #pragma unroll
;         for (int nt = 0; nt < 8; ++nt) { const bf16x8 bb = *(const bf16x8*)(KS + (16 * nt + r) * HP + 32 * ks + 8 * kq); acc[nt] = __builtin_amdgcn_mfma_f32_16x16x32_bf16(a, bb, acc[nt], 0, 0, 0); }
;     }
; #pragma unroll
;     for (int nt = 0; nt < 8; ++nt)
; #pragma unroll
;         for (int i = 0; i < 4; i += 2) { const unsigned w = cvt_pk_c(acc[nt][i], acc[nt][i + 1]); STG[(16 * wid + 4 * kq + i) * HP + 16 * nt + r] = (bf16_t)(w & 0xffffu); STG[(16 * wid + 4 * kq + i + 1) * HP + 16 * nt + r] = (bf16_t)(w >> 16); }
	v_cvt_pk_bf16_f32 v12, v12, v13
	v_mul_i32_i24_e32 v13, 0x88, v130
	v_lshlrev_b32_e32 v13, 1, v13
	v_add_u32_e32 v14, v101, v13
	v_add3_u32 v13, s37, v13, v124
	ds_write_b16 v14, v12 offset:8192
	ds_write_b16_d16_hi v13, v12 offset:8464
	v_pk_add_f32 v[12:13], v[122:123], 1.0 op_sel_hi:[1,0] neg_lo:[1,0] neg_hi:[1,0]
	v_exp_f32_e32 v0, v0
	v_pk_mul_f32 v[4:5], v[12:13], v[4:5]
	v_exp_f32_e32 v1, v1
	v_cvt_pk_bf16_f32 v12, v4, v5
	v_mul_i32_i24_e32 v4, 0x88, v129
	v_lshlrev_b32_e32 v13, 1, v4
	v_add_u32_e32 v4, v101, v13
	ds_write_b16 v4, v12 offset:8192
	v_sub_f32_e32 v4, v48, v6
	v_sub_f32_e32 v5, v49, v7
	v_exp_f32_e32 v4, v4
	v_exp_f32_e32 v5, v5
	v_add3_u32 v6, s37, v13, v124
	ds_write_b16_d16_hi v6, v12 offset:8464
	v_pk_add_f32 v[6:7], v[140:141], 1.0 op_sel_hi:[1,0] neg_lo:[1,0] neg_hi:[1,0]
	v_exp_f32_e32 v73, v73
	v_pk_mul_f32 v[4:5], v[6:7], v[4:5]
	v_exp_f32_e32 v72, v72
	v_cvt_pk_bf16_f32 v6, v4, v5
	v_mul_i32_i24_e32 v4, 0x88, v128
	v_lshlrev_b32_e32 v7, 1, v4
	v_add_u32_e32 v4, v101, v7
	ds_write_b16 v4, v6 offset:8192
	v_sub_f32_e32 v4, v46, v8
	v_sub_f32_e32 v5, v47, v9
	v_exp_f32_e32 v4, v4
	v_exp_f32_e32 v5, v5
	v_add3_u32 v7, s37, v7, v124
	ds_write_b16_d16_hi v7, v6 offset:8464
	v_pk_add_f32 v[6:7], v[78:79], 1.0 op_sel_hi:[1,0] neg_lo:[1,0] neg_hi:[1,0]
	s_nop 0
	v_pk_mul_f32 v[4:5], v[6:7], v[4:5]
	s_nop 0
	v_cvt_pk_bf16_f32 v6, v4, v5
	v_mul_i32_i24_e32 v4, 0x88, v127
	v_lshlrev_b32_e32 v7, 1, v4
	v_add_u32_e32 v4, v101, v7
	ds_write_b16 v4, v6 offset:8192
	v_sub_f32_e32 v4, v44, v10
	v_sub_f32_e32 v5, v45, v11
	v_exp_f32_e32 v4, v4
	v_exp_f32_e32 v5, v5
	v_add3_u32 v7, s37, v7, v124
	ds_write_b16_d16_hi v7, v6 offset:8464
	v_pk_add_f32 v[6:7], v[76:77], 1.0 op_sel_hi:[1,0] neg_lo:[1,0] neg_hi:[1,0]
	s_nop 0
	v_pk_mul_f32 v[4:5], v[6:7], v[4:5]
	s_nop 0
	v_cvt_pk_bf16_f32 v4, v4, v5
	v_mul_i32_i24_e32 v5, 0x88, v126
	v_lshlrev_b32_e32 v5, 1, v5
	v_add_u32_e32 v6, v101, v5
	v_add3_u32 v5, s37, v5, v124
	ds_write_b16 v6, v4 offset:8192
	ds_write_b16_d16_hi v5, v4 offset:8464
	v_pk_add_f32 v[4:5], v[74:75], 1.0 op_sel_hi:[1,0] neg_lo:[1,0] neg_hi:[1,0]
	s_nop 0
	v_pk_mul_f32 v[0:1], v[4:5], v[0:1]
	s_nop 0
	v_cvt_pk_bf16_f32 v4, v0, v1
	v_mul_i32_i24_e32 v0, 0x88, v125
	v_lshlrev_b32_e32 v5, 1, v0
	v_add_u32_e32 v0, v101, v5
	ds_write_b16 v0, v4 offset:8192
	v_sub_f32_e32 v0, v40, v2
	v_sub_f32_e32 v1, v41, v3
	v_exp_f32_e32 v0, v0
	v_exp_f32_e32 v1, v1
	v_add3_u32 v2, s37, v5, v124
	ds_write_b16_d16_hi v2, v4 offset:8464
	v_pk_add_f32 v[2:3], v[72:73], 1.0 op_sel_hi:[1,0] neg_lo:[1,0] neg_hi:[1,0]
	v_lshlrev_b32_e32 v4, 1, v100
	v_pk_mul_f32 v[0:1], v[2:3], v[0:1]
	v_mul_u32_u24_e32 v5, 0x110, v99
	v_cvt_pk_bf16_f32 v0, v0, v1
	v_mul_i32_i24_e32 v1, 0x88, v34
	v_lshlrev_b32_e32 v1, 1, v1
	v_add_u32_e32 v2, v101, v1
	v_add3_u32 v1, s37, v1, v124
	ds_write_b16 v2, v0 offset:8192
	ds_write_b16_d16_hi v1, v0 offset:8464
	v_or_b32_e32 v0, s3, v99
	v_mul_lo_u32 v0, v0, s30
	v_add3_u32 v34, s35, v0, v4
	s_waitcnt lgkmcnt(0)
	s_barrier
	ds_read_b128 v[0:3], v34
	v_add3_u32 v99, 0, v4, v5
	ds_read_b128 v[4:7], v99 offset:8192
	ds_read_b128 v[8:11], v34 offset:64
	ds_read_b128 v[12:15], v99 offset:8256
	ds_read_b128 v[16:19], v99 offset:12544
	ds_read_b128 v[20:23], v99 offset:12608
	ds_read_b128 v[24:27], v99 offset:16896
	ds_read_b128 v[28:31], v99 offset:16960
	ds_read_b128 v[40:43], v99 offset:21248
	ds_read_b128 v[44:47], v99 offset:21312
	s_waitcnt lgkmcnt(8)
	v_mfma_f32_16x16x32_bf16 v[4:7], v[0:3], v[4:7], 0
	ds_read_b128 v[48:51], v99 offset:25600
	ds_read_b128 v[52:55], v99 offset:25664
	ds_read_b128 v[56:59], v99 offset:29952
	ds_read_b128 v[60:63], v99 offset:30016
	ds_read_b128 v[64:67], v99 offset:34304
	ds_read_b128 v[68:71], v99 offset:34368
	s_waitcnt lgkmcnt(11)
	v_mfma_f32_16x16x32_bf16 v[16:19], v[0:3], v[16:19], 0
	ds_read_b128 v[72:75], v99 offset:38656
	ds_read_b128 v[76:79], v99 offset:38720
	s_waitcnt lgkmcnt(9)
	v_mfma_f32_16x16x32_bf16 v[40:43], v[0:3], v[40:43], 0
	v_mfma_f32_16x16x32_bf16 v[4:7], v[8:11], v[12:15], v[4:7]
	v_mfma_f32_16x16x32_bf16 v[12:15], v[8:11], v[20:23], v[16:19]
	s_waitcnt lgkmcnt(8)
	v_mfma_f32_16x16x32_bf16 v[20:23], v[8:11], v[44:47], v[40:43]
	ds_read_b128 v[44:47], v34 offset:128
	v_mfma_f32_16x16x32_bf16 v[24:27], v[0:3], v[24:27], 0
	s_waitcnt lgkmcnt(8)
	v_mfma_f32_16x16x32_bf16 v[48:51], v[0:3], v[48:51], 0
	s_waitcnt lgkmcnt(6)
	v_mfma_f32_16x16x32_bf16 v[56:59], v[0:3], v[56:59], 0
	s_waitcnt lgkmcnt(4)
	v_mfma_f32_16x16x32_bf16 v[64:67], v[0:3], v[64:67], 0
	s_waitcnt lgkmcnt(2)
	v_mfma_f32_16x16x32_bf16 v[0:3], v[0:3], v[72:75], 0
	v_mfma_f32_16x16x32_bf16 v[16:19], v[8:11], v[28:31], v[24:27]
	v_mfma_f32_16x16x32_bf16 v[24:27], v[8:11], v[52:55], v[48:51]
	v_mfma_f32_16x16x32_bf16 v[28:31], v[8:11], v[60:63], v[56:59]
	v_mfma_f32_16x16x32_bf16 v[40:43], v[8:11], v[68:71], v[64:67]
	s_waitcnt lgkmcnt(1)
	v_mfma_f32_16x16x32_bf16 v[0:3], v[8:11], v[76:79], v[0:3]
	ds_read_b128 v[8:11], v99 offset:8320
	ds_read_b128 v[48:51], v34 offset:192
	ds_read_b128 v[52:55], v99 offset:8384
	v_lshl_or_b32 v34, v98, 2, s3
	s_waitcnt lgkmcnt(2)
	v_mfma_f32_16x16x32_bf16 v[4:7], v[44:47], v[8:11], v[4:7]
	ds_read_b128 v[8:11], v99 offset:12672
	ds_read_b128 v[56:59], v99 offset:12736
	s_waitcnt lgkmcnt(1)
	v_mfma_f32_16x16x32_bf16 v[8:11], v[44:47], v[8:11], v[12:15]
	s_nop 2
	ds_read_b128 v[12:15], v99 offset:17024
	ds_read_b128 v[60:63], v99 offset:17088
	s_waitcnt lgkmcnt(1)
	v_mfma_f32_16x16x32_bf16 v[12:15], v[44:47], v[12:15], v[16:19]
	s_nop 2
	ds_read_b128 v[16:19], v99 offset:21376
	ds_read_b128 v[64:67], v99 offset:21440
	s_waitcnt lgkmcnt(1)
; __device__ __forceinline__ unsigned cvt_pk_c(float lo, float hi) { const f32x2_cv v = {lo, hi}; const bf16x2_cv b = __builtin_convertvector(v, bf16x2_cv); return __builtin_bit_cast(unsigned, b); }
; #define WAVE_LDS_FENCE() do { asm volatile("s_waitcnt lgkmcnt(0)" ::: "memory"); __builtin_amdgcn_wave_barrier(); } while (0)
; template <int DIR> __device__ __forceinline__ void h1_dir(unsigned char* lds, const bf16_t* zrow, int h, bf16_t* slot, float* decp) {
;     ...
;         for (int nt = 0; nt < 8; ++nt) { const bf16x8 bb = *(const bf16x8*)(KS + (16 * nt + r) * HP + 32 * ks + 8 * kq); acc[nt] = __builtin_amdgcn_mfma_f32_16x16x32_bf16(a, bb, acc[nt], 0, 0, 0); }
;     }
; #pragma unroll
;     for (int nt = 0; nt < 8; ++nt)
; #pragma unroll
;         for (int i = 0; i < 4; i += 2) { const unsigned w = cvt_pk_c(acc[nt][i], acc[nt][i + 1]); STG[(16 * wid + 4 * kq + i) * HP + 16 * nt + r] = (bf16_t)(w & 0xffffu); STG[(16 * wid + 4 * kq + i + 1) * HP + 16 * nt + r] = (bf16_t)(w >> 16); }
;     WAVE_LDS_FENCE();
; #pragma unroll
;     for (int it = 0; it < 4; ++it) { const int p = lane + 64 * it, row = p >> 4, c16 = p & 15; *(u32x4*)(slot + (size_t)(16 * wid + row) * 128 + c16 * 8) = *(const u32x4*)(STG + (16 * wid + row) * HP + c16 * 8); }
;     asm volatile("s_waitcnt lgkmcnt(0)\n\ts_barrier" ::: "memory");
	v_mfma_f32_16x16x32_bf16 v[16:19], v[44:47], v[16:19], v[20:23]
	s_nop 2
	ds_read_b128 v[20:23], v99 offset:25728
	ds_read_b128 v[68:71], v99 offset:25792
	s_waitcnt lgkmcnt(1)
	v_mfma_f32_16x16x32_bf16 v[20:23], v[44:47], v[20:23], v[24:27]
	s_nop 2
	ds_read_b128 v[24:27], v99 offset:30080
	ds_read_b128 v[72:75], v99 offset:30144
	v_mfma_f32_16x16x32_bf16 v[4:7], v[48:51], v[52:55], v[4:7]
	s_waitcnt lgkmcnt(1)
	v_mfma_f32_16x16x32_bf16 v[24:27], v[44:47], v[24:27], v[28:31]
	s_nop 2
	ds_read_b128 v[28:31], v99 offset:34432
	ds_read_b128 v[76:79], v99 offset:34496
	s_nop 0
	v_cvt_pk_bf16_f32 v4, v4, v5
	v_mul_lo_u32 v5, v34, s30
	v_mfma_f32_16x16x32_bf16 v[8:11], v[48:51], v[56:59], v[8:11]
	v_add3_u32 v34, 0, v124, v5
	v_add3_u32 v5, 0, v5, v124
	v_mfma_f32_16x16x32_bf16 v[12:15], v[48:51], v[60:63], v[12:15]
	s_waitcnt lgkmcnt(1)
	v_mfma_f32_16x16x32_bf16 v[28:31], v[44:47], v[28:31], v[40:43]
	s_nop 2
	ds_read_b128 v[40:43], v99 offset:38784
	ds_read_b128 v[100:103], v99 offset:38848
	ds_write_b16 v34, v4 offset:43008
	ds_write_b16_d16_hi v5, v4 offset:43280
	v_cvt_pk_bf16_f32 v4, v6, v7
	v_mfma_f32_16x16x32_bf16 v[16:19], v[48:51], v[64:67], v[16:19]
	ds_write_b16 v34, v4 offset:43552
	ds_write_b16_d16_hi v5, v4 offset:43824
	v_cvt_pk_bf16_f32 v4, v8, v9
	ds_write_b16 v34, v4 offset:43040
	ds_write_b16_d16_hi v5, v4 offset:43312
	v_cvt_pk_bf16_f32 v4, v10, v11
	v_mfma_f32_16x16x32_bf16 v[20:23], v[48:51], v[68:71], v[20:23]
	ds_write_b16 v34, v4 offset:43584
	ds_write_b16_d16_hi v5, v4 offset:43856
	v_cvt_pk_bf16_f32 v4, v12, v13
	ds_write_b16 v34, v4 offset:43072
	ds_write_b16_d16_hi v5, v4 offset:43344
	s_waitcnt lgkmcnt(11)
	v_mfma_f32_16x16x32_bf16 v[0:3], v[44:47], v[40:43], v[0:3]
	v_cvt_pk_bf16_f32 v4, v14, v15
	ds_write_b16 v34, v4 offset:43616
	ds_write_b16_d16_hi v5, v4 offset:43888
	v_cvt_pk_bf16_f32 v4, v16, v17
	v_mfma_f32_16x16x32_bf16 v[24:27], v[48:51], v[72:75], v[24:27]
	ds_write_b16 v34, v4 offset:43104
	ds_write_b16_d16_hi v5, v4 offset:43376
	v_cvt_pk_bf16_f32 v4, v18, v19
	ds_write_b16 v34, v4 offset:43648
	ds_write_b16_d16_hi v5, v4 offset:43920
	v_mfma_f32_16x16x32_bf16 v[28:31], v[48:51], v[76:79], v[28:31]
	v_cvt_pk_bf16_f32 v4, v20, v21
	ds_write_b16 v34, v4 offset:43136
	ds_write_b16_d16_hi v5, v4 offset:43408
	v_cvt_pk_bf16_f32 v4, v22, v23
	s_waitcnt lgkmcnt(14)
	v_mfma_f32_16x16x32_bf16 v[0:3], v[48:51], v[100:103], v[0:3]
	ds_write_b16 v34, v4 offset:43680
	ds_write_b16_d16_hi v5, v4 offset:43952
	v_cvt_pk_bf16_f32 v4, v24, v25
	ds_write_b16 v34, v4 offset:43168
	ds_write_b16_d16_hi v5, v4 offset:43440
	v_cvt_pk_bf16_f32 v4, v26, v27
	ds_write_b16 v34, v4 offset:43712
	ds_write_b16_d16_hi v5, v4 offset:43984
	v_cvt_pk_bf16_f32 v4, v28, v29
	ds_write_b16 v34, v4 offset:43200
	ds_write_b16_d16_hi v5, v4 offset:43472
	v_cvt_pk_bf16_f32 v4, v30, v31
	v_cvt_pk_bf16_f32 v0, v0, v1
	ds_write_b16 v34, v4 offset:43744
	ds_write_b16_d16_hi v5, v4 offset:44016
	ds_write_b16 v34, v0 offset:43232
	ds_write_b16_d16_hi v5, v0 offset:43504
	v_cvt_pk_bf16_f32 v0, v2, v3
	ds_write_b16 v34, v0 offset:43776
	ds_write_b16_d16_hi v5, v0 offset:44048
	v_lshlrev_b32_e32 v0, 4, v97
	v_or_b32_e32 v10, s3, v98
	v_and_b32_e32 v34, 0xf0, v0
	v_mul_lo_u32 v0, v10, s30
	v_add3_u32 v14, 0, v34, v0
	s_waitcnt lgkmcnt(0)
	ds_read_b128 v[0:3], v14 offset:43008
	v_ashrrev_i32_e32 v11, 31, v10
	v_lshl_add_u64 v[8:9], s[18:19], 0, v[34:35]
	v_lshlrev_b64 v[4:5], 8, v[10:11]
	v_lshl_add_u64 v[12:13], v[8:9], 0, v[4:5]
	ds_read_b128 v[4:7], v14 offset:44096
	s_waitcnt lgkmcnt(1)
	global_store_dwordx4 v[12:13], v[0:3], off
	v_and_b32_e32 v79, 63, v254
	v_or_b32_e32 v79, s62, v79
	s_nop 0
	v_or_b32_e32 v0, 4, v10
	v_ashrrev_i32_e32 v1, 31, v0
	v_lshlrev_b64 v[0:1], 8, v[0:1]
	v_lshl_add_u64 v[0:1], v[8:9], 0, v[0:1]
	s_waitcnt lgkmcnt(0)
	global_store_dwordx4 v[0:1], v[4:7], off
	ds_read_b128 v[0:3], v14 offset:45184
	s_nop 0
	v_or_b32_e32 v4, 8, v10
	v_ashrrev_i32_e32 v5, 31, v4
	v_lshlrev_b64 v[4:5], 8, v[4:5]
	v_lshl_add_u64 v[12:13], v[8:9], 0, v[4:5]
	ds_read_b128 v[4:7], v14 offset:46272
	s_waitcnt lgkmcnt(1)
	global_store_dwordx4 v[12:13], v[0:3], off
	s_nop 1
	v_or_b32_e32 v0, 12, v10
	v_ashrrev_i32_e32 v1, 31, v0
	v_lshlrev_b64 v[0:1], 8, v[0:1]
	v_lshl_add_u64 v[0:1], v[8:9], 0, v[0:1]
	s_waitcnt lgkmcnt(0)
	global_store_dwordx4 v[0:1], v[4:7], off
	s_waitcnt lgkmcnt(0)
	s_barrier
; template <int DIR> __device__ __forceinline__ void h1_dir(unsigned char* lds, const bf16_t* zrow, int h, bf16_t* slot, float* decp) {
;     int tid_l = threadIdx.x; asm volatile("" : "+v"(tid_l)); const int tid = tid_l, lane = tid & 63, wid = __builtin_amdgcn_readfirstlane(tid >> 6), r = lane & 15, kq = lane >> 4;
;     float* TOT = (float*)(lds + L_TOT); bf16_t* KS = (bf16_t*)(lds + L_KO); bf16_t* VT = (bf16_t*)(lds + L_VT); bf16_t* STG = (bf16_t*)(lds + L_ST);
;     float bl[32], kk[32];
;     load32(zrow + (size_t)(1 + DIR) * ZSEG + 8 * kq, bl);
; #pragma unroll
;     for (int i = 0; i < 32; ++i) kk[i] = 1.0f - __builtin_amdgcn_exp2f(bl[i]);
;         scan16x8<DIR>(bl); scan16x8<DIR>(bl + 8); scan16x8<DIR>(bl + 16); scan16x8<DIR>(bl + 24);
	s_nop 0
	v_bfe_u32 v78, v79, 4, 2
	v_lshlrev_b32_e32 v34, 4, v78
	v_lshl_add_u64 v[4:5], v[38:39], 0, v[34:35]
	v_add_co_u32_e32 v0, vcc, s31, v4
	v_lshl_add_u64 v[16:17], v[4:5], 0, s[10:11]
	s_nop 0
	v_addc_co_u32_e32 v1, vcc, 0, v5, vcc
	global_load_dwordx4 v[0:3], v[0:1], off
	s_nop 0
	global_load_dwordx4 v[4:7], v[16:17], off offset:64
	global_load_dwordx4 v[8:11], v[16:17], off offset:128
	global_load_dwordx4 v[12:15], v[16:17], off offset:192
	v_readfirstlane_b32 s3, v79
	v_and_b32_e32 v98, 15, v79
	s_ashr_i32 s37, s3, 6
	v_lshlrev_b32_e32 v97, 3, v78
	v_cmp_eq_u32_e32 vcc, 0, v98
	s_waitcnt vmcnt(2)
	v_lshlrev_b32_e32 v107, 16, v4
	v_lshlrev_b32_e32 v99, 16, v0
	v_and_b32_e32 v100, 0xffff0000, v0
	v_lshlrev_b32_e32 v101, 16, v1
	v_and_b32_e32 v102, 0xffff0000, v1
	v_lshlrev_b32_e32 v103, 16, v2
	v_and_b32_e32 v104, 0xffff0000, v2
	v_lshlrev_b32_e32 v105, 16, v3
	v_and_b32_e32 v106, 0xffff0000, v3
	v_mov_b32_e32 v31, v102
	v_mov_b32_e32 v21, v104
	v_mov_b32_e32 v28, v99
	v_mov_b32_e32 v23, v106
	v_mov_b32_e32 v30, v101
	v_mov_b32_e32 v20, v103
	v_mov_b32_e32 v22, v105
	v_mov_b32_e32 v29, v100
	s_nop 1
	v_add_f32_dpp v28, v28, v28 row_shl:1 row_mask:0xf bank_mask:0xf bound_ctrl:1
	v_add_f32_dpp v29, v29, v29 row_shl:1 row_mask:0xf bank_mask:0xf bound_ctrl:1
	v_add_f32_dpp v30, v30, v30 row_shl:1 row_mask:0xf bank_mask:0xf bound_ctrl:1
	v_add_f32_dpp v31, v31, v31 row_shl:1 row_mask:0xf bank_mask:0xf bound_ctrl:1
	v_add_f32_dpp v20, v20, v20 row_shl:1 row_mask:0xf bank_mask:0xf bound_ctrl:1
	v_add_f32_dpp v21, v21, v21 row_shl:1 row_mask:0xf bank_mask:0xf bound_ctrl:1
	v_add_f32_dpp v22, v22, v22 row_shl:1 row_mask:0xf bank_mask:0xf bound_ctrl:1
	v_add_f32_dpp v23, v23, v23 row_shl:1 row_mask:0xf bank_mask:0xf bound_ctrl:1
	v_and_b32_e32 v108, 0xffff0000, v4
	v_lshlrev_b32_e32 v109, 16, v5
	v_and_b32_e32 v110, 0xffff0000, v5
	v_lshlrev_b32_e32 v111, 16, v6
	v_and_b32_e32 v112, 0xffff0000, v6
	v_lshlrev_b32_e32 v113, 16, v7
	v_and_b32_e32 v114, 0xffff0000, v7
	s_nop 1
	v_add_f32_dpp v28, v28, v28 row_shl:2 row_mask:0xf bank_mask:0xf bound_ctrl:1
	v_add_f32_dpp v29, v29, v29 row_shl:2 row_mask:0xf bank_mask:0xf bound_ctrl:1
	v_add_f32_dpp v30, v30, v30 row_shl:2 row_mask:0xf bank_mask:0xf bound_ctrl:1
	v_add_f32_dpp v31, v31, v31 row_shl:2 row_mask:0xf bank_mask:0xf bound_ctrl:1
	v_add_f32_dpp v20, v20, v20 row_shl:2 row_mask:0xf bank_mask:0xf bound_ctrl:1
	v_add_f32_dpp v21, v21, v21 row_shl:2 row_mask:0xf bank_mask:0xf bound_ctrl:1
	v_add_f32_dpp v22, v22, v22 row_shl:2 row_mask:0xf bank_mask:0xf bound_ctrl:1
	v_add_f32_dpp v23, v23, v23 row_shl:2 row_mask:0xf bank_mask:0xf bound_ctrl:1
	s_waitcnt vmcnt(0)
	v_lshlrev_b32_e32 v76, 16, v12
	v_and_b32_e32 v77, 0xffff0000, v12
	v_lshlrev_b32_e32 v74, 16, v13
	v_and_b32_e32 v75, 0xffff0000, v13
	v_lshlrev_b32_e32 v72, 16, v14
	v_and_b32_e32 v73, 0xffff0000, v14
	v_lshlrev_b32_e32 v70, 16, v15
	v_and_b32_e32 v71, 0xffff0000, v15
	s_nop 1
	v_add_f32_dpp v28, v28, v28 row_shl:4 row_mask:0xf bank_mask:0xf bound_ctrl:1
	v_add_f32_dpp v29, v29, v29 row_shl:4 row_mask:0xf bank_mask:0xf bound_ctrl:1
	v_add_f32_dpp v30, v30, v30 row_shl:4 row_mask:0xf bank_mask:0xf bound_ctrl:1
	v_add_f32_dpp v31, v31, v31 row_shl:4 row_mask:0xf bank_mask:0xf bound_ctrl:1
	v_add_f32_dpp v20, v20, v20 row_shl:4 row_mask:0xf bank_mask:0xf bound_ctrl:1
	v_add_f32_dpp v21, v21, v21 row_shl:4 row_mask:0xf bank_mask:0xf bound_ctrl:1
	v_add_f32_dpp v22, v22, v22 row_shl:4 row_mask:0xf bank_mask:0xf bound_ctrl:1
	v_add_f32_dpp v23, v23, v23 row_shl:4 row_mask:0xf bank_mask:0xf bound_ctrl:1
	v_mov_b32_e32 v27, v110
	v_mov_b32_e32 v13, v112
	v_mov_b32_e32 v24, v107
	v_mov_b32_e32 v15, v114
	v_mov_b32_e32 v26, v109
	v_mov_b32_e32 v12, v111
	v_mov_b32_e32 v14, v113
	v_mov_b32_e32 v25, v108
	s_nop 1
	v_add_f32_dpp v28, v28, v28 row_shl:8 row_mask:0xf bank_mask:0xf bound_ctrl:1
	v_add_f32_dpp v29, v29, v29 row_shl:8 row_mask:0xf bank_mask:0xf bound_ctrl:1
	v_add_f32_dpp v30, v30, v30 row_shl:8 row_mask:0xf bank_mask:0xf bound_ctrl:1
	v_add_f32_dpp v31, v31, v31 row_shl:8 row_mask:0xf bank_mask:0xf bound_ctrl:1
	v_add_f32_dpp v20, v20, v20 row_shl:8 row_mask:0xf bank_mask:0xf bound_ctrl:1
	v_add_f32_dpp v21, v21, v21 row_shl:8 row_mask:0xf bank_mask:0xf bound_ctrl:1
	v_add_f32_dpp v22, v22, v22 row_shl:8 row_mask:0xf bank_mask:0xf bound_ctrl:1
	v_add_f32_dpp v23, v23, v23 row_shl:8 row_mask:0xf bank_mask:0xf bound_ctrl:1
	s_nop 1
	v_add_f32_dpp v24, v24, v24 row_shl:1 row_mask:0xf bank_mask:0xf bound_ctrl:1
	v_add_f32_dpp v25, v25, v25 row_shl:1 row_mask:0xf bank_mask:0xf bound_ctrl:1
	v_add_f32_dpp v26, v26, v26 row_shl:1 row_mask:0xf bank_mask:0xf bound_ctrl:1
	v_add_f32_dpp v27, v27, v27 row_shl:1 row_mask:0xf bank_mask:0xf bound_ctrl:1
	v_add_f32_dpp v12, v12, v12 row_shl:1 row_mask:0xf bank_mask:0xf bound_ctrl:1
	v_add_f32_dpp v13, v13, v13 row_shl:1 row_mask:0xf bank_mask:0xf bound_ctrl:1
	v_add_f32_dpp v14, v14, v14 row_shl:1 row_mask:0xf bank_mask:0xf bound_ctrl:1
	v_add_f32_dpp v15, v15, v15 row_shl:1 row_mask:0xf bank_mask:0xf bound_ctrl:1
	v_lshlrev_b32_e32 v115, 16, v8
	v_and_b32_e32 v116, 0xffff0000, v8
	v_lshlrev_b32_e32 v117, 16, v9
	v_and_b32_e32 v118, 0xffff0000, v9
	v_lshlrev_b32_e32 v119, 16, v10
	v_and_b32_e32 v120, 0xffff0000, v10
	v_lshlrev_b32_e32 v121, 16, v11
	v_and_b32_e32 v122, 0xffff0000, v11
	s_nop 1
	v_add_f32_dpp v24, v24, v24 row_shl:2 row_mask:0xf bank_mask:0xf bound_ctrl:1
	v_add_f32_dpp v25, v25, v25 row_shl:2 row_mask:0xf bank_mask:0xf bound_ctrl:1
	v_add_f32_dpp v26, v26, v26 row_shl:2 row_mask:0xf bank_mask:0xf bound_ctrl:1
	v_add_f32_dpp v27, v27, v27 row_shl:2 row_mask:0xf bank_mask:0xf bound_ctrl:1
; template <int DIR> __device__ __forceinline__ void scan16x8(float* v) {
;     if (DIR == 0) { SCAN_STEP("row_shr:", 1); SCAN_STEP("row_shr:", 2); SCAN_STEP("row_shr:", 4); SCAN_STEP("row_shr:", 8); }
;     else          { SCAN_STEP("row_shl:", 1); SCAN_STEP("row_shl:", 2); SCAN_STEP("row_shl:", 4); SCAN_STEP("row_shl:", 8); }
; }
; template <int DIR> __device__ __forceinline__ void h1_dir(unsigned char* lds, const bf16_t* zrow, int h, bf16_t* slot, float* decp) {
;     ...
;         scan16x8<DIR>(bl); scan16x8<DIR>(bl + 8); scan16x8<DIR>(bl + 16); scan16x8<DIR>(bl + 24);
	v_add_f32_dpp v12, v12, v12 row_shl:2 row_mask:0xf bank_mask:0xf bound_ctrl:1
	v_add_f32_dpp v13, v13, v13 row_shl:2 row_mask:0xf bank_mask:0xf bound_ctrl:1
	v_add_f32_dpp v14, v14, v14 row_shl:2 row_mask:0xf bank_mask:0xf bound_ctrl:1
	v_add_f32_dpp v15, v15, v15 row_shl:2 row_mask:0xf bank_mask:0xf bound_ctrl:1
	v_mov_b32_e32 v19, v118
	s_nop 1
	v_add_f32_dpp v24, v24, v24 row_shl:4 row_mask:0xf bank_mask:0xf bound_ctrl:1
	v_add_f32_dpp v25, v25, v25 row_shl:4 row_mask:0xf bank_mask:0xf bound_ctrl:1
	v_add_f32_dpp v26, v26, v26 row_shl:4 row_mask:0xf bank_mask:0xf bound_ctrl:1
	v_add_f32_dpp v27, v27, v27 row_shl:4 row_mask:0xf bank_mask:0xf bound_ctrl:1
	v_add_f32_dpp v12, v12, v12 row_shl:4 row_mask:0xf bank_mask:0xf bound_ctrl:1
	v_add_f32_dpp v13, v13, v13 row_shl:4 row_mask:0xf bank_mask:0xf bound_ctrl:1
	v_add_f32_dpp v14, v14, v14 row_shl:4 row_mask:0xf bank_mask:0xf bound_ctrl:1
	v_add_f32_dpp v15, v15, v15 row_shl:4 row_mask:0xf bank_mask:0xf bound_ctrl:1
	v_mov_b32_e32 v5, v120
	v_mov_b32_e32 v16, v115
	v_mov_b32_e32 v7, v122
	v_mov_b32_e32 v18, v117
	v_mov_b32_e32 v4, v119
	v_mov_b32_e32 v6, v121
	v_mov_b32_e32 v17, v116
	s_nop 1
	v_add_f32_dpp v24, v24, v24 row_shl:8 row_mask:0xf bank_mask:0xf bound_ctrl:1
	v_add_f32_dpp v25, v25, v25 row_shl:8 row_mask:0xf bank_mask:0xf bound_ctrl:1
	v_add_f32_dpp v26, v26, v26 row_shl:8 row_mask:0xf bank_mask:0xf bound_ctrl:1
	v_add_f32_dpp v27, v27, v27 row_shl:8 row_mask:0xf bank_mask:0xf bound_ctrl:1
	v_add_f32_dpp v12, v12, v12 row_shl:8 row_mask:0xf bank_mask:0xf bound_ctrl:1
	v_add_f32_dpp v13, v13, v13 row_shl:8 row_mask:0xf bank_mask:0xf bound_ctrl:1
	v_add_f32_dpp v14, v14, v14 row_shl:8 row_mask:0xf bank_mask:0xf bound_ctrl:1
	v_add_f32_dpp v15, v15, v15 row_shl:8 row_mask:0xf bank_mask:0xf bound_ctrl:1
	s_nop 1
	v_add_f32_dpp v16, v16, v16 row_shl:1 row_mask:0xf bank_mask:0xf bound_ctrl:1
	v_add_f32_dpp v17, v17, v17 row_shl:1 row_mask:0xf bank_mask:0xf bound_ctrl:1
	v_add_f32_dpp v18, v18, v18 row_shl:1 row_mask:0xf bank_mask:0xf bound_ctrl:1
	v_add_f32_dpp v19, v19, v19 row_shl:1 row_mask:0xf bank_mask:0xf bound_ctrl:1
	v_add_f32_dpp v4, v4, v4 row_shl:1 row_mask:0xf bank_mask:0xf bound_ctrl:1
	v_add_f32_dpp v5, v5, v5 row_shl:1 row_mask:0xf bank_mask:0xf bound_ctrl:1
	v_add_f32_dpp v6, v6, v6 row_shl:1 row_mask:0xf bank_mask:0xf bound_ctrl:1
	v_add_f32_dpp v7, v7, v7 row_shl:1 row_mask:0xf bank_mask:0xf bound_ctrl:1
	v_mov_b32_e32 v11, v75
	s_nop 1
	v_add_f32_dpp v16, v16, v16 row_shl:2 row_mask:0xf bank_mask:0xf bound_ctrl:1
	v_add_f32_dpp v17, v17, v17 row_shl:2 row_mask:0xf bank_mask:0xf bound_ctrl:1
	v_add_f32_dpp v18, v18, v18 row_shl:2 row_mask:0xf bank_mask:0xf bound_ctrl:1
	v_add_f32_dpp v19, v19, v19 row_shl:2 row_mask:0xf bank_mask:0xf bound_ctrl:1
	v_add_f32_dpp v4, v4, v4 row_shl:2 row_mask:0xf bank_mask:0xf bound_ctrl:1
	v_add_f32_dpp v5, v5, v5 row_shl:2 row_mask:0xf bank_mask:0xf bound_ctrl:1
	v_add_f32_dpp v6, v6, v6 row_shl:2 row_mask:0xf bank_mask:0xf bound_ctrl:1
	v_add_f32_dpp v7, v7, v7 row_shl:2 row_mask:0xf bank_mask:0xf bound_ctrl:1
	v_mov_b32_e32 v1, v73
	s_nop 1
	v_add_f32_dpp v16, v16, v16 row_shl:4 row_mask:0xf bank_mask:0xf bound_ctrl:1
	v_add_f32_dpp v17, v17, v17 row_shl:4 row_mask:0xf bank_mask:0xf bound_ctrl:1
	v_add_f32_dpp v18, v18, v18 row_shl:4 row_mask:0xf bank_mask:0xf bound_ctrl:1
	v_add_f32_dpp v19, v19, v19 row_shl:4 row_mask:0xf bank_mask:0xf bound_ctrl:1
	v_add_f32_dpp v4, v4, v4 row_shl:4 row_mask:0xf bank_mask:0xf bound_ctrl:1
	v_add_f32_dpp v5, v5, v5 row_shl:4 row_mask:0xf bank_mask:0xf bound_ctrl:1
	v_add_f32_dpp v6, v6, v6 row_shl:4 row_mask:0xf bank_mask:0xf bound_ctrl:1
	v_add_f32_dpp v7, v7, v7 row_shl:4 row_mask:0xf bank_mask:0xf bound_ctrl:1
; template <int DIR> __device__ __forceinline__ void h1_dir(unsigned char* lds, const bf16_t* zrow, int h, bf16_t* slot, float* decp) {
;     ...
;         scan16x8<DIR>(bl); scan16x8<DIR>(bl + 8); scan16x8<DIR>(bl + 16); scan16x8<DIR>(bl + 24);
;     if (r == (DIR ? 0 : 15)) {
; #pragma unroll
;         for (int ks = 0; ks < 4; ++ks) { *(f32x4*)(TOT + wid * 128 + 32 * ks + 8 * kq) = (f32x4){bl[8 * ks], bl[8 * ks + 1], bl[8 * ks + 2], bl[8 * ks + 3]}; *(f32x4*)(TOT + wid * 128 + 32 * ks + 8 * kq + 4) = (f32x4){bl[8 * ks + 4], bl[8 * ks + 5], bl[8 * ks + 6], bl[8 * ks + 7]}; }
;     }
	v_mov_b32_e32 v8, v76
	v_mov_b32_e32 v3, v71
	v_mov_b32_e32 v10, v74
	v_mov_b32_e32 v0, v72
	v_mov_b32_e32 v2, v70
	v_mov_b32_e32 v9, v77
	s_nop 1
	v_add_f32_dpp v16, v16, v16 row_shl:8 row_mask:0xf bank_mask:0xf bound_ctrl:1
	v_add_f32_dpp v17, v17, v17 row_shl:8 row_mask:0xf bank_mask:0xf bound_ctrl:1
	v_add_f32_dpp v18, v18, v18 row_shl:8 row_mask:0xf bank_mask:0xf bound_ctrl:1
	v_add_f32_dpp v19, v19, v19 row_shl:8 row_mask:0xf bank_mask:0xf bound_ctrl:1
	v_add_f32_dpp v4, v4, v4 row_shl:8 row_mask:0xf bank_mask:0xf bound_ctrl:1
	v_add_f32_dpp v5, v5, v5 row_shl:8 row_mask:0xf bank_mask:0xf bound_ctrl:1
	v_add_f32_dpp v6, v6, v6 row_shl:8 row_mask:0xf bank_mask:0xf bound_ctrl:1
	v_add_f32_dpp v7, v7, v7 row_shl:8 row_mask:0xf bank_mask:0xf bound_ctrl:1
	s_nop 1
	v_add_f32_dpp v8, v8, v8 row_shl:1 row_mask:0xf bank_mask:0xf bound_ctrl:1
	v_add_f32_dpp v9, v9, v9 row_shl:1 row_mask:0xf bank_mask:0xf bound_ctrl:1
	v_add_f32_dpp v10, v10, v10 row_shl:1 row_mask:0xf bank_mask:0xf bound_ctrl:1
	v_add_f32_dpp v11, v11, v11 row_shl:1 row_mask:0xf bank_mask:0xf bound_ctrl:1
	v_add_f32_dpp v0, v0, v0 row_shl:1 row_mask:0xf bank_mask:0xf bound_ctrl:1
	v_add_f32_dpp v1, v1, v1 row_shl:1 row_mask:0xf bank_mask:0xf bound_ctrl:1
	v_add_f32_dpp v2, v2, v2 row_shl:1 row_mask:0xf bank_mask:0xf bound_ctrl:1
	v_add_f32_dpp v3, v3, v3 row_shl:1 row_mask:0xf bank_mask:0xf bound_ctrl:1
	s_nop 0
	s_nop 1
	v_add_f32_dpp v8, v8, v8 row_shl:2 row_mask:0xf bank_mask:0xf bound_ctrl:1
	v_add_f32_dpp v9, v9, v9 row_shl:2 row_mask:0xf bank_mask:0xf bound_ctrl:1
	v_add_f32_dpp v10, v10, v10 row_shl:2 row_mask:0xf bank_mask:0xf bound_ctrl:1
	v_add_f32_dpp v11, v11, v11 row_shl:2 row_mask:0xf bank_mask:0xf bound_ctrl:1
	v_add_f32_dpp v0, v0, v0 row_shl:2 row_mask:0xf bank_mask:0xf bound_ctrl:1
	v_add_f32_dpp v1, v1, v1 row_shl:2 row_mask:0xf bank_mask:0xf bound_ctrl:1
	v_add_f32_dpp v2, v2, v2 row_shl:2 row_mask:0xf bank_mask:0xf bound_ctrl:1
	v_add_f32_dpp v3, v3, v3 row_shl:2 row_mask:0xf bank_mask:0xf bound_ctrl:1
	s_nop 0
	s_nop 1
	v_add_f32_dpp v8, v8, v8 row_shl:4 row_mask:0xf bank_mask:0xf bound_ctrl:1
	v_add_f32_dpp v9, v9, v9 row_shl:4 row_mask:0xf bank_mask:0xf bound_ctrl:1
	v_add_f32_dpp v10, v10, v10 row_shl:4 row_mask:0xf bank_mask:0xf bound_ctrl:1
	v_add_f32_dpp v11, v11, v11 row_shl:4 row_mask:0xf bank_mask:0xf bound_ctrl:1
	v_add_f32_dpp v0, v0, v0 row_shl:4 row_mask:0xf bank_mask:0xf bound_ctrl:1
	v_add_f32_dpp v1, v1, v1 row_shl:4 row_mask:0xf bank_mask:0xf bound_ctrl:1
	v_add_f32_dpp v2, v2, v2 row_shl:4 row_mask:0xf bank_mask:0xf bound_ctrl:1
	v_add_f32_dpp v3, v3, v3 row_shl:4 row_mask:0xf bank_mask:0xf bound_ctrl:1
	s_nop 0
	s_nop 1
	v_add_f32_dpp v8, v8, v8 row_shl:8 row_mask:0xf bank_mask:0xf bound_ctrl:1
	v_add_f32_dpp v9, v9, v9 row_shl:8 row_mask:0xf bank_mask:0xf bound_ctrl:1
	v_add_f32_dpp v10, v10, v10 row_shl:8 row_mask:0xf bank_mask:0xf bound_ctrl:1
	v_add_f32_dpp v11, v11, v11 row_shl:8 row_mask:0xf bank_mask:0xf bound_ctrl:1
	v_add_f32_dpp v0, v0, v0 row_shl:8 row_mask:0xf bank_mask:0xf bound_ctrl:1
	v_add_f32_dpp v1, v1, v1 row_shl:8 row_mask:0xf bank_mask:0xf bound_ctrl:1
	v_add_f32_dpp v2, v2, v2 row_shl:8 row_mask:0xf bank_mask:0xf bound_ctrl:1
	v_add_f32_dpp v3, v3, v3 row_shl:8 row_mask:0xf bank_mask:0xf bound_ctrl:1
	s_and_saveexec_b64 s[18:19], vcc
	s_cbranch_execz .LBB0_968
	s_lshl_b32 s3, s37, 9
	s_add_i32 s3, s3, 0
	v_lshl_add_u32 v34, v97, 2, s3
	ds_write_b128 v34, v[28:31]
	ds_write_b128 v34, v[20:23] offset:16
	ds_write_b128 v34, v[24:27] offset:128
	ds_write_b128 v34, v[12:15] offset:144
	ds_write_b128 v34, v[16:19] offset:256
	ds_write_b128 v34, v[4:7] offset:272
	ds_write_b128 v34, v[8:11] offset:384
	ds_write_b128 v34, v[0:3] offset:400

; template <bool STORE> __device__ __forceinline__ void h3_phase(unsigned char* lds, unsigned char* ws, const bf16_t* SF, const float* norm_g, int G, int blk) {
;     int tid_l = threadIdx.x; asm volatile("" : "+v"(tid_l)); const int tid = tid_l, lane = tid & 63, wid = __builtin_amdgcn_readfirstlane(tid >> 6), r = lane & 15, kq = lane >> 4;
;     bf16_t* Z = (bf16_t*)(ws + WS_Z); bf16_t* VT = (bf16_t*)(lds + L_VT); float* STGF = (float*)(lds + L_KO) + wid * 16 * 132;
;     for (int unit = blk; unit < 2048; unit += G) {
;         const int b = unit >> 10, c = (unit >> 3) & 127, h = unit & 7, chain = b * 8 + h;
;         const size_t tok0 = (size_t)b * SEQ + c * 128 + 16 * wid;
;         const bf16_t* zrow = Z + ((size_t)h * M + tok0 + r) * 128;
.LBB0_1097:
	s_or_b64 exec, exec, s[4:5]
	s_mov_b64 s[4:5], s[0:1]
	s_mov_b32 s16, s2
	s_mov_b32 s17, s74
	s_waitcnt lgkmcnt(0)
	v_readfirstlane_b32 s62, v254
	s_lshr_b32 s62, s62, 6
	s_sub_u32 s63, 11, s62
	s_cmp_lt_u32 s62, 4
	s_cselect_b32 s62, s62, s63
	s_lshl_b32 s62, s62, 6
	v_and_b32_e32 v0, 63, v254
	v_or_b32_e32 v0, s62, v0
	s_barrier
	s_cmpk_gt_i32 s16, 0x7ff
	v_readfirstlane_b32 s3, v0
	s_cbranch_scc1 .LBB0_1120
	s_load_dwordx4 s[12:15], s[4:5], 0x88
	s_load_dwordx2 s[6:7], s[4:5], 0x38
	v_and_b32_e32 v112, 15, v0
	v_bfe_u32 v114, v0, 4, 2
	v_lshlrev_b32_e32 v0, 3, v0
	s_waitcnt lgkmcnt(0)
	s_add_u32 s18, s12, 0x4000000
	s_addc_u32 s19, s13, 0
	s_add_u32 s10, s14, 0x6800000
	s_addc_u32 s11, s15, 0
	s_ashr_i32 s3, s3, 2
	s_and_b32 s20, s3, -16
	s_mul_i32 s3, s20, 0x210
	s_lshl_b32 s5, s20, 1
	v_and_b32_e32 v0, 0x78, v0
	s_mov_b32 s4, 0
	s_add_i32 s3, s3, 0
	v_mov_b32_e32 v117, 0
	s_add_i32 s5, s5, 0
	v_lshlrev_b32_e32 v116, 2, v0
	v_mul_u32_u24_e32 v5, 0x440, v114
	s_ashr_i32 s21, s20, 31
	s_add_i32 s5, s5, 0x13000
	v_lshlrev_b32_e32 v1, 1, v112
	v_add_u32_e32 v4, s3, v116
	v_lshl_add_u64 v[118:119], s[6:7], 0, v[116:117]
	v_lshlrev_b32_e32 v116, 1, v0
	v_mul_u32_u24_e32 v0, 0x210, v114
	v_lshlrev_b32_e32 v5, 1, v5
	v_or_b32_e32 v122, 4, v114
	s_mov_b32 s6, s4
	s_mov_b32 s7, s4
	v_lshlrev_b32_e32 v2, 3, v114
	s_add_u32 s22, s14, 0x1a800000
	v_lshl_add_u32 v3, v112, 2, s3
	v_add3_u32 v113, s5, v1, v5
	v_add3_u32 v115, s5, v5, v1
	v_mul_u32_u24_e32 v1, 0x840, v114
	v_mul_u32_u24_e32 v5, 0x210, v122
	s_mov_b32 s5, s4
	v_mov_b64_e32 v[186:187], s[6:7]
	v_add_u32_e32 v145, v4, v0
	v_mbcnt_lo_u32_b32 v0, -1, 0
	s_mov_b64 s[8:9], 0x4000000
	s_addc_u32 s23, s15, 0
	v_lshl_add_u64 v[120:121], s[10:11], 0, v[116:117]
	s_movk_i32 s24, 0x440
	v_add_u32_e32 v123, 0x220, v113
	v_add_u32_e32 v125, 0x440, v113
	v_add_u32_e32 v127, 0x660, v113
	v_add_u32_e32 v130, 0x2200, v113
	v_add_u32_e32 v131, 0x2420, v113
	v_add_u32_e32 v132, 0x2640, v113
	v_add_u32_e32 v133, 0x2860, v113
	v_add_u32_e32 v134, 0x4400, v113
	v_add_u32_e32 v135, 0x4620, v113
	v_add_u32_e32 v136, 0x4840, v113
	v_add_u32_e32 v137, 0x4a60, v113
	v_add_u32_e32 v138, 0x6600, v113
	v_add_u32_e32 v139, 0x6820, v113
	v_add_u32_e32 v140, 0x6a40, v113
	v_add_u32_e32 v141, 0x6c60, v113
	v_or_b32_e32 v124, 8, v114
	v_or_b32_e32 v126, 12, v114
	v_lshlrev_b32_e32 v128, 1, v2
	v_mov_b32_e32 v129, v117
	s_mov_b64 s[12:13], 0xc000000
	s_brev_b32 s25, 48
	s_brev_b32 s26, 32
	s_movk_i32 s27, 0x110
	v_mov_b64_e32 v[184:185], s[4:5]
	s_mov_b64 s[14:15], 0x8000000
	s_brev_b32 s28, 16
	v_mov_b32_e32 v142, 0x3727c5ac
	s_mov_b32 s29, 0xf800000
	v_mov_b32_e32 v143, 0x260
	v_add_u32_e32 v144, v3, v1
	s_brev_b32 s30, 8
	v_add_u32_e32 v146, v4, v5
	v_mbcnt_hi_u32_b32 v147, -1, v0
	s_branch .LBB0_1100

; template <int DIR> __device__ __forceinline__ void h3_dir(unsigned char* lds, const bf16_t* zrow, int h, const bf16_t* slot, f32x4 (&o)[8]) {
;     int tid_l = threadIdx.x; asm volatile("" : "+v"(tid_l)); const int tid = tid_l, lane = tid & 63, wid = __builtin_amdgcn_readfirstlane(tid >> 6), r = lane & 15, kq = lane >> 4;
;     float* TOT = (float*)(lds + L_TOT); float* TOTE = (float*)(lds + L_TOTE); bf16_t* KO = (bf16_t*)(lds + L_KO); bf16_t* ST = (bf16_t*)(lds + L_ST); const bf16_t* VT = (const bf16_t*)(lds + L_VT); bf16_t* Pw = (bf16_t*)(lds + L_P) + wid * 16 * HP;
;     float bl[32], qin[32]; bf16x8 kin[4];
;     load32(zrow + (size_t)(1 + DIR) * ZSEG + 8 * kq, bl);
;     load32(zrow + 8 * kq, qin);
;     {
;         float kk[32];
; #pragma unroll
;         for (int i = 0; i < 32; ++i) kk[i] = 1.0f - __builtin_amdgcn_exp2f(bl[i]);
;         scan16x8<DIR>(bl); scan16x8<DIR>(bl + 8); scan16x8<DIR>(bl + 16); scan16x8<DIR>(bl + 24);
; template <bool STORE> __device__ __forceinline__ void h3_phase(unsigned char* lds, unsigned char* ws, const bf16_t* SF, const float* norm_g, int G, int blk) {
;     ...
;         {
; #pragma unroll
;           for (int ks = 0; ks < 4; ++ks) { const u32x4 w = *(const u32x4*)(zrow + 3 * ZSEG + 8 * kq + 32 * ks);
; #pragma unroll
;               for (int e = 0; e < 4; ++e) { VT[(32 * ks + 8 * kq + 2 * e) * HP + 16 * wid + r] = (bf16_t)(w[e] & 0xffffu); VT[(32 * ks + 8 * kq + 2 * e + 1) * HP + 16 * wid + r] = (bf16_t)(w[e] >> 16); } } }
.LBB0_1100:
	s_ashr_i32 s4, s16, 10
	s_bfe_u32 s3, s16, 0x70003
	s_and_b32 s36, s16, 7
	s_ashr_i32 s5, s4, 31
	s_lshl_b64 s[6:7], s[4:5], 14
	s_lshl_b32 s5, s3, 7
	s_lshl_b32 s31, s36, 15
	s_add_u32 s6, s6, s20
	s_addc_u32 s7, s7, s21
	s_add_u32 s6, s6, s31
	s_addc_u32 s7, s7, 0
	s_add_u32 s31, s6, s5
	s_addc_u32 s34, s7, 0
	v_mov_b32_e32 v1, s34
	v_or_b32_e32 v0, s31, v112
	v_lshlrev_b64 v[0:1], 8, v[0:1]
	v_lshl_add_u64 v[80:81], s[10:11], 0, v[0:1]
	v_lshl_add_u64 v[4:5], v[80:81], 0, v[128:129]
	v_add_co_u32_e32 v0, vcc, s25, v4
	v_lshl_add_u64 v[16:17], v[4:5], 0, s[12:13]
	s_nop 0
	v_addc_co_u32_e32 v1, vcc, 0, v5, vcc
	global_load_dwordx4 v[0:3], v[0:1], off
	s_nop 0
	global_load_dwordx4 v[4:7], v[16:17], off offset:64
	global_load_dwordx4 v[8:11], v[16:17], off offset:128
	global_load_dwordx4 v[12:15], v[16:17], off offset:192
	v_bfe_u32 v206, v254, 4, 2
	v_lshlrev_b32_e32 v206, 4, v206
	v_mov_b32_e32 v207, 0
	v_lshl_add_u64 v[222:223], v[80:81], 0, v[206:207]
	v_lshl_add_u64 v[224:225], v[222:223], 0, s[8:9]
	global_load_dwordx4 v[206:209], v[224:225], off
	global_load_dwordx4 v[210:213], v[224:225], off offset:64
	global_load_dwordx4 v[214:217], v[224:225], off offset:128
	global_load_dwordx4 v[218:221], v[224:225], off offset:192
	global_load_dwordx4 v[64:67], v[222:223], off
	global_load_dwordx4 v[52:55], v[222:223], off offset:64
	global_load_dwordx4 v[48:51], v[222:223], off offset:128
	global_load_dwordx4 v[44:47], v[222:223], off offset:192
	v_and_b32_e32 v85, 63, v254
	v_or_b32_e32 v85, s62, v85
	s_waitcnt vmcnt(11)
	ds_write_b16 v113, v0
	ds_write_b16_d16_hi v115, v0 offset:272
	ds_write_b16 v113, v1 offset:544
	ds_write_b16_d16_hi v123, v1 offset:272
	ds_write_b16 v113, v2 offset:1088
	ds_write_b16_d16_hi v125, v2 offset:272
	ds_write_b16 v113, v3 offset:1632
	ds_write_b16_d16_hi v127, v3 offset:272
	s_waitcnt vmcnt(10)
	ds_write_b16 v113, v4 offset:8704
	ds_write_b16_d16_hi v130, v4 offset:272
	ds_write_b16 v113, v5 offset:9248
	ds_write_b16_d16_hi v131, v5 offset:272
	ds_write_b16 v113, v6 offset:9792
	ds_write_b16_d16_hi v132, v6 offset:272
	ds_write_b16 v113, v7 offset:10336
	ds_write_b16_d16_hi v133, v7 offset:272
	s_waitcnt vmcnt(9)
	ds_write_b16 v113, v8 offset:17408
	ds_write_b16_d16_hi v134, v8 offset:272
	ds_write_b16 v113, v9 offset:17952
	ds_write_b16_d16_hi v135, v9 offset:272
	ds_write_b16 v113, v10 offset:18496
	ds_write_b16_d16_hi v136, v10 offset:272
	ds_write_b16 v113, v11 offset:19040
	ds_write_b16_d16_hi v137, v11 offset:272
	s_waitcnt vmcnt(8)
	ds_write_b16 v113, v12 offset:26112
	ds_write_b16_d16_hi v138, v12 offset:272
	ds_write_b16 v113, v13 offset:26656
	ds_write_b16_d16_hi v139, v13 offset:272
	ds_write_b16 v113, v14 offset:27200
	ds_write_b16_d16_hi v140, v14 offset:272
	ds_write_b16 v113, v15 offset:27744
	ds_write_b16_d16_hi v141, v15 offset:272
	s_nop 0
	v_bfe_u32 v84, v85, 4, 2
	v_lshlrev_b32_e32 v116, 4, v84
	v_lshl_add_u64 v[16:17], v[80:81], 0, v[116:117]
	v_lshl_add_u64 v[18:19], v[16:17], 0, s[8:9]
	s_waitcnt vmcnt(4)
	v_mov_b32_e32 v0, v206
	v_mov_b32_e32 v1, v207
	v_mov_b32_e32 v2, v208
	v_mov_b32_e32 v3, v209
	v_mov_b32_e32 v4, v210
	v_mov_b32_e32 v5, v211
	v_mov_b32_e32 v6, v212
	v_mov_b32_e32 v7, v213
	v_mov_b32_e32 v8, v214
	v_mov_b32_e32 v9, v215
	v_mov_b32_e32 v10, v216
	v_mov_b32_e32 v11, v217
	v_mov_b32_e32 v12, v218
	v_mov_b32_e32 v13, v219
	v_mov_b32_e32 v14, v220
	v_mov_b32_e32 v15, v221
	v_readfirstlane_b32 s5, v85
	s_ashr_i32 s35, s5, 6
	v_and_b32_e32 v83, 15, v85
	v_lshlrev_b32_e32 v82, 3, v84
	v_cmp_eq_u32_e32 vcc, 15, v83
	s_lshl_b32 s37, s35, 9
	s_waitcnt vmcnt(6)
	v_lshlrev_b32_e32 v111, 16, v4
	v_lshlrev_b32_e32 v107, 16, v0
	v_and_b32_e32 v106, 0xffff0000, v0
	v_lshlrev_b32_e32 v152, 16, v1
	v_and_b32_e32 v151, 0xffff0000, v1
	v_lshlrev_b32_e32 v150, 16, v2
	v_and_b32_e32 v149, 0xffff0000, v2
	v_lshlrev_b32_e32 v148, 16, v3
	v_and_b32_e32 v116, 0xffff0000, v3
	v_mov_b32_e32 v26, v148
	v_mov_b32_e32 v33, v106
	v_mov_b32_e32 v35, v151
	v_mov_b32_e32 v25, v149
	v_mov_b32_e32 v32, v107
	v_mov_b32_e32 v27, v116
	v_mov_b32_e32 v34, v152
	v_mov_b32_e32 v24, v150
	s_nop 1
	v_add_f32_dpp v32, v32, v32 row_shr:1 row_mask:0xf bank_mask:0xf bound_ctrl:1
	v_add_f32_dpp v33, v33, v33 row_shr:1 row_mask:0xf bank_mask:0xf bound_ctrl:1
	v_add_f32_dpp v34, v34, v34 row_shr:1 row_mask:0xf bank_mask:0xf bound_ctrl:1
	v_add_f32_dpp v35, v35, v35 row_shr:1 row_mask:0xf bank_mask:0xf bound_ctrl:1
	v_add_f32_dpp v24, v24, v24 row_shr:1 row_mask:0xf bank_mask:0xf bound_ctrl:1
	v_add_f32_dpp v25, v25, v25 row_shr:1 row_mask:0xf bank_mask:0xf bound_ctrl:1
	v_add_f32_dpp v26, v26, v26 row_shr:1 row_mask:0xf bank_mask:0xf bound_ctrl:1
	v_add_f32_dpp v27, v27, v27 row_shr:1 row_mask:0xf bank_mask:0xf bound_ctrl:1
	v_and_b32_e32 v110, 0xffff0000, v4
	v_lshlrev_b32_e32 v109, 16, v5
	v_and_b32_e32 v108, 0xffff0000, v5
	v_lshlrev_b32_e32 v102, 16, v6
	v_and_b32_e32 v103, 0xffff0000, v6
	v_lshlrev_b32_e32 v104, 16, v7
	v_and_b32_e32 v105, 0xffff0000, v7
	s_nop 1
	v_add_f32_dpp v32, v32, v32 row_shr:2 row_mask:0xf bank_mask:0xf bound_ctrl:1
	v_add_f32_dpp v33, v33, v33 row_shr:2 row_mask:0xf bank_mask:0xf bound_ctrl:1
	v_add_f32_dpp v34, v34, v34 row_shr:2 row_mask:0xf bank_mask:0xf bound_ctrl:1
	v_add_f32_dpp v35, v35, v35 row_shr:2 row_mask:0xf bank_mask:0xf bound_ctrl:1
	v_add_f32_dpp v24, v24, v24 row_shr:2 row_mask:0xf bank_mask:0xf bound_ctrl:1
	v_add_f32_dpp v25, v25, v25 row_shr:2 row_mask:0xf bank_mask:0xf bound_ctrl:1
	v_add_f32_dpp v26, v26, v26 row_shr:2 row_mask:0xf bank_mask:0xf bound_ctrl:1
	v_add_f32_dpp v27, v27, v27 row_shr:2 row_mask:0xf bank_mask:0xf bound_ctrl:1
	v_mov_b32_e32 v18, v104
	v_mov_b32_e32 v21, v110
	v_mov_b32_e32 v23, v108
	v_mov_b32_e32 v17, v103
	v_mov_b32_e32 v20, v111
	v_mov_b32_e32 v19, v105
	v_mov_b32_e32 v22, v109
	v_mov_b32_e32 v16, v102
	s_nop 1
	v_add_f32_dpp v32, v32, v32 row_shr:4 row_mask:0xf bank_mask:0xf bound_ctrl:1
	v_add_f32_dpp v33, v33, v33 row_shr:4 row_mask:0xf bank_mask:0xf bound_ctrl:1
	v_add_f32_dpp v34, v34, v34 row_shr:4 row_mask:0xf bank_mask:0xf bound_ctrl:1
	v_add_f32_dpp v35, v35, v35 row_shr:4 row_mask:0xf bank_mask:0xf bound_ctrl:1
	v_add_f32_dpp v24, v24, v24 row_shr:4 row_mask:0xf bank_mask:0xf bound_ctrl:1
	v_add_f32_dpp v25, v25, v25 row_shr:4 row_mask:0xf bank_mask:0xf bound_ctrl:1
	v_add_f32_dpp v26, v26, v26 row_shr:4 row_mask:0xf bank_mask:0xf bound_ctrl:1
	v_add_f32_dpp v27, v27, v27 row_shr:4 row_mask:0xf bank_mask:0xf bound_ctrl:1
	s_waitcnt vmcnt(5)
; template <int DIR> __device__ __forceinline__ void scan16x8(float* v) {
;     if (DIR == 0) { SCAN_STEP("row_shr:", 1); SCAN_STEP("row_shr:", 2); SCAN_STEP("row_shr:", 4); SCAN_STEP("row_shr:", 8); }
;     else          { SCAN_STEP("row_shl:", 1); SCAN_STEP("row_shl:", 2); SCAN_STEP("row_shl:", 4); SCAN_STEP("row_shl:", 8); }
; }
; template <int DIR> __device__ __forceinline__ void h3_dir(unsigned char* lds, const bf16_t* zrow, int h, const bf16_t* slot, f32x4 (&o)[8]) {
;     ...
;         scan16x8<DIR>(bl); scan16x8<DIR>(bl + 8); scan16x8<DIR>(bl + 16); scan16x8<DIR>(bl + 24);
	v_lshlrev_b32_e32 v98, 16, v8
	s_nop 1
	v_add_f32_dpp v32, v32, v32 row_shr:8 row_mask:0xf bank_mask:0xf bound_ctrl:1
	v_add_f32_dpp v33, v33, v33 row_shr:8 row_mask:0xf bank_mask:0xf bound_ctrl:1
	v_add_f32_dpp v34, v34, v34 row_shr:8 row_mask:0xf bank_mask:0xf bound_ctrl:1
	v_add_f32_dpp v35, v35, v35 row_shr:8 row_mask:0xf bank_mask:0xf bound_ctrl:1
	v_add_f32_dpp v24, v24, v24 row_shr:8 row_mask:0xf bank_mask:0xf bound_ctrl:1
	v_add_f32_dpp v25, v25, v25 row_shr:8 row_mask:0xf bank_mask:0xf bound_ctrl:1
	v_add_f32_dpp v26, v26, v26 row_shr:8 row_mask:0xf bank_mask:0xf bound_ctrl:1
	v_add_f32_dpp v27, v27, v27 row_shr:8 row_mask:0xf bank_mask:0xf bound_ctrl:1
	s_nop 1
	v_add_f32_dpp v20, v20, v20 row_shr:1 row_mask:0xf bank_mask:0xf bound_ctrl:1
	v_add_f32_dpp v21, v21, v21 row_shr:1 row_mask:0xf bank_mask:0xf bound_ctrl:1
	v_add_f32_dpp v22, v22, v22 row_shr:1 row_mask:0xf bank_mask:0xf bound_ctrl:1
	v_add_f32_dpp v23, v23, v23 row_shr:1 row_mask:0xf bank_mask:0xf bound_ctrl:1
	v_add_f32_dpp v16, v16, v16 row_shr:1 row_mask:0xf bank_mask:0xf bound_ctrl:1
	v_add_f32_dpp v17, v17, v17 row_shr:1 row_mask:0xf bank_mask:0xf bound_ctrl:1
	v_add_f32_dpp v18, v18, v18 row_shr:1 row_mask:0xf bank_mask:0xf bound_ctrl:1
	v_add_f32_dpp v19, v19, v19 row_shr:1 row_mask:0xf bank_mask:0xf bound_ctrl:1
	v_and_b32_e32 v99, 0xffff0000, v8
	v_lshlrev_b32_e32 v100, 16, v9
	v_and_b32_e32 v101, 0xffff0000, v9
	v_lshlrev_b32_e32 v94, 16, v10
	v_and_b32_e32 v95, 0xffff0000, v10
	v_lshlrev_b32_e32 v96, 16, v11
	v_and_b32_e32 v97, 0xffff0000, v11
	s_nop 1
	v_add_f32_dpp v20, v20, v20 row_shr:2 row_mask:0xf bank_mask:0xf bound_ctrl:1
	v_add_f32_dpp v21, v21, v21 row_shr:2 row_mask:0xf bank_mask:0xf bound_ctrl:1
	v_add_f32_dpp v22, v22, v22 row_shr:2 row_mask:0xf bank_mask:0xf bound_ctrl:1
	v_add_f32_dpp v23, v23, v23 row_shr:2 row_mask:0xf bank_mask:0xf bound_ctrl:1
	v_add_f32_dpp v16, v16, v16 row_shr:2 row_mask:0xf bank_mask:0xf bound_ctrl:1
	v_add_f32_dpp v17, v17, v17 row_shr:2 row_mask:0xf bank_mask:0xf bound_ctrl:1
	v_add_f32_dpp v18, v18, v18 row_shr:2 row_mask:0xf bank_mask:0xf bound_ctrl:1
	v_add_f32_dpp v19, v19, v19 row_shr:2 row_mask:0xf bank_mask:0xf bound_ctrl:1
	s_waitcnt vmcnt(4)
	v_lshlrev_b32_e32 v90, 16, v12
	v_and_b32_e32 v91, 0xffff0000, v12
	v_lshlrev_b32_e32 v92, 16, v13
	v_and_b32_e32 v93, 0xffff0000, v13
	v_lshlrev_b32_e32 v86, 16, v14
	v_and_b32_e32 v87, 0xffff0000, v14
	v_lshlrev_b32_e32 v88, 16, v15
	v_and_b32_e32 v89, 0xffff0000, v15
	v_mov_b32_e32 v10, v96
	v_mov_b32_e32 v13, v99
	v_mov_b32_e32 v15, v101
	v_mov_b32_e32 v9, v95
	v_mov_b32_e32 v12, v98
	v_mov_b32_e32 v11, v97
	v_mov_b32_e32 v14, v100
	v_mov_b32_e32 v8, v94
	s_nop 1
	v_add_f32_dpp v20, v20, v20 row_shr:4 row_mask:0xf bank_mask:0xf bound_ctrl:1
	v_add_f32_dpp v21, v21, v21 row_shr:4 row_mask:0xf bank_mask:0xf bound_ctrl:1
	v_add_f32_dpp v22, v22, v22 row_shr:4 row_mask:0xf bank_mask:0xf bound_ctrl:1
	v_add_f32_dpp v23, v23, v23 row_shr:4 row_mask:0xf bank_mask:0xf bound_ctrl:1
	v_add_f32_dpp v16, v16, v16 row_shr:4 row_mask:0xf bank_mask:0xf bound_ctrl:1
	v_add_f32_dpp v17, v17, v17 row_shr:4 row_mask:0xf bank_mask:0xf bound_ctrl:1
	v_add_f32_dpp v18, v18, v18 row_shr:4 row_mask:0xf bank_mask:0xf bound_ctrl:1
	v_add_f32_dpp v19, v19, v19 row_shr:4 row_mask:0xf bank_mask:0xf bound_ctrl:1
	v_mov_b32_e32 v2, v88
	s_nop 1
	v_add_f32_dpp v20, v20, v20 row_shr:8 row_mask:0xf bank_mask:0xf bound_ctrl:1
	v_add_f32_dpp v21, v21, v21 row_shr:8 row_mask:0xf bank_mask:0xf bound_ctrl:1
	v_add_f32_dpp v22, v22, v22 row_shr:8 row_mask:0xf bank_mask:0xf bound_ctrl:1
	v_add_f32_dpp v23, v23, v23 row_shr:8 row_mask:0xf bank_mask:0xf bound_ctrl:1
	v_add_f32_dpp v16, v16, v16 row_shr:8 row_mask:0xf bank_mask:0xf bound_ctrl:1
	v_add_f32_dpp v17, v17, v17 row_shr:8 row_mask:0xf bank_mask:0xf bound_ctrl:1
	v_add_f32_dpp v18, v18, v18 row_shr:8 row_mask:0xf bank_mask:0xf bound_ctrl:1
	v_add_f32_dpp v19, v19, v19 row_shr:8 row_mask:0xf bank_mask:0xf bound_ctrl:1
	s_nop 1
	v_add_f32_dpp v12, v12, v12 row_shr:1 row_mask:0xf bank_mask:0xf bound_ctrl:1
	v_add_f32_dpp v13, v13, v13 row_shr:1 row_mask:0xf bank_mask:0xf bound_ctrl:1
	v_add_f32_dpp v14, v14, v14 row_shr:1 row_mask:0xf bank_mask:0xf bound_ctrl:1
	v_add_f32_dpp v15, v15, v15 row_shr:1 row_mask:0xf bank_mask:0xf bound_ctrl:1
	v_add_f32_dpp v8, v8, v8 row_shr:1 row_mask:0xf bank_mask:0xf bound_ctrl:1
	v_add_f32_dpp v9, v9, v9 row_shr:1 row_mask:0xf bank_mask:0xf bound_ctrl:1
	v_add_f32_dpp v10, v10, v10 row_shr:1 row_mask:0xf bank_mask:0xf bound_ctrl:1
	v_add_f32_dpp v11, v11, v11 row_shr:1 row_mask:0xf bank_mask:0xf bound_ctrl:1
	v_mov_b32_e32 v5, v91
	s_nop 1
	v_add_f32_dpp v12, v12, v12 row_shr:2 row_mask:0xf bank_mask:0xf bound_ctrl:1
	v_add_f32_dpp v13, v13, v13 row_shr:2 row_mask:0xf bank_mask:0xf bound_ctrl:1
	v_add_f32_dpp v14, v14, v14 row_shr:2 row_mask:0xf bank_mask:0xf bound_ctrl:1
	v_add_f32_dpp v15, v15, v15 row_shr:2 row_mask:0xf bank_mask:0xf bound_ctrl:1
	v_add_f32_dpp v8, v8, v8 row_shr:2 row_mask:0xf bank_mask:0xf bound_ctrl:1
	v_add_f32_dpp v9, v9, v9 row_shr:2 row_mask:0xf bank_mask:0xf bound_ctrl:1
	v_add_f32_dpp v10, v10, v10 row_shr:2 row_mask:0xf bank_mask:0xf bound_ctrl:1
	v_add_f32_dpp v11, v11, v11 row_shr:2 row_mask:0xf bank_mask:0xf bound_ctrl:1
	v_mov_b32_e32 v7, v93
	v_mov_b32_e32 v1, v87
	v_mov_b32_e32 v4, v90
; template <int DIR> __device__ __forceinline__ void h3_dir(unsigned char* lds, const bf16_t* zrow, int h, const bf16_t* slot, f32x4 (&o)[8]) {
;     ...
;         scan16x8<DIR>(bl); scan16x8<DIR>(bl + 8); scan16x8<DIR>(bl + 16); scan16x8<DIR>(bl + 24);
;         float eb[32];
; #pragma unroll
;         for (int i = 0; i < 32; ++i) { eb[i] = __builtin_amdgcn_exp2f(bl[i]); qin[i] *= eb[i]; }
;         if (r == (DIR ? 0 : 15)) {
; #pragma unroll
;             for (int ks = 0; ks < 4; ++ks) { *(f32x4*)(TOT + wid * 128 + 32 * ks + 8 * kq) = (f32x4){bl[8 * ks], bl[8 * ks + 1], bl[8 * ks + 2], bl[8 * ks + 3]}; *(f32x4*)(TOT + wid * 128 + 32 * ks + 8 * kq + 4) = (f32x4){bl[8 * ks + 4], bl[8 * ks + 5], bl[8 * ks + 6], bl[8 * ks + 7]}; }
; #pragma unroll
;             for (int ks = 0; ks < 4; ++ks) { *(f32x4*)(TOTE + wid * 128 + 32 * ks + 8 * kq) = (f32x4){eb[8 * ks], eb[8 * ks + 1], eb[8 * ks + 2], eb[8 * ks + 3]}; *(f32x4*)(TOTE + wid * 128 + 32 * ks + 8 * kq + 4) = (f32x4){eb[8 * ks + 4], eb[8 * ks + 5], eb[8 * ks + 6], eb[8 * ks + 7]}; }
;         }
	v_mov_b32_e32 v3, v89
	v_mov_b32_e32 v6, v92
	v_mov_b32_e32 v0, v86
	s_nop 1
	v_add_f32_dpp v12, v12, v12 row_shr:4 row_mask:0xf bank_mask:0xf bound_ctrl:1
	v_add_f32_dpp v13, v13, v13 row_shr:4 row_mask:0xf bank_mask:0xf bound_ctrl:1
	v_add_f32_dpp v14, v14, v14 row_shr:4 row_mask:0xf bank_mask:0xf bound_ctrl:1
	v_add_f32_dpp v15, v15, v15 row_shr:4 row_mask:0xf bank_mask:0xf bound_ctrl:1
	v_add_f32_dpp v8, v8, v8 row_shr:4 row_mask:0xf bank_mask:0xf bound_ctrl:1
	v_add_f32_dpp v9, v9, v9 row_shr:4 row_mask:0xf bank_mask:0xf bound_ctrl:1
	v_add_f32_dpp v10, v10, v10 row_shr:4 row_mask:0xf bank_mask:0xf bound_ctrl:1
	v_add_f32_dpp v11, v11, v11 row_shr:4 row_mask:0xf bank_mask:0xf bound_ctrl:1
	v_exp_f32_e32 v60, v32
	s_nop 1
	v_add_f32_dpp v12, v12, v12 row_shr:8 row_mask:0xf bank_mask:0xf bound_ctrl:1
	v_add_f32_dpp v13, v13, v13 row_shr:8 row_mask:0xf bank_mask:0xf bound_ctrl:1
	v_add_f32_dpp v14, v14, v14 row_shr:8 row_mask:0xf bank_mask:0xf bound_ctrl:1
	v_add_f32_dpp v15, v15, v15 row_shr:8 row_mask:0xf bank_mask:0xf bound_ctrl:1
	v_add_f32_dpp v8, v8, v8 row_shr:8 row_mask:0xf bank_mask:0xf bound_ctrl:1
	v_add_f32_dpp v9, v9, v9 row_shr:8 row_mask:0xf bank_mask:0xf bound_ctrl:1
	v_add_f32_dpp v10, v10, v10 row_shr:8 row_mask:0xf bank_mask:0xf bound_ctrl:1
	v_add_f32_dpp v11, v11, v11 row_shr:8 row_mask:0xf bank_mask:0xf bound_ctrl:1
	s_nop 1
	v_add_f32_dpp v4, v4, v4 row_shr:1 row_mask:0xf bank_mask:0xf bound_ctrl:1
	v_add_f32_dpp v5, v5, v5 row_shr:1 row_mask:0xf bank_mask:0xf bound_ctrl:1
	v_add_f32_dpp v6, v6, v6 row_shr:1 row_mask:0xf bank_mask:0xf bound_ctrl:1
	v_add_f32_dpp v7, v7, v7 row_shr:1 row_mask:0xf bank_mask:0xf bound_ctrl:1
	v_add_f32_dpp v0, v0, v0 row_shr:1 row_mask:0xf bank_mask:0xf bound_ctrl:1
	v_add_f32_dpp v1, v1, v1 row_shr:1 row_mask:0xf bank_mask:0xf bound_ctrl:1
	v_add_f32_dpp v2, v2, v2 row_shr:1 row_mask:0xf bank_mask:0xf bound_ctrl:1
	v_add_f32_dpp v3, v3, v3 row_shr:1 row_mask:0xf bank_mask:0xf bound_ctrl:1
	v_exp_f32_e32 v61, v33
	s_nop 1
	v_add_f32_dpp v4, v4, v4 row_shr:2 row_mask:0xf bank_mask:0xf bound_ctrl:1
	v_add_f32_dpp v5, v5, v5 row_shr:2 row_mask:0xf bank_mask:0xf bound_ctrl:1
	v_add_f32_dpp v6, v6, v6 row_shr:2 row_mask:0xf bank_mask:0xf bound_ctrl:1
	v_add_f32_dpp v7, v7, v7 row_shr:2 row_mask:0xf bank_mask:0xf bound_ctrl:1
	v_add_f32_dpp v0, v0, v0 row_shr:2 row_mask:0xf bank_mask:0xf bound_ctrl:1
	v_add_f32_dpp v1, v1, v1 row_shr:2 row_mask:0xf bank_mask:0xf bound_ctrl:1
	v_add_f32_dpp v2, v2, v2 row_shr:2 row_mask:0xf bank_mask:0xf bound_ctrl:1
	v_add_f32_dpp v3, v3, v3 row_shr:2 row_mask:0xf bank_mask:0xf bound_ctrl:1
	v_exp_f32_e32 v62, v34
	s_nop 1
	v_add_f32_dpp v4, v4, v4 row_shr:4 row_mask:0xf bank_mask:0xf bound_ctrl:1
	v_add_f32_dpp v5, v5, v5 row_shr:4 row_mask:0xf bank_mask:0xf bound_ctrl:1
	v_add_f32_dpp v6, v6, v6 row_shr:4 row_mask:0xf bank_mask:0xf bound_ctrl:1
	v_add_f32_dpp v7, v7, v7 row_shr:4 row_mask:0xf bank_mask:0xf bound_ctrl:1
	v_add_f32_dpp v0, v0, v0 row_shr:4 row_mask:0xf bank_mask:0xf bound_ctrl:1
	v_add_f32_dpp v1, v1, v1 row_shr:4 row_mask:0xf bank_mask:0xf bound_ctrl:1
	v_add_f32_dpp v2, v2, v2 row_shr:4 row_mask:0xf bank_mask:0xf bound_ctrl:1
	v_add_f32_dpp v3, v3, v3 row_shr:4 row_mask:0xf bank_mask:0xf bound_ctrl:1
	v_exp_f32_e32 v63, v35
	v_exp_f32_e32 v56, v24
	v_exp_f32_e32 v57, v25
	v_exp_f32_e32 v58, v26
	v_exp_f32_e32 v59, v27
	v_exp_f32_e32 v72, v20
	v_exp_f32_e32 v73, v21
	v_exp_f32_e32 v74, v22
	v_exp_f32_e32 v75, v23
	v_exp_f32_e32 v68, v16
	v_exp_f32_e32 v69, v17
	v_exp_f32_e32 v70, v18
	v_exp_f32_e32 v71, v19
	v_exp_f32_e32 v76, v12
	v_exp_f32_e32 v77, v13
	v_exp_f32_e32 v78, v14
	v_exp_f32_e32 v79, v15
	v_exp_f32_e32 v40, v8
	v_exp_f32_e32 v41, v9
	v_exp_f32_e32 v42, v10
	v_exp_f32_e32 v43, v11
	s_nop 1
	v_add_f32_dpp v4, v4, v4 row_shr:8 row_mask:0xf bank_mask:0xf bound_ctrl:1
	v_add_f32_dpp v5, v5, v5 row_shr:8 row_mask:0xf bank_mask:0xf bound_ctrl:1
	v_add_f32_dpp v6, v6, v6 row_shr:8 row_mask:0xf bank_mask:0xf bound_ctrl:1
	v_add_f32_dpp v7, v7, v7 row_shr:8 row_mask:0xf bank_mask:0xf bound_ctrl:1
	v_add_f32_dpp v0, v0, v0 row_shr:8 row_mask:0xf bank_mask:0xf bound_ctrl:1
	v_add_f32_dpp v1, v1, v1 row_shr:8 row_mask:0xf bank_mask:0xf bound_ctrl:1
	v_add_f32_dpp v2, v2, v2 row_shr:8 row_mask:0xf bank_mask:0xf bound_ctrl:1
	v_add_f32_dpp v3, v3, v3 row_shr:8 row_mask:0xf bank_mask:0xf bound_ctrl:1
	s_nop 0
	v_exp_f32_e32 v36, v4
	v_exp_f32_e32 v37, v5
	v_exp_f32_e32 v38, v6
	v_exp_f32_e32 v39, v7
	v_exp_f32_e32 v28, v0
	v_exp_f32_e32 v29, v1
	v_exp_f32_e32 v30, v2
	v_exp_f32_e32 v31, v3
	s_and_saveexec_b64 s[6:7], vcc
	s_cbranch_execz .LBB0_1102
	s_add_i32 s5, s37, 0
	v_lshl_add_u32 v153, v82, 2, s5
	ds_write_b128 v153, v[32:35]
	ds_write_b128 v153, v[24:27] offset:16
	ds_write_b128 v153, v[20:23] offset:128
	ds_write_b128 v153, v[16:19] offset:144
	ds_write_b128 v153, v[12:15] offset:256
	ds_write_b128 v153, v[8:11] offset:272
	ds_write_b128 v153, v[4:7] offset:384
	ds_write_b128 v153, v[0:3] offset:400
	ds_write_b128 v153, v[60:63] offset:4096
	ds_write_b128 v153, v[56:59] offset:4112
	ds_write_b128 v153, v[72:75] offset:4224
	ds_write_b128 v153, v[68:71] offset:4240
	ds_write_b128 v153, v[76:79] offset:4352
	ds_write_b128 v153, v[40:43] offset:4368
	ds_write_b128 v153, v[36:39] offset:4480
	ds_write_b128 v153, v[28:31] offset:4496

; __device__ __forceinline__ bf16x8 pk8(const float* v) { u32x4 w; w.x = cvt_pk_bf16(v[0], v[1]); w.y = cvt_pk_bf16(v[2], v[3]); w.z = cvt_pk_bf16(v[4], v[5]); w.w = cvt_pk_bf16(v[6], v[7]); return __builtin_bit_cast(bf16x8, w); }
; #define WAVE_LDS_FENCE() do { asm volatile("s_waitcnt lgkmcnt(0)" ::: "memory"); __builtin_amdgcn_wave_barrier(); } while (0)
; template <int DIR> __device__ __forceinline__ void h3_dir(unsigned char* lds, const bf16_t* zrow, int h, const bf16_t* slot, f32x4 (&o)[8]) {
;     ...
; #pragma unroll
;     for (int i = 0; i < 32; ++i) qin[i] *= run[i];
;     WAVE_LDS_FENCE();
; #pragma unroll
;     for (int ks = 0; ks < 4; ++ks) {
;         const bf16x8 aq = pk8(qin + 8 * ks), ap = *(const bf16x8*)(Pw + r * HP + 32 * ks + 8 * kq);
; #pragma unroll
;         for (int nt = 0; nt < 8; ++nt) {
;             o[nt] = __builtin_amdgcn_mfma_f32_16x16x32_bf16(aq, *(const bf16x8*)(ST + (16 * nt + r) * HP + 32 * ks + 8 * kq), o[nt], 0, 0, 0);
;             o[nt] = __builtin_amdgcn_mfma_f32_16x16x32_bf16(ap, *(const bf16x8*)(VT + (16 * nt + r) * HP + 32 * ks + 8 * kq), o[nt], 0, 0, 0);
;         }
.LBB0_1110:
	v_mul_u32_u24_e32 v45, 0x88, v83
	v_lshlrev_b32_e32 v45, 1, v45
	v_lshlrev_b32_e32 v44, 1, v82
	v_add_u32_e32 v110, v40, v45
	v_mul_u32_u24_e32 v40, 0x110, v83
	v_mul_f32_e32 v24, v60, v24
	v_mul_f32_e32 v25, v61, v25
	v_mul_f32_e32 v26, v62, v26
	v_mul_f32_e32 v27, v63, v27
	v_mul_f32_e32 v28, v64, v28
	v_mul_f32_e32 v29, v65, v29
	v_mul_f32_e32 v30, v66, v30
	v_mul_f32_e32 v31, v59, v31
	v_add3_u32 v102, s6, v40, v44
	s_waitcnt lgkmcnt(0)
	v_cvt_pk_bf16_f32 v24, v24, v25
	v_cvt_pk_bf16_f32 v25, v26, v27
	v_cvt_pk_bf16_f32 v26, v28, v29
	v_cvt_pk_bf16_f32 v27, v30, v31
	ds_read_b128 v[28:31], v110 offset:43008
	ds_read_b128 v[60:63], v102
	s_add_i32 s35, 0, 0x13000
	v_add3_u32 v111, s35, v44, v45
	ds_read_b128 v[64:67], v111
	s_waitcnt lgkmcnt(2)
	v_mfma_f32_16x16x32_bf16 v[28:31], v[24:27], v[28:31], 0
	v_add_u32_e32 v40, 0xa800, v110
	ds_read_b128 v[68:71], v40 offset:30464
	v_mul_f32_e32 v45, v54, v22
	s_waitcnt lgkmcnt(1)
	v_mfma_f32_16x16x32_bf16 v[28:31], v[60:63], v[64:67], v[28:31]
	ds_read_b128 v[64:67], v110 offset:47360
	ds_read_b128 v[72:75], v110 offset:51712
	ds_read_b128 v[76:79], v111 offset:4352
	ds_read_b128 v[82:85], v111 offset:8704
	v_mul_f32_e32 v54, v55, v23
	s_waitcnt lgkmcnt(3)
	v_mfma_f32_16x16x32_bf16 v[64:67], v[24:27], v[64:67], 0
	v_mul_f32_e32 v55, v56, v16
	v_mul_f32_e32 v51, v51, v17
	v_mul_f32_e32 v56, v52, v18
	s_waitcnt lgkmcnt(2)
	v_mfma_f32_16x16x32_bf16 v[72:75], v[24:27], v[72:75], 0
	v_mul_f32_e32 v44, v58, v21
	v_add_u32_e32 v116, 0xa8c0, v110
	v_and_b32_e32 v151, 63, v254
	v_or_b32_e32 v151, s62, v151
	s_waitcnt lgkmcnt(1)
	v_mfma_f32_16x16x32_bf16 v[64:67], v[60:63], v[76:79], v[64:67]
	s_waitcnt lgkmcnt(0)
	v_mfma_f32_16x16x32_bf16 v[72:75], v[60:63], v[82:85], v[72:75]
	ds_read_b128 v[76:79], v110 offset:56064
	ds_read_b128 v[82:85], v110 offset:60416
	ds_read_b128 v[86:89], v111 offset:13056
	ds_read_b128 v[90:93], v111 offset:17408
	s_waitcnt lgkmcnt(3)
	v_mfma_f32_16x16x32_bf16 v[76:79], v[24:27], v[76:79], 0
	s_waitcnt lgkmcnt(2)
	v_mfma_f32_16x16x32_bf16 v[82:85], v[24:27], v[82:85], 0
	s_waitcnt lgkmcnt(1)
	v_mfma_f32_16x16x32_bf16 v[76:79], v[60:63], v[86:89], v[76:79]
	s_waitcnt lgkmcnt(0)
	v_mfma_f32_16x16x32_bf16 v[82:85], v[60:63], v[90:93], v[82:85]
	ds_read_b128 v[86:89], v110 offset:64768
	ds_read_b128 v[90:93], v40 offset:26112
	ds_read_b128 v[94:97], v111 offset:21760
	ds_read_b128 v[98:101], v111 offset:26112
	v_mul_f32_e32 v40, v57, v20
	s_waitcnt lgkmcnt(3)
	v_mfma_f32_16x16x32_bf16 v[86:89], v[24:27], v[86:89], 0
	v_mul_f32_e32 v57, v53, v19
	s_waitcnt lgkmcnt(2)
	v_mfma_f32_16x16x32_bf16 v[90:93], v[24:27], v[90:93], 0
	v_mfma_f32_16x16x32_bf16 v[16:19], v[24:27], v[68:71], 0
	ds_read_b128 v[24:27], v111 offset:30464
	v_cvt_pk_bf16_f32 v52, v40, v44
	v_cvt_pk_bf16_f32 v53, v45, v54
	v_cvt_pk_bf16_f32 v54, v55, v51
	v_cvt_pk_bf16_f32 v55, v56, v57
	ds_read_b128 v[56:59], v110 offset:43072
	s_waitcnt lgkmcnt(1)
	v_mfma_f32_16x16x32_bf16 v[16:19], v[60:63], v[24:27], v[16:19]
	ds_read_b128 v[24:27], v102 offset:64
	v_mul_f32_e32 v40, v49, v8
	v_mfma_f32_16x16x32_bf16 v[86:89], v[60:63], v[94:97], v[86:89]
	v_mul_f32_e32 v94, v50, v9
	v_mfma_f32_16x16x32_bf16 v[20:23], v[60:63], v[98:101], v[90:93]
	s_waitcnt lgkmcnt(1)
	v_mfma_f32_16x16x32_bf16 v[28:31], v[52:55], v[56:59], v[28:31]
	ds_read_b128 v[56:59], v111 offset:64
	ds_read_b128 v[60:63], v110 offset:64832
	s_waitcnt lgkmcnt(1)
	v_mfma_f32_16x16x32_bf16 v[28:31], v[24:27], v[56:59], v[28:31]
	ds_read_b128 v[56:59], v110 offset:47424
	ds_read_b128 v[68:71], v110 offset:51776
	s_waitcnt lgkmcnt(1)
	v_mfma_f32_16x16x32_bf16 v[56:59], v[52:55], v[56:59], v[64:67]
	s_nop 2
	ds_read_b128 v[64:67], v111 offset:4416
	ds_read_b128 v[90:93], v111 offset:8768
	s_waitcnt lgkmcnt(1)
	v_mfma_f32_16x16x32_bf16 v[56:59], v[24:27], v[64:67], v[56:59]
	v_mfma_f32_16x16x32_bf16 v[64:67], v[52:55], v[68:71], v[72:75]
	s_waitcnt lgkmcnt(0)
	v_mfma_f32_16x16x32_bf16 v[64:67], v[24:27], v[90:93], v[64:67]
	ds_read_b128 v[68:71], v110 offset:56128
	ds_read_b128 v[72:75], v111 offset:13120
	ds_read_b128 v[90:93], v110 offset:60480
	s_waitcnt lgkmcnt(2)
	v_mfma_f32_16x16x32_bf16 v[68:71], v[52:55], v[68:71], v[76:79]
	s_nop 2
	ds_read_b128 v[76:79], v111 offset:17472
	s_waitcnt lgkmcnt(2)
	v_mfma_f32_16x16x32_bf16 v[68:71], v[24:27], v[72:75], v[68:71]
	v_mul_f32_e32 v72, v46, v10
	v_mul_f32_e32 v73, v47, v11
	v_mul_f32_e32 v74, v48, v4
	s_waitcnt lgkmcnt(1)
	v_mfma_f32_16x16x32_bf16 v[8:11], v[52:55], v[90:93], v[82:85]
	v_mul_f32_e32 v90, v32, v12
	v_add_u32_e32 v32, 0xa840, v110
	v_mul_f32_e32 v75, v41, v5
	v_mul_f32_e32 v82, v42, v6
	v_mul_f32_e32 v83, v34, v7
	s_waitcnt lgkmcnt(0)
	v_mfma_f32_16x16x32_bf16 v[4:7], v[24:27], v[76:79], v[8:11]
	v_mul_f32_e32 v91, v33, v13
	v_mul_f32_e32 v92, v43, v1
	v_mul_f32_e32 v93, v38, v2
	ds_read_b128 v[8:11], v111 offset:21824
	v_mfma_f32_16x16x32_bf16 v[44:47], v[52:55], v[60:63], v[86:89]
	ds_read_b128 v[48:51], v32 offset:26112
	ds_read_b128 v[60:63], v111 offset:26176
	s_nop 0
	v_mul_f32_e32 v87, v36, v14
	v_mul_f32_e32 v88, v37, v15
	ds_read_b128 v[12:15], v111 offset:30528
	v_mul_f32_e32 v89, v35, v0
	ds_read_b128 v[32:35], v32 offset:30464
	s_waitcnt lgkmcnt(4)
	v_mfma_f32_16x16x32_bf16 v[8:11], v[24:27], v[8:11], v[44:47]
	v_cvt_pk_bf16_f32 v40, v40, v94
	v_cvt_pk_bf16_f32 v41, v72, v73
	v_cvt_pk_bf16_f32 v42, v74, v75
	s_waitcnt lgkmcnt(0)
; __device__ __forceinline__ float bf_lo(unsigned w) { return __uint_as_float(w << 16); }
; __device__ __forceinline__ float bf_hi(unsigned w) { return __uint_as_float(w & 0xffff0000u); }
; __device__ __forceinline__ bf16x8 pk8(const float* v) { u32x4 w; w.x = cvt_pk_bf16(v[0], v[1]); w.y = cvt_pk_bf16(v[2], v[3]); w.z = cvt_pk_bf16(v[4], v[5]); w.w = cvt_pk_bf16(v[6], v[7]); return __builtin_bit_cast(bf16x8, w); }
; __device__ __forceinline__ void load32(const bf16_t* p, float (&v)[32]) {
; #pragma unroll
;     for (int ks = 0; ks < 4; ++ks) { const u32x4 w = *(const u32x4*)(p + 32 * ks);
;         v[8 * ks + 0] = bf_lo(w.x); v[8 * ks + 1] = bf_hi(w.x); v[8 * ks + 2] = bf_lo(w.y); v[8 * ks + 3] = bf_hi(w.y); v[8 * ks + 4] = bf_lo(w.z); v[8 * ks + 5] = bf_hi(w.z); v[8 * ks + 6] = bf_lo(w.w); v[8 * ks + 7] = bf_hi(w.w); }
; template <int DIR> __device__ __forceinline__ void h3_dir(unsigned char* lds, const bf16_t* zrow, int h, const bf16_t* slot, f32x4 (&o)[8]) {
;     ...
;     for (int ks = 0; ks < 4; ++ks) {
;         const bf16x8 aq = pk8(qin + 8 * ks), ap = *(const bf16x8*)(Pw + r * HP + 32 * ks + 8 * kq);
; #pragma unroll
;         for (int nt = 0; nt < 8; ++nt) {
;             o[nt] = __builtin_amdgcn_mfma_f32_16x16x32_bf16(aq, *(const bf16x8*)(ST + (16 * nt + r) * HP + 32 * ks + 8 * kq), o[nt], 0, 0, 0);
;             o[nt] = __builtin_amdgcn_mfma_f32_16x16x32_bf16(ap, *(const bf16x8*)(VT + (16 * nt + r) * HP + 32 * ks + 8 * kq), o[nt], 0, 0, 0);
;         }
;     }
;     __syncthreads();
	v_mfma_f32_16x16x32_bf16 v[16:19], v[52:55], v[32:35], v[16:19]
	v_cvt_pk_bf16_f32 v43, v82, v83
	ds_read_b128 v[32:35], v102 offset:128
	ds_read_b128 v[44:47], v110 offset:43136
	v_mul_f32_e32 v94, v39, v3
	v_mfma_f32_16x16x32_bf16 v[20:23], v[52:55], v[48:51], v[20:23]
	ds_read_b128 v[0:3], v111 offset:128
	v_add_u32_e32 v82, 0xa880, v110
	v_mfma_f32_16x16x32_bf16 v[20:23], v[24:27], v[60:63], v[20:23]
	v_mfma_f32_16x16x32_bf16 v[12:15], v[24:27], v[12:15], v[16:19]
	s_waitcnt lgkmcnt(1)
	v_mfma_f32_16x16x32_bf16 v[16:19], v[40:43], v[44:47], v[28:31]
	ds_read_b128 v[24:27], v110 offset:47488
	s_nop 1
	ds_read_b128 v[28:31], v110 offset:64896
	s_waitcnt lgkmcnt(2)
	v_mfma_f32_16x16x32_bf16 v[0:3], v[32:35], v[0:3], v[16:19]
	s_nop 2
	ds_read_b128 v[16:19], v110 offset:51840
	ds_read_b128 v[36:39], v111 offset:4480
	ds_read_b128 v[44:47], v111 offset:8832
	s_waitcnt lgkmcnt(4)
	v_mfma_f32_16x16x32_bf16 v[24:27], v[40:43], v[24:27], v[56:59]
	ds_read_b128 v[48:51], v110 offset:56192
	ds_read_b128 v[52:55], v110 offset:60544
	s_nop 0
	ds_read_b128 v[56:59], v111 offset:13184
	ds_read_b128 v[60:63], v111 offset:17536
	s_waitcnt lgkmcnt(2)
	v_mfma_f32_16x16x32_bf16 v[4:7], v[40:43], v[52:55], v[4:7]
	v_mfma_f32_16x16x32_bf16 v[16:19], v[40:43], v[16:19], v[64:67]
	v_mfma_f32_16x16x32_bf16 v[36:39], v[32:35], v[36:39], v[24:27]
	s_nop 2
	ds_read_b128 v[24:27], v111 offset:21888
	ds_read_b128 v[72:75], v111 offset:26240
	ds_read_b128 v[76:79], v82 offset:30464
	ds_read_b128 v[64:67], v82 offset:26112
	ds_read_b128 v[82:85], v111 offset:30592
	v_cvt_pk_bf16_f32 v86, v90, v91
	s_waitcnt lgkmcnt(5)
	v_mfma_f32_16x16x32_bf16 v[60:63], v[32:35], v[60:63], v[4:7]
	v_cvt_pk_bf16_f32 v87, v87, v88
	v_cvt_pk_bf16_f32 v88, v89, v92
	v_cvt_pk_bf16_f32 v89, v93, v94
	v_mfma_f32_16x16x32_bf16 v[4:7], v[40:43], v[28:31], v[8:11]
	v_mfma_f32_16x16x32_bf16 v[16:19], v[32:35], v[44:47], v[16:19]
	v_mfma_f32_16x16x32_bf16 v[44:47], v[40:43], v[48:51], v[68:71]
	ds_read_b128 v[48:51], v102 offset:192
	s_nop 1
	ds_read_b128 v[68:71], v110 offset:43200
	ds_read_b128 v[90:93], v110 offset:47552
	ds_read_b128 v[94:97], v110 offset:51904
	s_waitcnt lgkmcnt(8)
	v_mfma_f32_16x16x32_bf16 v[208:211], v[32:35], v[24:27], v[4:7]
	s_waitcnt lgkmcnt(5)
	v_mfma_f32_16x16x32_bf16 v[4:7], v[40:43], v[64:67], v[20:23]
	v_mfma_f32_16x16x32_bf16 v[44:47], v[32:35], v[56:59], v[44:47]
	ds_read_b128 v[56:59], v111 offset:4544
	ds_read_b128 v[98:101], v111 offset:8896
	ds_read_b128 v[102:105], v110 offset:56256
	ds_read_b128 v[106:109], v110 offset:60608
	ds_read_b128 v[52:55], v111 offset:13248
	ds_read_b128 v[152:155], v111 offset:17600
	ds_read_b128 v[156:159], v111 offset:192
	ds_read_b128 v[188:191], v110 offset:64960
	ds_read_b128 v[192:195], v111 offset:21952
	ds_read_b128 v[196:199], v111 offset:26304
	ds_read_b128 v[200:203], v116 offset:30464
	ds_read_b128 v[28:31], v116 offset:26112
	ds_read_b128 v[204:207], v111 offset:30656
	s_waitcnt lgkmcnt(0)
	s_barrier
	v_mfma_f32_16x16x32_bf16 v[20:23], v[32:35], v[72:75], v[4:7]
	v_bfe_u32 v150, v151, 4, 2
	v_lshlrev_b32_e32 v116, 4, v150
	v_lshl_add_u64 v[80:81], v[80:81], 0, v[116:117]
	v_add_co_u32_e32 v4, vcc, s28, v80
	v_lshl_add_u64 v[24:25], v[80:81], 0, s[14:15]
	s_nop 0
	v_addc_co_u32_e32 v5, vcc, 0, v81, vcc
	s_waitcnt vmcnt(0)
	v_mov_b32_e32 v4, v212
	v_mov_b32_e32 v5, v213
	v_mov_b32_e32 v6, v214
	v_mov_b32_e32 v7, v215
	v_mfma_f32_16x16x32_bf16 v[8:11], v[40:43], v[76:79], v[12:15]
	v_mov_b32_e32 v40, v220
	v_mov_b32_e32 v41, v221
	v_mov_b32_e32 v42, v222
	v_mov_b32_e32 v43, v223
	v_mov_b32_e32 v64, v224
	v_mov_b32_e32 v65, v225
	v_mov_b32_e32 v66, v226
	v_mov_b32_e32 v67, v227
	v_readfirstlane_b32 s3, v151
	v_mov_b32_e32 v12, v216
	v_mov_b32_e32 v13, v217
	v_mov_b32_e32 v14, v218
	v_mov_b32_e32 v15, v219
	v_mfma_f32_16x16x32_bf16 v[32:35], v[32:35], v[82:85], v[8:11]
	s_ashr_i32 s36, s3, 6
	v_and_b32_e32 v149, 15, v151
	v_lshlrev_b32_e32 v148, 3, v150
	v_mfma_f32_16x16x32_bf16 v[8:11], v[86:89], v[102:105], v[44:47]
	v_cmp_eq_u32_e32 vcc, 0, v149
	s_lshl_b32 s3, s36, 9
	s_waitcnt vmcnt(3)
	v_lshlrev_b32_e32 v182, 16, v4
	v_and_b32_e32 v181, 0xffff0000, v4
	v_lshlrev_b32_e32 v180, 16, v5
	v_and_b32_e32 v179, 0xffff0000, v5
	v_lshlrev_b32_e32 v177, 16, v6
	v_and_b32_e32 v178, 0xffff0000, v6
	v_lshlrev_b32_e32 v176, 16, v7
	v_and_b32_e32 v174, 0xffff0000, v7
	v_mfma_f32_16x16x32_bf16 v[4:7], v[86:89], v[94:97], v[16:19]
	s_waitcnt vmcnt(0)
; __device__ __forceinline__ float bf_lo(unsigned w) { return __uint_as_float(w << 16); }
; __device__ __forceinline__ float bf_hi(unsigned w) { return __uint_as_float(w & 0xffff0000u); }
; __device__ __forceinline__ bf16x8 pk8(const float* v) { u32x4 w; w.x = cvt_pk_bf16(v[0], v[1]); w.y = cvt_pk_bf16(v[2], v[3]); w.z = cvt_pk_bf16(v[4], v[5]); w.w = cvt_pk_bf16(v[6], v[7]); return __builtin_bit_cast(bf16x8, w); }
; template <int DIR> __device__ __forceinline__ void scan16x8(float* v) {
;     if (DIR == 0) { SCAN_STEP("row_shr:", 1); SCAN_STEP("row_shr:", 2); SCAN_STEP("row_shr:", 4); SCAN_STEP("row_shr:", 8); }
;     else          { SCAN_STEP("row_shl:", 1); SCAN_STEP("row_shl:", 2); SCAN_STEP("row_shl:", 4); SCAN_STEP("row_shl:", 8); }
; }
; __device__ __forceinline__ void load32(const bf16_t* p, float (&v)[32]) {
; #pragma unroll
;     for (int ks = 0; ks < 4; ++ks) { const u32x4 w = *(const u32x4*)(p + 32 * ks);
;         v[8 * ks + 0] = bf_lo(w.x); v[8 * ks + 1] = bf_hi(w.x); v[8 * ks + 2] = bf_lo(w.y); v[8 * ks + 3] = bf_hi(w.y); v[8 * ks + 4] = bf_lo(w.z); v[8 * ks + 5] = bf_hi(w.z); v[8 * ks + 6] = bf_lo(w.w); v[8 * ks + 7] = bf_hi(w.w); }
; template <int DIR> __device__ __forceinline__ void h3_dir(unsigned char* lds, const bf16_t* zrow, int h, const bf16_t* slot, f32x4 (&o)[8]) {
;     ...
;     for (int ks = 0; ks < 4; ++ks) {
;         const bf16x8 aq = pk8(qin + 8 * ks), ap = *(const bf16x8*)(Pw + r * HP + 32 * ks + 8 * kq);
; #pragma unroll
;         for (int nt = 0; nt < 8; ++nt) {
;             o[nt] = __builtin_amdgcn_mfma_f32_16x16x32_bf16(aq, *(const bf16x8*)(ST + (16 * nt + r) * HP + 32 * ks + 8 * kq), o[nt], 0, 0, 0);
;             o[nt] = __builtin_amdgcn_mfma_f32_16x16x32_bf16(ap, *(const bf16x8*)(VT + (16 * nt + r) * HP + 32 * ks + 8 * kq), o[nt], 0, 0, 0);
;         }
;     }
	v_lshlrev_b32_e32 v175, 16, v12
	v_and_b32_e32 v173, 0xffff0000, v12
	v_lshlrev_b32_e32 v116, 16, v13
	v_mfma_f32_16x16x32_bf16 v[4:7], v[48:51], v[98:101], v[4:7]
	v_and_b32_e32 v172, 0xffff0000, v13
	v_lshlrev_b32_e32 v168, 16, v14
	v_and_b32_e32 v169, 0xffff0000, v14
	v_lshlrev_b32_e32 v170, 16, v15
	v_and_b32_e32 v171, 0xffff0000, v15
	v_mfma_f32_16x16x32_bf16 v[12:15], v[86:89], v[106:109], v[60:63]
	v_mov_b32_e32 v108, v230
	v_mov_b32_e32 v109, v231
	v_mov_b32_e32 v110, v232
	v_mov_b32_e32 v111, v233
	v_mov_b32_e32 v104, v234
	v_mov_b32_e32 v105, v235
	v_mov_b32_e32 v106, v236
	v_mov_b32_e32 v107, v237
	v_mov_b32_e32 v100, v238
	v_mov_b32_e32 v101, v239
	v_mov_b32_e32 v102, v240
	v_mov_b32_e32 v103, v241
	v_mov_b32_e32 v96, v242
	v_mov_b32_e32 v97, v243
	v_mov_b32_e32 v98, v244
	v_mov_b32_e32 v99, v245
	v_mov_b32_e32 v60, v177
	v_mov_b32_e32 v62, v176
	v_mfma_f32_16x16x32_bf16 v[0:3], v[86:89], v[68:71], v[0:3]
	v_mov_b32_e32 v61, v178
	v_mov_b32_e32 v63, v174
	v_lshlrev_b32_e32 v164, 16, v40
	v_mfma_f32_16x16x32_bf16 v[24:27], v[48:51], v[156:159], v[0:3]
	v_lshlrev_b32_e32 v156, 16, v64
	v_and_b32_e32 v157, 0xffff0000, v64
	v_lshlrev_b32_e32 v158, 16, v65
	v_mfma_f32_16x16x32_bf16 v[0:3], v[86:89], v[90:93], v[36:39]
	v_and_b32_e32 v159, 0xffff0000, v65
	v_mov_b32_e32 v65, v181
	v_mov_b32_e32 v64, v182
	v_mfma_f32_16x16x32_bf16 v[16:19], v[86:89], v[188:191], v[208:211]
	v_and_b32_e32 v165, 0xffff0000, v40
	v_lshlrev_b32_e32 v166, 16, v41
	v_and_b32_e32 v167, 0xffff0000, v41
	v_mfma_f32_16x16x32_bf16 v[20:23], v[86:89], v[28:31], v[20:23]
	v_lshlrev_b32_e32 v160, 16, v42
	v_and_b32_e32 v161, 0xffff0000, v42
	v_lshlrev_b32_e32 v162, 16, v43
	v_mfma_f32_16x16x32_bf16 v[28:31], v[86:89], v[200:203], v[32:35]
	v_and_b32_e32 v163, 0xffff0000, v43
	v_mov_b32_e32 v40, v160
	v_mov_b32_e32 v42, v162
	v_mfma_f32_16x16x32_bf16 v[12:15], v[48:51], v[152:155], v[12:15]
	v_lshlrev_b32_e32 v152, 16, v66
	v_and_b32_e32 v153, 0xffff0000, v66
	v_lshlrev_b32_e32 v154, 16, v67
	v_and_b32_e32 v155, 0xffff0000, v67
	v_mov_b32_e32 v67, v179
	v_mov_b32_e32 v66, v180
	s_nop 1
	v_add_f32_dpp v64, v64, v64 row_shl:1 row_mask:0xf bank_mask:0xf bound_ctrl:1
	v_add_f32_dpp v65, v65, v65 row_shl:1 row_mask:0xf bank_mask:0xf bound_ctrl:1
	v_add_f32_dpp v66, v66, v66 row_shl:1 row_mask:0xf bank_mask:0xf bound_ctrl:1
	v_add_f32_dpp v67, v67, v67 row_shl:1 row_mask:0xf bank_mask:0xf bound_ctrl:1
	v_add_f32_dpp v60, v60, v60 row_shl:1 row_mask:0xf bank_mask:0xf bound_ctrl:1
	v_add_f32_dpp v61, v61, v61 row_shl:1 row_mask:0xf bank_mask:0xf bound_ctrl:1
	v_add_f32_dpp v62, v62, v62 row_shl:1 row_mask:0xf bank_mask:0xf bound_ctrl:1
	v_add_f32_dpp v63, v63, v63 row_shl:1 row_mask:0xf bank_mask:0xf bound_ctrl:1
	v_mfma_f32_16x16x32_bf16 v[0:3], v[48:51], v[56:59], v[0:3]
	s_nop 1
	v_add_f32_dpp v64, v64, v64 row_shl:2 row_mask:0xf bank_mask:0xf bound_ctrl:1
	v_add_f32_dpp v65, v65, v65 row_shl:2 row_mask:0xf bank_mask:0xf bound_ctrl:1
	v_add_f32_dpp v66, v66, v66 row_shl:2 row_mask:0xf bank_mask:0xf bound_ctrl:1
	v_add_f32_dpp v67, v67, v67 row_shl:2 row_mask:0xf bank_mask:0xf bound_ctrl:1
	v_add_f32_dpp v60, v60, v60 row_shl:2 row_mask:0xf bank_mask:0xf bound_ctrl:1
	v_add_f32_dpp v61, v61, v61 row_shl:2 row_mask:0xf bank_mask:0xf bound_ctrl:1
	v_add_f32_dpp v62, v62, v62 row_shl:2 row_mask:0xf bank_mask:0xf bound_ctrl:1
	v_add_f32_dpp v63, v63, v63 row_shl:2 row_mask:0xf bank_mask:0xf bound_ctrl:1
	v_mov_b32_e32 v45, v165
	s_nop 1
	v_add_f32_dpp v64, v64, v64 row_shl:4 row_mask:0xf bank_mask:0xf bound_ctrl:1
	v_add_f32_dpp v65, v65, v65 row_shl:4 row_mask:0xf bank_mask:0xf bound_ctrl:1
	v_add_f32_dpp v66, v66, v66 row_shl:4 row_mask:0xf bank_mask:0xf bound_ctrl:1
	v_add_f32_dpp v67, v67, v67 row_shl:4 row_mask:0xf bank_mask:0xf bound_ctrl:1
	v_add_f32_dpp v60, v60, v60 row_shl:4 row_mask:0xf bank_mask:0xf bound_ctrl:1
	v_add_f32_dpp v61, v61, v61 row_shl:4 row_mask:0xf bank_mask:0xf bound_ctrl:1
	v_add_f32_dpp v62, v62, v62 row_shl:4 row_mask:0xf bank_mask:0xf bound_ctrl:1
	v_add_f32_dpp v63, v63, v63 row_shl:4 row_mask:0xf bank_mask:0xf bound_ctrl:1
	v_mfma_f32_16x16x32_bf16 v[8:11], v[48:51], v[52:55], v[8:11]
	v_mov_b32_e32 v53, v173
	v_mov_b32_e32 v55, v172
	v_mov_b32_e32 v52, v175
	v_mfma_f32_16x16x32_bf16 v[16:19], v[48:51], v[192:195], v[16:19]
	v_mov_b32_e32 v54, v116
	s_nop 1
	v_add_f32_dpp v64, v64, v64 row_shl:8 row_mask:0xf bank_mask:0xf bound_ctrl:1
	v_add_f32_dpp v65, v65, v65 row_shl:8 row_mask:0xf bank_mask:0xf bound_ctrl:1
	v_add_f32_dpp v66, v66, v66 row_shl:8 row_mask:0xf bank_mask:0xf bound_ctrl:1
	v_add_f32_dpp v67, v67, v67 row_shl:8 row_mask:0xf bank_mask:0xf bound_ctrl:1
	v_add_f32_dpp v60, v60, v60 row_shl:8 row_mask:0xf bank_mask:0xf bound_ctrl:1
	v_add_f32_dpp v61, v61, v61 row_shl:8 row_mask:0xf bank_mask:0xf bound_ctrl:1
	v_add_f32_dpp v62, v62, v62 row_shl:8 row_mask:0xf bank_mask:0xf bound_ctrl:1
	v_add_f32_dpp v63, v63, v63 row_shl:8 row_mask:0xf bank_mask:0xf bound_ctrl:1
	v_mov_b32_e32 v47, v167
	v_mfma_f32_16x16x32_bf16 v[20:23], v[48:51], v[196:199], v[20:23]
	v_mov_b32_e32 v41, v161
	v_mov_b32_e32 v44, v164
	v_mov_b32_e32 v43, v163
	v_mfma_f32_16x16x32_bf16 v[28:31], v[48:51], v[204:207], v[28:31]
	v_mov_b32_e32 v48, v168
	v_mov_b32_e32 v50, v170
	v_mov_b32_e32 v49, v169
	v_mov_b32_e32 v51, v171
	s_nop 1
	v_add_f32_dpp v52, v52, v52 row_shl:1 row_mask:0xf bank_mask:0xf bound_ctrl:1
	v_add_f32_dpp v53, v53, v53 row_shl:1 row_mask:0xf bank_mask:0xf bound_ctrl:1
	v_add_f32_dpp v54, v54, v54 row_shl:1 row_mask:0xf bank_mask:0xf bound_ctrl:1
	v_add_f32_dpp v55, v55, v55 row_shl:1 row_mask:0xf bank_mask:0xf bound_ctrl:1
; template <int DIR> __device__ __forceinline__ void scan16x8(float* v) {
;     if (DIR == 0) { SCAN_STEP("row_shr:", 1); SCAN_STEP("row_shr:", 2); SCAN_STEP("row_shr:", 4); SCAN_STEP("row_shr:", 8); }
;     else          { SCAN_STEP("row_shl:", 1); SCAN_STEP("row_shl:", 2); SCAN_STEP("row_shl:", 4); SCAN_STEP("row_shl:", 8); }
; }
	v_add_f32_dpp v48, v48, v48 row_shl:1 row_mask:0xf bank_mask:0xf bound_ctrl:1
	v_add_f32_dpp v49, v49, v49 row_shl:1 row_mask:0xf bank_mask:0xf bound_ctrl:1
	v_add_f32_dpp v50, v50, v50 row_shl:1 row_mask:0xf bank_mask:0xf bound_ctrl:1
	v_add_f32_dpp v51, v51, v51 row_shl:1 row_mask:0xf bank_mask:0xf bound_ctrl:1
	v_mov_b32_e32 v46, v166
	s_nop 1
	v_add_f32_dpp v52, v52, v52 row_shl:2 row_mask:0xf bank_mask:0xf bound_ctrl:1
	v_add_f32_dpp v53, v53, v53 row_shl:2 row_mask:0xf bank_mask:0xf bound_ctrl:1
	v_add_f32_dpp v54, v54, v54 row_shl:2 row_mask:0xf bank_mask:0xf bound_ctrl:1
	v_add_f32_dpp v55, v55, v55 row_shl:2 row_mask:0xf bank_mask:0xf bound_ctrl:1
	v_add_f32_dpp v48, v48, v48 row_shl:2 row_mask:0xf bank_mask:0xf bound_ctrl:1
	v_add_f32_dpp v49, v49, v49 row_shl:2 row_mask:0xf bank_mask:0xf bound_ctrl:1
	v_add_f32_dpp v50, v50, v50 row_shl:2 row_mask:0xf bank_mask:0xf bound_ctrl:1
	v_add_f32_dpp v51, v51, v51 row_shl:2 row_mask:0xf bank_mask:0xf bound_ctrl:1
	v_mov_b32_e32 v32, v152
	s_nop 1
	v_add_f32_dpp v52, v52, v52 row_shl:4 row_mask:0xf bank_mask:0xf bound_ctrl:1
	v_add_f32_dpp v53, v53, v53 row_shl:4 row_mask:0xf bank_mask:0xf bound_ctrl:1
	v_add_f32_dpp v54, v54, v54 row_shl:4 row_mask:0xf bank_mask:0xf bound_ctrl:1
	v_add_f32_dpp v55, v55, v55 row_shl:4 row_mask:0xf bank_mask:0xf bound_ctrl:1
	v_add_f32_dpp v48, v48, v48 row_shl:4 row_mask:0xf bank_mask:0xf bound_ctrl:1
	v_add_f32_dpp v49, v49, v49 row_shl:4 row_mask:0xf bank_mask:0xf bound_ctrl:1
	v_add_f32_dpp v50, v50, v50 row_shl:4 row_mask:0xf bank_mask:0xf bound_ctrl:1
	v_add_f32_dpp v51, v51, v51 row_shl:4 row_mask:0xf bank_mask:0xf bound_ctrl:1
	v_mov_b32_e32 v34, v154
	s_nop 1
	v_add_f32_dpp v52, v52, v52 row_shl:8 row_mask:0xf bank_mask:0xf bound_ctrl:1
	v_add_f32_dpp v53, v53, v53 row_shl:8 row_mask:0xf bank_mask:0xf bound_ctrl:1
	v_add_f32_dpp v54, v54, v54 row_shl:8 row_mask:0xf bank_mask:0xf bound_ctrl:1
	v_add_f32_dpp v55, v55, v55 row_shl:8 row_mask:0xf bank_mask:0xf bound_ctrl:1
	v_add_f32_dpp v48, v48, v48 row_shl:8 row_mask:0xf bank_mask:0xf bound_ctrl:1
	v_add_f32_dpp v49, v49, v49 row_shl:8 row_mask:0xf bank_mask:0xf bound_ctrl:1
	v_add_f32_dpp v50, v50, v50 row_shl:8 row_mask:0xf bank_mask:0xf bound_ctrl:1
	v_add_f32_dpp v51, v51, v51 row_shl:8 row_mask:0xf bank_mask:0xf bound_ctrl:1
	s_nop 1
	v_add_f32_dpp v44, v44, v44 row_shl:1 row_mask:0xf bank_mask:0xf bound_ctrl:1
	v_add_f32_dpp v45, v45, v45 row_shl:1 row_mask:0xf bank_mask:0xf bound_ctrl:1
	v_add_f32_dpp v46, v46, v46 row_shl:1 row_mask:0xf bank_mask:0xf bound_ctrl:1
	v_add_f32_dpp v47, v47, v47 row_shl:1 row_mask:0xf bank_mask:0xf bound_ctrl:1
	v_add_f32_dpp v40, v40, v40 row_shl:1 row_mask:0xf bank_mask:0xf bound_ctrl:1
	v_add_f32_dpp v41, v41, v41 row_shl:1 row_mask:0xf bank_mask:0xf bound_ctrl:1
	v_add_f32_dpp v42, v42, v42 row_shl:1 row_mask:0xf bank_mask:0xf bound_ctrl:1
	v_add_f32_dpp v43, v43, v43 row_shl:1 row_mask:0xf bank_mask:0xf bound_ctrl:1
	v_mov_b32_e32 v37, v157
	s_nop 1
	v_add_f32_dpp v44, v44, v44 row_shl:2 row_mask:0xf bank_mask:0xf bound_ctrl:1
	v_add_f32_dpp v45, v45, v45 row_shl:2 row_mask:0xf bank_mask:0xf bound_ctrl:1
	v_add_f32_dpp v46, v46, v46 row_shl:2 row_mask:0xf bank_mask:0xf bound_ctrl:1
	v_add_f32_dpp v47, v47, v47 row_shl:2 row_mask:0xf bank_mask:0xf bound_ctrl:1
	v_add_f32_dpp v40, v40, v40 row_shl:2 row_mask:0xf bank_mask:0xf bound_ctrl:1
	v_add_f32_dpp v41, v41, v41 row_shl:2 row_mask:0xf bank_mask:0xf bound_ctrl:1
	v_add_f32_dpp v42, v42, v42 row_shl:2 row_mask:0xf bank_mask:0xf bound_ctrl:1
	v_add_f32_dpp v43, v43, v43 row_shl:2 row_mask:0xf bank_mask:0xf bound_ctrl:1
	v_mov_b32_e32 v39, v159
	s_nop 1
	v_add_f32_dpp v44, v44, v44 row_shl:4 row_mask:0xf bank_mask:0xf bound_ctrl:1
	v_add_f32_dpp v45, v45, v45 row_shl:4 row_mask:0xf bank_mask:0xf bound_ctrl:1
	v_add_f32_dpp v46, v46, v46 row_shl:4 row_mask:0xf bank_mask:0xf bound_ctrl:1
	v_add_f32_dpp v47, v47, v47 row_shl:4 row_mask:0xf bank_mask:0xf bound_ctrl:1
	v_add_f32_dpp v40, v40, v40 row_shl:4 row_mask:0xf bank_mask:0xf bound_ctrl:1
	v_add_f32_dpp v41, v41, v41 row_shl:4 row_mask:0xf bank_mask:0xf bound_ctrl:1
	v_add_f32_dpp v42, v42, v42 row_shl:4 row_mask:0xf bank_mask:0xf bound_ctrl:1
	v_add_f32_dpp v43, v43, v43 row_shl:4 row_mask:0xf bank_mask:0xf bound_ctrl:1
	v_mov_b32_e32 v33, v153
	v_mov_b32_e32 v36, v156
	v_mov_b32_e32 v35, v155
	v_mov_b32_e32 v38, v158
	s_nop 1
	v_add_f32_dpp v44, v44, v44 row_shl:8 row_mask:0xf bank_mask:0xf bound_ctrl:1
	v_add_f32_dpp v45, v45, v45 row_shl:8 row_mask:0xf bank_mask:0xf bound_ctrl:1
; template <int DIR> __device__ __forceinline__ void h3_dir(unsigned char* lds, const bf16_t* zrow, int h, const bf16_t* slot, f32x4 (&o)[8]) {
;     ...
;         for (int i = 0; i < 32; ++i) kk[i] = 1.0f - __builtin_amdgcn_exp2f(bl[i]);
;         scan16x8<DIR>(bl); scan16x8<DIR>(bl + 8); scan16x8<DIR>(bl + 16); scan16x8<DIR>(bl + 24);
;         float eb[32];
; #pragma unroll
;         for (int i = 0; i < 32; ++i) { eb[i] = __builtin_amdgcn_exp2f(bl[i]); qin[i] *= eb[i]; }
;         if (r == (DIR ? 0 : 15)) {
; #pragma unroll
;             for (int ks = 0; ks < 4; ++ks) { *(f32x4*)(TOT + wid * 128 + 32 * ks + 8 * kq) = (f32x4){bl[8 * ks], bl[8 * ks + 1], bl[8 * ks + 2], bl[8 * ks + 3]}; *(f32x4*)(TOT + wid * 128 + 32 * ks + 8 * kq + 4) = (f32x4){bl[8 * ks + 4], bl[8 * ks + 5], bl[8 * ks + 6], bl[8 * ks + 7]}; }
; #pragma unroll
;             for (int ks = 0; ks < 4; ++ks) { *(f32x4*)(TOTE + wid * 128 + 32 * ks + 8 * kq) = (f32x4){eb[8 * ks], eb[8 * ks + 1], eb[8 * ks + 2], eb[8 * ks + 3]}; *(f32x4*)(TOTE + wid * 128 + 32 * ks + 8 * kq + 4) = (f32x4){eb[8 * ks + 4], eb[8 * ks + 5], eb[8 * ks + 6], eb[8 * ks + 7]}; }
;         }
	v_add_f32_dpp v46, v46, v46 row_shl:8 row_mask:0xf bank_mask:0xf bound_ctrl:1
	v_add_f32_dpp v47, v47, v47 row_shl:8 row_mask:0xf bank_mask:0xf bound_ctrl:1
	v_add_f32_dpp v40, v40, v40 row_shl:8 row_mask:0xf bank_mask:0xf bound_ctrl:1
	v_add_f32_dpp v41, v41, v41 row_shl:8 row_mask:0xf bank_mask:0xf bound_ctrl:1
	v_add_f32_dpp v42, v42, v42 row_shl:8 row_mask:0xf bank_mask:0xf bound_ctrl:1
	v_add_f32_dpp v43, v43, v43 row_shl:8 row_mask:0xf bank_mask:0xf bound_ctrl:1
	s_nop 1
	v_add_f32_dpp v36, v36, v36 row_shl:1 row_mask:0xf bank_mask:0xf bound_ctrl:1
	v_add_f32_dpp v37, v37, v37 row_shl:1 row_mask:0xf bank_mask:0xf bound_ctrl:1
	v_add_f32_dpp v38, v38, v38 row_shl:1 row_mask:0xf bank_mask:0xf bound_ctrl:1
	v_add_f32_dpp v39, v39, v39 row_shl:1 row_mask:0xf bank_mask:0xf bound_ctrl:1
	v_add_f32_dpp v32, v32, v32 row_shl:1 row_mask:0xf bank_mask:0xf bound_ctrl:1
	v_add_f32_dpp v33, v33, v33 row_shl:1 row_mask:0xf bank_mask:0xf bound_ctrl:1
	v_add_f32_dpp v34, v34, v34 row_shl:1 row_mask:0xf bank_mask:0xf bound_ctrl:1
	v_add_f32_dpp v35, v35, v35 row_shl:1 row_mask:0xf bank_mask:0xf bound_ctrl:1
	v_exp_f32_e32 v92, v64
	s_nop 1
	v_add_f32_dpp v36, v36, v36 row_shl:2 row_mask:0xf bank_mask:0xf bound_ctrl:1
	v_add_f32_dpp v37, v37, v37 row_shl:2 row_mask:0xf bank_mask:0xf bound_ctrl:1
	v_add_f32_dpp v38, v38, v38 row_shl:2 row_mask:0xf bank_mask:0xf bound_ctrl:1
	v_add_f32_dpp v39, v39, v39 row_shl:2 row_mask:0xf bank_mask:0xf bound_ctrl:1
	v_add_f32_dpp v32, v32, v32 row_shl:2 row_mask:0xf bank_mask:0xf bound_ctrl:1
	v_add_f32_dpp v33, v33, v33 row_shl:2 row_mask:0xf bank_mask:0xf bound_ctrl:1
	v_add_f32_dpp v34, v34, v34 row_shl:2 row_mask:0xf bank_mask:0xf bound_ctrl:1
	v_add_f32_dpp v35, v35, v35 row_shl:2 row_mask:0xf bank_mask:0xf bound_ctrl:1
	v_exp_f32_e32 v93, v65
	s_nop 1
	v_add_f32_dpp v36, v36, v36 row_shl:4 row_mask:0xf bank_mask:0xf bound_ctrl:1
	v_add_f32_dpp v37, v37, v37 row_shl:4 row_mask:0xf bank_mask:0xf bound_ctrl:1
	v_add_f32_dpp v38, v38, v38 row_shl:4 row_mask:0xf bank_mask:0xf bound_ctrl:1
	v_add_f32_dpp v39, v39, v39 row_shl:4 row_mask:0xf bank_mask:0xf bound_ctrl:1
	v_add_f32_dpp v32, v32, v32 row_shl:4 row_mask:0xf bank_mask:0xf bound_ctrl:1
	v_add_f32_dpp v33, v33, v33 row_shl:4 row_mask:0xf bank_mask:0xf bound_ctrl:1
	v_add_f32_dpp v34, v34, v34 row_shl:4 row_mask:0xf bank_mask:0xf bound_ctrl:1
	v_add_f32_dpp v35, v35, v35 row_shl:4 row_mask:0xf bank_mask:0xf bound_ctrl:1
	v_exp_f32_e32 v94, v66
	s_nop 1
	v_add_f32_dpp v36, v36, v36 row_shl:8 row_mask:0xf bank_mask:0xf bound_ctrl:1
	v_add_f32_dpp v37, v37, v37 row_shl:8 row_mask:0xf bank_mask:0xf bound_ctrl:1
	v_add_f32_dpp v38, v38, v38 row_shl:8 row_mask:0xf bank_mask:0xf bound_ctrl:1
	v_add_f32_dpp v39, v39, v39 row_shl:8 row_mask:0xf bank_mask:0xf bound_ctrl:1
	v_add_f32_dpp v32, v32, v32 row_shl:8 row_mask:0xf bank_mask:0xf bound_ctrl:1
	v_add_f32_dpp v33, v33, v33 row_shl:8 row_mask:0xf bank_mask:0xf bound_ctrl:1
	v_add_f32_dpp v34, v34, v34 row_shl:8 row_mask:0xf bank_mask:0xf bound_ctrl:1
	v_add_f32_dpp v35, v35, v35 row_shl:8 row_mask:0xf bank_mask:0xf bound_ctrl:1
	v_exp_f32_e32 v95, v67
	v_exp_f32_e32 v88, v60
	v_exp_f32_e32 v89, v61
	v_exp_f32_e32 v90, v62
	v_exp_f32_e32 v91, v63
	v_exp_f32_e32 v84, v52
	v_exp_f32_e32 v85, v53
	v_exp_f32_e32 v86, v54
	v_exp_f32_e32 v87, v55
	v_exp_f32_e32 v80, v48
	v_exp_f32_e32 v81, v49
	v_exp_f32_e32 v82, v50
	v_exp_f32_e32 v83, v51
	v_exp_f32_e32 v76, v44
	v_exp_f32_e32 v77, v45
	v_exp_f32_e32 v78, v46
	v_exp_f32_e32 v79, v47
	v_exp_f32_e32 v72, v40
	v_exp_f32_e32 v73, v41
	v_exp_f32_e32 v74, v42
	v_exp_f32_e32 v75, v43
	v_exp_f32_e32 v68, v36
	v_exp_f32_e32 v69, v37
	v_exp_f32_e32 v70, v38
	v_exp_f32_e32 v71, v39
	v_exp_f32_e32 v56, v32
	v_exp_f32_e32 v57, v33
	v_exp_f32_e32 v58, v34
	v_exp_f32_e32 v59, v35
	s_and_saveexec_b64 s[6:7], vcc
	s_cbranch_execz .LBB0_1112
	s_add_i32 s37, s3, 0
	v_lshl_add_u32 v183, v148, 2, s37
	ds_write_b128 v183, v[64:67]
	ds_write_b128 v183, v[60:63] offset:16
	ds_write_b128 v183, v[52:55] offset:128
	ds_write_b128 v183, v[48:51] offset:144
	ds_write_b128 v183, v[44:47] offset:256
	ds_write_b128 v183, v[40:43] offset:272
	ds_write_b128 v183, v[36:39] offset:384
	ds_write_b128 v183, v[32:35] offset:400
	ds_write_b128 v183, v[92:95] offset:4096
	ds_write_b128 v183, v[88:91] offset:4112
	ds_write_b128 v183, v[84:87] offset:4224
	ds_write_b128 v183, v[80:83] offset:4240
	ds_write_b128 v183, v[76:79] offset:4352
	ds_write_b128 v183, v[72:75] offset:4368
	ds_write_b128 v183, v[68:71] offset:4480
	ds_write_b128 v183, v[56:59] offset:4496

; __device__ __forceinline__ void h1_phase(unsigned char* lds, unsigned char* ws, bf16_t* SF, int G, int blk) {
;     int tid_l = threadIdx.x; asm volatile("" : "+v"(tid_l)); const int tid = tid_l, lane = tid & 63, wid = __builtin_amdgcn_readfirstlane(tid >> 6), r = lane & 15, kq = lane >> 4;
;     const bf16_t* Z = (const bf16_t*)(ws + WS_Z); bf16_t* VT = (bf16_t*)(lds + L_VT);
;     for (int unit = blk; unit < 2048; unit += G) {
;         const int b = unit >> 10, c = (unit >> 3) & 127, h = unit & 7, chain = b * 8 + h;
;         const bf16_t* zrow = Z + ((size_t)h * M + (size_t)b * SEQ + c * 128 + 16 * wid + r) * 128;
.LBB0_2450:
	s_or_b64 exec, exec, s[4:5]
	s_mov_b32 s20, s74
	s_mov_b64 s[4:5], s[0:1]
	s_mov_b32 s21, s2
	s_waitcnt lgkmcnt(0)
	v_readfirstlane_b32 s62, v254
	s_lshr_b32 s62, s62, 6
	s_sub_u32 s63, 11, s62
	s_cmp_lt_u32 s62, 4
	s_cselect_b32 s62, s62, s63
	s_lshl_b32 s62, s62, 6
	v_and_b32_e32 v0, 63, v254
	v_or_b32_e32 v0, s62, v0
	s_barrier
	s_cmpk_gt_i32 s21, 0x7ff
	v_readfirstlane_b32 s3, v0
	s_cbranch_scc1 .LBB0_2497
	s_load_dwordx4 s[8:11], s[4:5], 0x88
	v_and_b32_e32 v1, 15, v0
	v_lshrrev_b32_e32 v0, 1, v0
	v_and_b32_e32 v0, 24, v0
	v_lshlrev_b32_e32 v2, 1, v1
	s_waitcnt lgkmcnt(0)
	s_add_u32 s22, s8, 0x4000000
	s_addc_u32 s23, s9, 0
	s_add_u32 s6, s10, 0x6800000
	s_addc_u32 s7, s11, 0
	s_ashr_i32 s3, s3, 2
	s_and_b32 s3, s3, -16
	s_lshl_b32 s8, s3, 1
	s_add_i32 s8, s8, 0
	s_ashr_i32 s9, s3, 31
	s_add_u32 s24, s10, 0x1fa00000
	s_addc_u32 s25, s11, 0
	v_or_b32_e32 v32, s3, v1
	s_add_u32 s26, s10, 0x1a800000
	v_mul_u32_u24_e32 v1, 0x88, v0
	s_addc_u32 s27, s11, 0
	v_lshlrev_b32_e32 v1, 1, v1
	s_add_i32 s8, s8, 0x13000
	v_mov_b32_e32 v35, 0
	v_add3_u32 v81, v1, s8, v2
	s_mov_b64 s[4:5], 0x4000000
	v_mov_b32_e32 v33, s9
	v_add3_u32 v80, s8, v2, v1
	v_add_u32_e32 v82, 0x220, v81
	v_add_u32_e32 v83, 0x440, v81
	v_add_u32_e32 v84, 0x660, v81
	v_add_u32_e32 v85, 0x2200, v81
	v_add_u32_e32 v86, 0x2420, v81
	v_add_u32_e32 v87, 0x2640, v81
	v_add_u32_e32 v88, 0x2860, v81
	v_add_u32_e32 v89, 0x4400, v81
	v_add_u32_e32 v90, 0x4620, v81
	v_add_u32_e32 v91, 0x4840, v81
	v_add_u32_e32 v92, 0x4a60, v81
	v_add_u32_e32 v93, 0x6600, v81
	v_add_u32_e32 v94, 0x6820, v81
	v_add_u32_e32 v95, 0x6a40, v81
	v_add_u32_e32 v96, 0x6c60, v81
	v_lshlrev_b32_e32 v36, 1, v0
	v_mov_b32_e32 v37, v35
	s_mov_b64 s[8:9], 0xc000000
	s_brev_b32 s28, 48
	s_brev_b32 s29, 32
	s_movk_i32 s30, 0x110
	s_mov_b64 s[10:11], 0x8000000
	s_brev_b32 s31, 16
	s_mov_b64 s[12:13], 0x100000
	s_mov_b32 s34, 0x100000
	s_add_i32 s35, 0, 0x13000
	s_branch .LBB0_2453

; template <int DIR> __device__ __forceinline__ void h1_dir(unsigned char* lds, const bf16_t* zrow, int h, bf16_t* slot, float* decp) {
;     int tid_l = threadIdx.x; asm volatile("" : "+v"(tid_l)); const int tid = tid_l, lane = tid & 63, wid = __builtin_amdgcn_readfirstlane(tid >> 6), r = lane & 15, kq = lane >> 4;
;     float* TOT = (float*)(lds + L_TOT); bf16_t* KS = (bf16_t*)(lds + L_KO); bf16_t* VT = (bf16_t*)(lds + L_VT); bf16_t* STG = (bf16_t*)(lds + L_ST);
;     float bl[32], kk[32];
;     load32(zrow + (size_t)(1 + DIR) * ZSEG + 8 * kq, bl);
; #pragma unroll
;     for (int i = 0; i < 32; ++i) kk[i] = 1.0f - __builtin_amdgcn_exp2f(bl[i]);
;         scan16x8<DIR>(bl); scan16x8<DIR>(bl + 8); scan16x8<DIR>(bl + 16); scan16x8<DIR>(bl + 24);
; __device__ __forceinline__ void h1_phase(unsigned char* lds, unsigned char* ws, bf16_t* SF, int G, int blk) {
;     ...
;         const int b = unit >> 10, c = (unit >> 3) & 127, h = unit & 7, chain = b * 8 + h;
;         const bf16_t* zrow = Z + ((size_t)h * M + (size_t)b * SEQ + c * 128 + 16 * wid + r) * 128;
;         {
; #pragma unroll
;           for (int ks = 0; ks < 4; ++ks) { const u32x4 w = *(const u32x4*)(zrow + 3 * ZSEG + 8 * kq + 32 * ks);
; #pragma unroll
;               for (int e = 0; e < 4; ++e) { VT[(32 * ks + 8 * kq + 2 * e) * HP + 16 * wid + r] = (bf16_t)(w[e] & 0xffffu); VT[(32 * ks + 8 * kq + 2 * e + 1) * HP + 16 * wid + r] = (bf16_t)(w[e] >> 16); } } }
.LBB0_2453:
	s_ashr_i32 s14, s21, 10
	s_bfe_u32 s36, s21, 0x70003
	s_ashr_i32 s15, s14, 31
	s_and_b32 s38, s21, 7
	s_lshl_b64 s[16:17], s[14:15], 14
	s_lshl_b32 s15, s36, 7
	s_lshl_b32 s3, s38, 15
	s_or_b32 s15, s16, s15
	s_add_u32 s16, s15, s3
	s_addc_u32 s17, s17, 0
	v_lshl_add_u64 v[0:1], s[16:17], 0, v[32:33]
	v_lshlrev_b64 v[0:1], 8, v[0:1]
	v_lshl_add_u64 v[38:39], s[6:7], 0, v[0:1]
	v_lshl_add_u64 v[4:5], v[38:39], 0, v[36:37]
	v_add_co_u32_e32 v0, vcc, s28, v4
	v_lshl_add_u64 v[16:17], v[4:5], 0, s[8:9]
	s_nop 0
	v_addc_co_u32_e32 v1, vcc, 0, v5, vcc
	global_load_dwordx4 v[0:3], v[0:1], off
	s_nop 0
	global_load_dwordx4 v[4:7], v[16:17], off offset:64
	global_load_dwordx4 v[8:11], v[16:17], off offset:128
	global_load_dwordx4 v[12:15], v[16:17], off offset:192
	v_and_b32_e32 v97, 63, v254
	v_or_b32_e32 v97, s62, v97
	s_waitcnt vmcnt(3)
	ds_write_b16 v80, v0
	ds_write_b16_d16_hi v81, v0 offset:272
	ds_write_b16 v80, v1 offset:544
	ds_write_b16_d16_hi v82, v1 offset:272
	ds_write_b16 v80, v2 offset:1088
	ds_write_b16_d16_hi v83, v2 offset:272
	ds_write_b16 v80, v3 offset:1632
	ds_write_b16_d16_hi v84, v3 offset:272
	s_waitcnt vmcnt(2)
	ds_write_b16 v80, v4 offset:8704
	ds_write_b16_d16_hi v85, v4 offset:272
	ds_write_b16 v80, v5 offset:9248
	ds_write_b16_d16_hi v86, v5 offset:272
	ds_write_b16 v80, v6 offset:9792
	ds_write_b16_d16_hi v87, v6 offset:272
	ds_write_b16 v80, v7 offset:10336
	ds_write_b16_d16_hi v88, v7 offset:272
	s_waitcnt vmcnt(1)
	ds_write_b16 v80, v8 offset:17408
	ds_write_b16_d16_hi v89, v8 offset:272
	ds_write_b16 v80, v9 offset:17952
	ds_write_b16_d16_hi v90, v9 offset:272
	ds_write_b16 v80, v10 offset:18496
	ds_write_b16_d16_hi v91, v10 offset:272
	ds_write_b16 v80, v11 offset:19040
	ds_write_b16_d16_hi v92, v11 offset:272
	s_waitcnt vmcnt(0)
	ds_write_b16 v80, v12 offset:26112
	ds_write_b16_d16_hi v93, v12 offset:272
	ds_write_b16 v80, v13 offset:26656
	ds_write_b16_d16_hi v94, v13 offset:272
	ds_write_b16 v80, v14 offset:27200
	ds_write_b16_d16_hi v95, v14 offset:272
	ds_write_b16 v80, v15 offset:27744
	ds_write_b16_d16_hi v96, v15 offset:272
	s_nop 0
	v_bfe_u32 v98, v97, 4, 2
	v_lshlrev_b32_e32 v34, 4, v98
	v_lshl_add_u64 v[4:5], v[38:39], 0, v[34:35]
	v_add_co_u32_e32 v0, vcc, s29, v4
	v_lshl_add_u64 v[16:17], v[4:5], 0, s[4:5]
	s_nop 0
	v_addc_co_u32_e32 v1, vcc, 0, v5, vcc
	global_load_dwordx4 v[0:3], v[0:1], off
	s_nop 0
	global_load_dwordx4 v[4:7], v[16:17], off offset:64
	global_load_dwordx4 v[8:11], v[16:17], off offset:128
	global_load_dwordx4 v[12:15], v[16:17], off offset:192
	v_readfirstlane_b32 s3, v97
	v_and_b32_e32 v99, 15, v97
	s_ashr_i32 s37, s3, 6
	v_lshlrev_b32_e32 v100, 3, v98
	v_cmp_eq_u32_e32 vcc, 15, v99
	s_waitcnt vmcnt(2)
	v_lshlrev_b32_e32 v109, 16, v4
	v_lshlrev_b32_e32 v101, 16, v0
	v_and_b32_e32 v102, 0xffff0000, v0
	v_lshlrev_b32_e32 v103, 16, v1
	v_and_b32_e32 v104, 0xffff0000, v1
	v_lshlrev_b32_e32 v105, 16, v2
	v_and_b32_e32 v106, 0xffff0000, v2
	v_lshlrev_b32_e32 v107, 16, v3
	v_and_b32_e32 v108, 0xffff0000, v3
	v_mov_b32_e32 v20, v105
	v_mov_b32_e32 v22, v107
	v_mov_b32_e32 v29, v102
	v_mov_b32_e32 v31, v104
	v_mov_b32_e32 v21, v106
	v_mov_b32_e32 v28, v101
	v_mov_b32_e32 v23, v108
	v_mov_b32_e32 v30, v103
	s_nop 1
	v_add_f32_dpp v28, v28, v28 row_shr:1 row_mask:0xf bank_mask:0xf bound_ctrl:1
	v_add_f32_dpp v29, v29, v29 row_shr:1 row_mask:0xf bank_mask:0xf bound_ctrl:1
	v_add_f32_dpp v30, v30, v30 row_shr:1 row_mask:0xf bank_mask:0xf bound_ctrl:1
	v_add_f32_dpp v31, v31, v31 row_shr:1 row_mask:0xf bank_mask:0xf bound_ctrl:1
	v_add_f32_dpp v20, v20, v20 row_shr:1 row_mask:0xf bank_mask:0xf bound_ctrl:1
	v_add_f32_dpp v21, v21, v21 row_shr:1 row_mask:0xf bank_mask:0xf bound_ctrl:1
	v_add_f32_dpp v22, v22, v22 row_shr:1 row_mask:0xf bank_mask:0xf bound_ctrl:1
	v_add_f32_dpp v23, v23, v23 row_shr:1 row_mask:0xf bank_mask:0xf bound_ctrl:1
	v_and_b32_e32 v110, 0xffff0000, v4
	v_lshlrev_b32_e32 v111, 16, v5
	v_and_b32_e32 v112, 0xffff0000, v5
	v_lshlrev_b32_e32 v113, 16, v6
	v_and_b32_e32 v114, 0xffff0000, v6
	v_lshlrev_b32_e32 v115, 16, v7
	v_and_b32_e32 v116, 0xffff0000, v7
	s_nop 1
	v_add_f32_dpp v28, v28, v28 row_shr:2 row_mask:0xf bank_mask:0xf bound_ctrl:1
	v_add_f32_dpp v29, v29, v29 row_shr:2 row_mask:0xf bank_mask:0xf bound_ctrl:1
	v_add_f32_dpp v30, v30, v30 row_shr:2 row_mask:0xf bank_mask:0xf bound_ctrl:1
	v_add_f32_dpp v31, v31, v31 row_shr:2 row_mask:0xf bank_mask:0xf bound_ctrl:1
	v_add_f32_dpp v20, v20, v20 row_shr:2 row_mask:0xf bank_mask:0xf bound_ctrl:1
	v_add_f32_dpp v21, v21, v21 row_shr:2 row_mask:0xf bank_mask:0xf bound_ctrl:1
	v_add_f32_dpp v22, v22, v22 row_shr:2 row_mask:0xf bank_mask:0xf bound_ctrl:1
	v_add_f32_dpp v23, v23, v23 row_shr:2 row_mask:0xf bank_mask:0xf bound_ctrl:1
	s_waitcnt vmcnt(0)
; __device__ __forceinline__ float bf_lo(unsigned w) { return __uint_as_float(w << 16); }
; __device__ __forceinline__ float bf_hi(unsigned w) { return __uint_as_float(w & 0xffff0000u); }
; template <int DIR> __device__ __forceinline__ void scan16x8(float* v) {
;     if (DIR == 0) { SCAN_STEP("row_shr:", 1); SCAN_STEP("row_shr:", 2); SCAN_STEP("row_shr:", 4); SCAN_STEP("row_shr:", 8); }
;     else          { SCAN_STEP("row_shl:", 1); SCAN_STEP("row_shl:", 2); SCAN_STEP("row_shl:", 4); SCAN_STEP("row_shl:", 8); }
; }
; __device__ __forceinline__ void load32(const bf16_t* p, float (&v)[32]) {
; #pragma unroll
;     for (int ks = 0; ks < 4; ++ks) { const u32x4 w = *(const u32x4*)(p + 32 * ks);
;         v[8 * ks + 0] = bf_lo(w.x); v[8 * ks + 1] = bf_hi(w.x); v[8 * ks + 2] = bf_lo(w.y); v[8 * ks + 3] = bf_hi(w.y); v[8 * ks + 4] = bf_lo(w.z); v[8 * ks + 5] = bf_hi(w.z); v[8 * ks + 6] = bf_lo(w.w); v[8 * ks + 7] = bf_hi(w.w); }
	v_lshlrev_b32_e32 v78, 16, v12
	v_and_b32_e32 v79, 0xffff0000, v12
	v_lshlrev_b32_e32 v76, 16, v13
	v_and_b32_e32 v77, 0xffff0000, v13
	v_lshlrev_b32_e32 v74, 16, v14
	v_and_b32_e32 v75, 0xffff0000, v14
	v_lshlrev_b32_e32 v72, 16, v15
	v_and_b32_e32 v73, 0xffff0000, v15
	v_mov_b32_e32 v12, v113
	v_mov_b32_e32 v14, v115
	v_mov_b32_e32 v25, v110
	v_mov_b32_e32 v27, v112
	v_mov_b32_e32 v13, v114
	v_mov_b32_e32 v24, v109
	v_mov_b32_e32 v15, v116
	v_mov_b32_e32 v26, v111
	s_nop 1
	v_add_f32_dpp v28, v28, v28 row_shr:4 row_mask:0xf bank_mask:0xf bound_ctrl:1
	v_add_f32_dpp v29, v29, v29 row_shr:4 row_mask:0xf bank_mask:0xf bound_ctrl:1
	v_add_f32_dpp v30, v30, v30 row_shr:4 row_mask:0xf bank_mask:0xf bound_ctrl:1
	v_add_f32_dpp v31, v31, v31 row_shr:4 row_mask:0xf bank_mask:0xf bound_ctrl:1
	v_add_f32_dpp v20, v20, v20 row_shr:4 row_mask:0xf bank_mask:0xf bound_ctrl:1
	v_add_f32_dpp v21, v21, v21 row_shr:4 row_mask:0xf bank_mask:0xf bound_ctrl:1
	v_add_f32_dpp v22, v22, v22 row_shr:4 row_mask:0xf bank_mask:0xf bound_ctrl:1
	v_add_f32_dpp v23, v23, v23 row_shr:4 row_mask:0xf bank_mask:0xf bound_ctrl:1
	v_lshlrev_b32_e32 v117, 16, v8
	s_nop 1
	v_add_f32_dpp v28, v28, v28 row_shr:8 row_mask:0xf bank_mask:0xf bound_ctrl:1
	v_add_f32_dpp v29, v29, v29 row_shr:8 row_mask:0xf bank_mask:0xf bound_ctrl:1
	v_add_f32_dpp v30, v30, v30 row_shr:8 row_mask:0xf bank_mask:0xf bound_ctrl:1
	v_add_f32_dpp v31, v31, v31 row_shr:8 row_mask:0xf bank_mask:0xf bound_ctrl:1
	v_add_f32_dpp v20, v20, v20 row_shr:8 row_mask:0xf bank_mask:0xf bound_ctrl:1
	v_add_f32_dpp v21, v21, v21 row_shr:8 row_mask:0xf bank_mask:0xf bound_ctrl:1
	v_add_f32_dpp v22, v22, v22 row_shr:8 row_mask:0xf bank_mask:0xf bound_ctrl:1
	v_add_f32_dpp v23, v23, v23 row_shr:8 row_mask:0xf bank_mask:0xf bound_ctrl:1
	s_nop 1
	v_add_f32_dpp v24, v24, v24 row_shr:1 row_mask:0xf bank_mask:0xf bound_ctrl:1
	v_add_f32_dpp v25, v25, v25 row_shr:1 row_mask:0xf bank_mask:0xf bound_ctrl:1
	v_add_f32_dpp v26, v26, v26 row_shr:1 row_mask:0xf bank_mask:0xf bound_ctrl:1
	v_add_f32_dpp v27, v27, v27 row_shr:1 row_mask:0xf bank_mask:0xf bound_ctrl:1
	v_add_f32_dpp v12, v12, v12 row_shr:1 row_mask:0xf bank_mask:0xf bound_ctrl:1
	v_add_f32_dpp v13, v13, v13 row_shr:1 row_mask:0xf bank_mask:0xf bound_ctrl:1
	v_add_f32_dpp v14, v14, v14 row_shr:1 row_mask:0xf bank_mask:0xf bound_ctrl:1
	v_add_f32_dpp v15, v15, v15 row_shr:1 row_mask:0xf bank_mask:0xf bound_ctrl:1
	v_and_b32_e32 v118, 0xffff0000, v8
	v_lshlrev_b32_e32 v119, 16, v9
	v_and_b32_e32 v120, 0xffff0000, v9
	v_lshlrev_b32_e32 v121, 16, v10
	v_and_b32_e32 v122, 0xffff0000, v10
	v_lshlrev_b32_e32 v123, 16, v11
	v_and_b32_e32 v124, 0xffff0000, v11
	s_nop 1
	v_add_f32_dpp v24, v24, v24 row_shr:2 row_mask:0xf bank_mask:0xf bound_ctrl:1
	v_add_f32_dpp v25, v25, v25 row_shr:2 row_mask:0xf bank_mask:0xf bound_ctrl:1
	v_add_f32_dpp v26, v26, v26 row_shr:2 row_mask:0xf bank_mask:0xf bound_ctrl:1
	v_add_f32_dpp v27, v27, v27 row_shr:2 row_mask:0xf bank_mask:0xf bound_ctrl:1
	v_add_f32_dpp v12, v12, v12 row_shr:2 row_mask:0xf bank_mask:0xf bound_ctrl:1
	v_add_f32_dpp v13, v13, v13 row_shr:2 row_mask:0xf bank_mask:0xf bound_ctrl:1
	v_add_f32_dpp v14, v14, v14 row_shr:2 row_mask:0xf bank_mask:0xf bound_ctrl:1
	v_add_f32_dpp v15, v15, v15 row_shr:2 row_mask:0xf bank_mask:0xf bound_ctrl:1
	v_mov_b32_e32 v4, v121
	v_mov_b32_e32 v6, v123
	v_mov_b32_e32 v17, v118
	v_mov_b32_e32 v19, v120
	v_mov_b32_e32 v5, v122
	v_mov_b32_e32 v16, v117
	v_mov_b32_e32 v7, v124
	v_mov_b32_e32 v18, v119
	s_nop 1
	v_add_f32_dpp v24, v24, v24 row_shr:4 row_mask:0xf bank_mask:0xf bound_ctrl:1
	v_add_f32_dpp v25, v25, v25 row_shr:4 row_mask:0xf bank_mask:0xf bound_ctrl:1
	v_add_f32_dpp v26, v26, v26 row_shr:4 row_mask:0xf bank_mask:0xf bound_ctrl:1
	v_add_f32_dpp v27, v27, v27 row_shr:4 row_mask:0xf bank_mask:0xf bound_ctrl:1
	v_add_f32_dpp v12, v12, v12 row_shr:4 row_mask:0xf bank_mask:0xf bound_ctrl:1
	v_add_f32_dpp v13, v13, v13 row_shr:4 row_mask:0xf bank_mask:0xf bound_ctrl:1
	v_add_f32_dpp v14, v14, v14 row_shr:4 row_mask:0xf bank_mask:0xf bound_ctrl:1
	v_add_f32_dpp v15, v15, v15 row_shr:4 row_mask:0xf bank_mask:0xf bound_ctrl:1
	v_mov_b32_e32 v0, v74
	s_nop 1
	v_add_f32_dpp v24, v24, v24 row_shr:8 row_mask:0xf bank_mask:0xf bound_ctrl:1
	v_add_f32_dpp v25, v25, v25 row_shr:8 row_mask:0xf bank_mask:0xf bound_ctrl:1
	v_add_f32_dpp v26, v26, v26 row_shr:8 row_mask:0xf bank_mask:0xf bound_ctrl:1
	v_add_f32_dpp v27, v27, v27 row_shr:8 row_mask:0xf bank_mask:0xf bound_ctrl:1
	v_add_f32_dpp v12, v12, v12 row_shr:8 row_mask:0xf bank_mask:0xf bound_ctrl:1
	v_add_f32_dpp v13, v13, v13 row_shr:8 row_mask:0xf bank_mask:0xf bound_ctrl:1
	v_add_f32_dpp v14, v14, v14 row_shr:8 row_mask:0xf bank_mask:0xf bound_ctrl:1
	v_add_f32_dpp v15, v15, v15 row_shr:8 row_mask:0xf bank_mask:0xf bound_ctrl:1
	s_nop 1
	v_add_f32_dpp v16, v16, v16 row_shr:1 row_mask:0xf bank_mask:0xf bound_ctrl:1
	v_add_f32_dpp v17, v17, v17 row_shr:1 row_mask:0xf bank_mask:0xf bound_ctrl:1
	v_add_f32_dpp v18, v18, v18 row_shr:1 row_mask:0xf bank_mask:0xf bound_ctrl:1
	v_add_f32_dpp v19, v19, v19 row_shr:1 row_mask:0xf bank_mask:0xf bound_ctrl:1
	v_add_f32_dpp v4, v4, v4 row_shr:1 row_mask:0xf bank_mask:0xf bound_ctrl:1
; template <int DIR> __device__ __forceinline__ void h1_dir(unsigned char* lds, const bf16_t* zrow, int h, bf16_t* slot, float* decp) {
;     ...
;     load32(zrow + (size_t)(1 + DIR) * ZSEG + 8 * kq, bl);
; #pragma unroll
;     for (int i = 0; i < 32; ++i) kk[i] = 1.0f - __builtin_amdgcn_exp2f(bl[i]);
;         scan16x8<DIR>(bl); scan16x8<DIR>(bl + 8); scan16x8<DIR>(bl + 16); scan16x8<DIR>(bl + 24);
;     if (r == (DIR ? 0 : 15)) {
; #pragma unroll
;         for (int ks = 0; ks < 4; ++ks) { *(f32x4*)(TOT + wid * 128 + 32 * ks + 8 * kq) = (f32x4){bl[8 * ks], bl[8 * ks + 1], bl[8 * ks + 2], bl[8 * ks + 3]}; *(f32x4*)(TOT + wid * 128 + 32 * ks + 8 * kq + 4) = (f32x4){bl[8 * ks + 4], bl[8 * ks + 5], bl[8 * ks + 6], bl[8 * ks + 7]}; }
;     }
	v_add_f32_dpp v5, v5, v5 row_shr:1 row_mask:0xf bank_mask:0xf bound_ctrl:1
	v_add_f32_dpp v6, v6, v6 row_shr:1 row_mask:0xf bank_mask:0xf bound_ctrl:1
	v_add_f32_dpp v7, v7, v7 row_shr:1 row_mask:0xf bank_mask:0xf bound_ctrl:1
	v_mov_b32_e32 v2, v72
	s_nop 1
	v_add_f32_dpp v16, v16, v16 row_shr:2 row_mask:0xf bank_mask:0xf bound_ctrl:1
	v_add_f32_dpp v17, v17, v17 row_shr:2 row_mask:0xf bank_mask:0xf bound_ctrl:1
	v_add_f32_dpp v18, v18, v18 row_shr:2 row_mask:0xf bank_mask:0xf bound_ctrl:1
	v_add_f32_dpp v19, v19, v19 row_shr:2 row_mask:0xf bank_mask:0xf bound_ctrl:1
	v_add_f32_dpp v4, v4, v4 row_shr:2 row_mask:0xf bank_mask:0xf bound_ctrl:1
	v_add_f32_dpp v5, v5, v5 row_shr:2 row_mask:0xf bank_mask:0xf bound_ctrl:1
	v_add_f32_dpp v6, v6, v6 row_shr:2 row_mask:0xf bank_mask:0xf bound_ctrl:1
	v_add_f32_dpp v7, v7, v7 row_shr:2 row_mask:0xf bank_mask:0xf bound_ctrl:1
	v_mov_b32_e32 v9, v79
	v_mov_b32_e32 v11, v77
	v_mov_b32_e32 v1, v75
	v_mov_b32_e32 v8, v78
	v_mov_b32_e32 v3, v73
	v_mov_b32_e32 v10, v76
	s_nop 1
	v_add_f32_dpp v16, v16, v16 row_shr:4 row_mask:0xf bank_mask:0xf bound_ctrl:1
	v_add_f32_dpp v17, v17, v17 row_shr:4 row_mask:0xf bank_mask:0xf bound_ctrl:1
	v_add_f32_dpp v18, v18, v18 row_shr:4 row_mask:0xf bank_mask:0xf bound_ctrl:1
	v_add_f32_dpp v19, v19, v19 row_shr:4 row_mask:0xf bank_mask:0xf bound_ctrl:1
	v_add_f32_dpp v4, v4, v4 row_shr:4 row_mask:0xf bank_mask:0xf bound_ctrl:1
	v_add_f32_dpp v5, v5, v5 row_shr:4 row_mask:0xf bank_mask:0xf bound_ctrl:1
	v_add_f32_dpp v6, v6, v6 row_shr:4 row_mask:0xf bank_mask:0xf bound_ctrl:1
	v_add_f32_dpp v7, v7, v7 row_shr:4 row_mask:0xf bank_mask:0xf bound_ctrl:1
	s_nop 0
	s_nop 1
	v_add_f32_dpp v16, v16, v16 row_shr:8 row_mask:0xf bank_mask:0xf bound_ctrl:1
	v_add_f32_dpp v17, v17, v17 row_shr:8 row_mask:0xf bank_mask:0xf bound_ctrl:1
	v_add_f32_dpp v18, v18, v18 row_shr:8 row_mask:0xf bank_mask:0xf bound_ctrl:1
	v_add_f32_dpp v19, v19, v19 row_shr:8 row_mask:0xf bank_mask:0xf bound_ctrl:1
	v_add_f32_dpp v4, v4, v4 row_shr:8 row_mask:0xf bank_mask:0xf bound_ctrl:1
	v_add_f32_dpp v5, v5, v5 row_shr:8 row_mask:0xf bank_mask:0xf bound_ctrl:1
	v_add_f32_dpp v6, v6, v6 row_shr:8 row_mask:0xf bank_mask:0xf bound_ctrl:1
	v_add_f32_dpp v7, v7, v7 row_shr:8 row_mask:0xf bank_mask:0xf bound_ctrl:1
	s_nop 1
	v_add_f32_dpp v8, v8, v8 row_shr:1 row_mask:0xf bank_mask:0xf bound_ctrl:1
	v_add_f32_dpp v9, v9, v9 row_shr:1 row_mask:0xf bank_mask:0xf bound_ctrl:1
	v_add_f32_dpp v10, v10, v10 row_shr:1 row_mask:0xf bank_mask:0xf bound_ctrl:1
	v_add_f32_dpp v11, v11, v11 row_shr:1 row_mask:0xf bank_mask:0xf bound_ctrl:1
	v_add_f32_dpp v0, v0, v0 row_shr:1 row_mask:0xf bank_mask:0xf bound_ctrl:1
	v_add_f32_dpp v1, v1, v1 row_shr:1 row_mask:0xf bank_mask:0xf bound_ctrl:1
	v_add_f32_dpp v2, v2, v2 row_shr:1 row_mask:0xf bank_mask:0xf bound_ctrl:1
	v_add_f32_dpp v3, v3, v3 row_shr:1 row_mask:0xf bank_mask:0xf bound_ctrl:1
	s_nop 0
	s_nop 1
	v_add_f32_dpp v8, v8, v8 row_shr:2 row_mask:0xf bank_mask:0xf bound_ctrl:1
	v_add_f32_dpp v9, v9, v9 row_shr:2 row_mask:0xf bank_mask:0xf bound_ctrl:1
	v_add_f32_dpp v10, v10, v10 row_shr:2 row_mask:0xf bank_mask:0xf bound_ctrl:1
	v_add_f32_dpp v11, v11, v11 row_shr:2 row_mask:0xf bank_mask:0xf bound_ctrl:1
	v_add_f32_dpp v0, v0, v0 row_shr:2 row_mask:0xf bank_mask:0xf bound_ctrl:1
	v_add_f32_dpp v1, v1, v1 row_shr:2 row_mask:0xf bank_mask:0xf bound_ctrl:1
	v_add_f32_dpp v2, v2, v2 row_shr:2 row_mask:0xf bank_mask:0xf bound_ctrl:1
	v_add_f32_dpp v3, v3, v3 row_shr:2 row_mask:0xf bank_mask:0xf bound_ctrl:1
	s_nop 0
	s_nop 1
	v_add_f32_dpp v8, v8, v8 row_shr:4 row_mask:0xf bank_mask:0xf bound_ctrl:1
	v_add_f32_dpp v9, v9, v9 row_shr:4 row_mask:0xf bank_mask:0xf bound_ctrl:1
	v_add_f32_dpp v10, v10, v10 row_shr:4 row_mask:0xf bank_mask:0xf bound_ctrl:1
	v_add_f32_dpp v11, v11, v11 row_shr:4 row_mask:0xf bank_mask:0xf bound_ctrl:1
	v_add_f32_dpp v0, v0, v0 row_shr:4 row_mask:0xf bank_mask:0xf bound_ctrl:1
	v_add_f32_dpp v1, v1, v1 row_shr:4 row_mask:0xf bank_mask:0xf bound_ctrl:1
	v_add_f32_dpp v2, v2, v2 row_shr:4 row_mask:0xf bank_mask:0xf bound_ctrl:1
	v_add_f32_dpp v3, v3, v3 row_shr:4 row_mask:0xf bank_mask:0xf bound_ctrl:1
	s_nop 0
	s_nop 1
	v_add_f32_dpp v8, v8, v8 row_shr:8 row_mask:0xf bank_mask:0xf bound_ctrl:1
	v_add_f32_dpp v9, v9, v9 row_shr:8 row_mask:0xf bank_mask:0xf bound_ctrl:1
	v_add_f32_dpp v10, v10, v10 row_shr:8 row_mask:0xf bank_mask:0xf bound_ctrl:1
	v_add_f32_dpp v11, v11, v11 row_shr:8 row_mask:0xf bank_mask:0xf bound_ctrl:1
	v_add_f32_dpp v0, v0, v0 row_shr:8 row_mask:0xf bank_mask:0xf bound_ctrl:1
	v_add_f32_dpp v1, v1, v1 row_shr:8 row_mask:0xf bank_mask:0xf bound_ctrl:1
	v_add_f32_dpp v2, v2, v2 row_shr:8 row_mask:0xf bank_mask:0xf bound_ctrl:1
	v_add_f32_dpp v3, v3, v3 row_shr:8 row_mask:0xf bank_mask:0xf bound_ctrl:1
	s_and_saveexec_b64 s[16:17], vcc
	s_cbranch_execz .LBB0_2455
	s_lshl_b32 s15, s37, 9
	s_add_i32 s15, s15, 0
	v_lshl_add_u32 v34, v100, 2, s15
	ds_write_b128 v34, v[28:31]
	ds_write_b128 v34, v[20:23] offset:16
	ds_write_b128 v34, v[24:27] offset:128
	ds_write_b128 v34, v[12:15] offset:144
	ds_write_b128 v34, v[16:19] offset:256
	ds_write_b128 v34, v[4:7] offset:272
	ds_write_b128 v34, v[8:11] offset:384
	ds_write_b128 v34, v[0:3] offset:400

; __device__ __forceinline__ unsigned cvt_pk_c(float lo, float hi) { const f32x2_cv v = {lo, hi}; const bf16x2_cv b = __builtin_convertvector(v, bf16x2_cv); return __builtin_bit_cast(unsigned, b); }
; template <int DIR> __device__ __forceinline__ void h1_dir(unsigned char* lds, const bf16_t* zrow, int h, bf16_t* slot, float* decp) {
;     ...
; #pragma unroll
;         for (int ks = 0; ks < 4; ++ks)
; #pragma unroll
;             for (int e = 0; e < 8; e += 2) { const unsigned w = cvt_pk_c(kk[8 * ks + e] * __builtin_amdgcn_exp2f(aft[8 * ks + e] - bl[8 * ks + e]), kk[8 * ks + e + 1] * __builtin_amdgcn_exp2f(aft[8 * ks + e + 1] - bl[8 * ks + e + 1]));
;                 KS[(32 * ks + 8 * kq + e) * HP + 16 * wid + r] = (bf16_t)(w & 0xffffu); KS[(32 * ks + 8 * kq + e + 1) * HP + 16 * wid + r] = (bf16_t)(w >> 16); }
.LBB0_2475:
	s_or_b64 exec, exec, s[18:19]
	v_exp_f32_e32 v140, v123
	v_exp_f32_e32 v123, v122
	v_exp_f32_e32 v122, v121
	v_exp_f32_e32 v121, v120
	v_exp_f32_e32 v120, v119
	v_exp_f32_e32 v119, v118
	v_exp_f32_e32 v118, v117
	v_exp_f32_e32 v117, v116
	v_exp_f32_e32 v116, v115
	v_exp_f32_e32 v115, v114
	v_exp_f32_e32 v114, v113
	v_exp_f32_e32 v113, v112
	v_exp_f32_e32 v112, v111
	v_exp_f32_e32 v111, v110
	v_exp_f32_e32 v110, v109
	v_exp_f32_e32 v109, v108
	v_exp_f32_e32 v108, v107
	v_exp_f32_e32 v107, v106
	v_exp_f32_e32 v106, v105
	v_exp_f32_e32 v105, v104
	v_exp_f32_e32 v104, v103
	v_exp_f32_e32 v103, v102
	v_exp_f32_e32 v102, v101
	v_sub_f32_e32 v28, v70, v28
	v_sub_f32_e32 v29, v71, v29
	v_exp_f32_e32 v28, v28
	v_exp_f32_e32 v29, v29
	s_lshl_b64 s[18:19], s[14:15], 15
	s_add_u32 s18, s22, s18
	v_pk_add_f32 v[70:71], v[102:103], 1.0 op_sel_hi:[1,0] neg_lo:[1,0] neg_hi:[1,0]
	s_addc_u32 s19, s23, s19
	s_lshl_b32 s3, s37, 4
	s_lshl_b32 s37, s37, 5
	v_pk_mul_f32 v[28:29], v[70:71], v[28:29]
	v_exp_f32_e32 v141, v124
	s_add_i32 s37, s37, 0
	v_lshlrev_b32_e32 v124, 1, v99
	v_cvt_pk_bf16_f32 v70, v28, v29
	v_mul_u32_u24_e32 v28, 0x440, v98
	v_add_u32_e32 v101, s37, v124
	v_lshlrev_b32_e32 v71, 1, v28
	v_add_u32_e32 v28, v101, v71
	ds_write_b16 v28, v70 offset:8192
	v_sub_f32_e32 v28, v68, v30
	v_sub_f32_e32 v29, v69, v31
	v_exp_f32_e32 v28, v28
	v_exp_f32_e32 v29, v29
	v_add3_u32 v30, s37, v71, v124
	ds_write_b16_d16_hi v30, v70 offset:8464
	v_pk_add_f32 v[30:31], v[104:105], 1.0 op_sel_hi:[1,0] neg_lo:[1,0] neg_hi:[1,0]
	v_sub_f32_e32 v20, v66, v20
	v_pk_mul_f32 v[28:29], v[30:31], v[28:29]
	v_sub_f32_e32 v21, v67, v21
	v_cvt_pk_bf16_f32 v28, v28, v29
	v_mul_i32_i24_e32 v29, 0x88, v138
	v_exp_f32_e32 v20, v20
	v_exp_f32_e32 v21, v21
	v_lshlrev_b32_e32 v29, 1, v29
	v_add_u32_e32 v30, v101, v29
	v_add3_u32 v29, s37, v29, v124
	ds_write_b16 v30, v28 offset:8192
	ds_write_b16_d16_hi v29, v28 offset:8464
	v_pk_add_f32 v[28:29], v[106:107], 1.0 op_sel_hi:[1,0] neg_lo:[1,0] neg_hi:[1,0]
	v_sub_f32_e32 v12, v58, v12
	v_pk_mul_f32 v[20:21], v[28:29], v[20:21]
	v_sub_f32_e32 v13, v59, v13
	v_cvt_pk_bf16_f32 v28, v20, v21
	v_mul_i32_i24_e32 v20, 0x88, v137
	v_lshlrev_b32_e32 v29, 1, v20
	v_add_u32_e32 v20, v101, v29
	ds_write_b16 v20, v28 offset:8192
	v_sub_f32_e32 v20, v64, v22
	v_sub_f32_e32 v21, v65, v23
	v_exp_f32_e32 v20, v20
	v_exp_f32_e32 v21, v21
	v_add3_u32 v22, s37, v29, v124
	ds_write_b16_d16_hi v22, v28 offset:8464
	v_pk_add_f32 v[22:23], v[108:109], 1.0 op_sel_hi:[1,0] neg_lo:[1,0] neg_hi:[1,0]
	v_exp_f32_e32 v12, v12
	v_pk_mul_f32 v[20:21], v[22:23], v[20:21]
	v_exp_f32_e32 v13, v13
	v_cvt_pk_bf16_f32 v22, v20, v21
	v_mul_i32_i24_e32 v20, 0x88, v136
	v_lshlrev_b32_e32 v23, 1, v20
	v_add_u32_e32 v20, v101, v23
	ds_write_b16 v20, v22 offset:8192
	v_sub_f32_e32 v20, v62, v24
	v_sub_f32_e32 v21, v63, v25
	v_exp_f32_e32 v20, v20
	v_exp_f32_e32 v21, v21
	v_add3_u32 v23, s37, v23, v124
	ds_write_b16_d16_hi v23, v22 offset:8464
	v_pk_add_f32 v[22:23], v[110:111], 1.0 op_sel_hi:[1,0] neg_lo:[1,0] neg_hi:[1,0]
	v_sub_f32_e32 v4, v50, v4
	v_pk_mul_f32 v[20:21], v[22:23], v[20:21]
	v_sub_f32_e32 v5, v51, v5
	v_cvt_pk_bf16_f32 v22, v20, v21
	v_mul_i32_i24_e32 v20, 0x88, v135
	v_lshlrev_b32_e32 v23, 1, v20
	v_add_u32_e32 v20, v101, v23
	ds_write_b16 v20, v22 offset:8192
	v_sub_f32_e32 v20, v60, v26
	v_sub_f32_e32 v21, v61, v27
	v_exp_f32_e32 v20, v20
	v_exp_f32_e32 v21, v21
	v_add3_u32 v23, s37, v23, v124
	ds_write_b16_d16_hi v23, v22 offset:8464
	v_pk_add_f32 v[22:23], v[112:113], 1.0 op_sel_hi:[1,0] neg_lo:[1,0] neg_hi:[1,0]
	v_exp_f32_e32 v4, v4
	v_pk_mul_f32 v[20:21], v[22:23], v[20:21]
	v_exp_f32_e32 v5, v5
	v_cvt_pk_bf16_f32 v20, v20, v21
	v_mul_i32_i24_e32 v21, 0x88, v134
	v_lshlrev_b32_e32 v21, 1, v21
	v_add_u32_e32 v22, v101, v21
	v_add3_u32 v21, s37, v21, v124
	ds_write_b16 v22, v20 offset:8192
	ds_write_b16_d16_hi v21, v20 offset:8464
	v_pk_add_f32 v[20:21], v[114:115], 1.0 op_sel_hi:[1,0] neg_lo:[1,0] neg_hi:[1,0]
	v_exp_f32_e32 v79, v79
	v_pk_mul_f32 v[12:13], v[20:21], v[12:13]
	v_exp_f32_e32 v78, v78
	v_cvt_pk_bf16_f32 v20, v12, v13
	v_mul_i32_i24_e32 v12, 0x88, v133
	v_lshlrev_b32_e32 v21, 1, v12
	v_add_u32_e32 v12, v101, v21
	ds_write_b16 v12, v20 offset:8192
	v_sub_f32_e32 v12, v56, v14
	v_sub_f32_e32 v13, v57, v15
	v_exp_f32_e32 v12, v12
	v_exp_f32_e32 v13, v13
	v_add3_u32 v14, s37, v21, v124
	ds_write_b16_d16_hi v14, v20 offset:8464
	v_pk_add_f32 v[14:15], v[116:117], 1.0 op_sel_hi:[1,0] neg_lo:[1,0] neg_hi:[1,0]
	v_exp_f32_e32 v77, v77
	v_pk_mul_f32 v[12:13], v[14:15], v[12:13]
	v_exp_f32_e32 v76, v76
	v_cvt_pk_bf16_f32 v14, v12, v13
	v_mul_i32_i24_e32 v12, 0x88, v132
	v_lshlrev_b32_e32 v15, 1, v12
	v_add_u32_e32 v12, v101, v15
	ds_write_b16 v12, v14 offset:8192
	v_sub_f32_e32 v12, v54, v16
	v_sub_f32_e32 v13, v55, v17
	v_exp_f32_e32 v12, v12
	v_exp_f32_e32 v13, v13
	v_add3_u32 v15, s37, v15, v124
	ds_write_b16_d16_hi v15, v14 offset:8464
	v_pk_add_f32 v[14:15], v[118:119], 1.0 op_sel_hi:[1,0] neg_lo:[1,0] neg_hi:[1,0]
	v_exp_f32_e32 v75, v75
	v_pk_mul_f32 v[12:13], v[14:15], v[12:13]
	v_exp_f32_e32 v74, v74
	v_cvt_pk_bf16_f32 v14, v12, v13
	v_mul_i32_i24_e32 v12, 0x88, v131
	v_lshlrev_b32_e32 v15, 1, v12
	v_add_u32_e32 v12, v101, v15
	ds_write_b16 v12, v14 offset:8192
	v_sub_f32_e32 v12, v52, v18
	v_sub_f32_e32 v13, v53, v19
	v_exp_f32_e32 v12, v12
	v_exp_f32_e32 v13, v13
	v_add3_u32 v15, s37, v15, v124
	ds_write_b16_d16_hi v15, v14 offset:8464
	v_pk_add_f32 v[14:15], v[120:121], 1.0 op_sel_hi:[1,0] neg_lo:[1,0] neg_hi:[1,0]
	v_sub_f32_e32 v0, v42, v0
	v_pk_mul_f32 v[12:13], v[14:15], v[12:13]
	v_sub_f32_e32 v1, v43, v1
; __device__ __forceinline__ unsigned cvt_pk_c(float lo, float hi) { const f32x2_cv v = {lo, hi}; const bf16x2_cv b = __builtin_convertvector(v, bf16x2_cv); return __builtin_bit_cast(unsigned, b); }
; template <int DIR> __device__ __forceinline__ void h1_dir(unsigned char* lds, const bf16_t* zrow, int h, bf16_t* slot, float* decp) {
;     ...
; #pragma unroll
;         for (int ks = 0; ks < 4; ++ks)
; #pragma unroll
;             for (int e = 0; e < 8; e += 2) { const unsigned w = cvt_pk_c(kk[8 * ks + e] * __builtin_amdgcn_exp2f(aft[8 * ks + e] - bl[8 * ks + e]), kk[8 * ks + e + 1] * __builtin_amdgcn_exp2f(aft[8 * ks + e + 1] - bl[8 * ks + e + 1]));
;                 KS[(32 * ks + 8 * kq + e) * HP + 16 * wid + r] = (bf16_t)(w & 0xffffu); KS[(32 * ks + 8 * kq + e + 1) * HP + 16 * wid + r] = (bf16_t)(w >> 16); }
;     }
;     __syncthreads();
;     f32x4 acc[8];
; #pragma unroll
;     for (int nt = 0; nt < 8; ++nt) acc[nt] = (f32x4){0.f, 0.f, 0.f, 0.f};
; #pragma unroll
;     for (int ks = 0; ks < 4; ++ks) {
;         const bf16x8 a = *(const bf16x8*)(VT + (16 * wid + r) * HP + 32 * ks + 8 * kq);
; #pragma unroll
;         for (int nt = 0; nt < 8; ++nt) { const bf16x8 bb = *(const bf16x8*)(KS + (16 * nt + r) * HP + 32 * ks + 8 * kq); acc[nt] = __builtin_amdgcn_mfma_f32_16x16x32_bf16(a, bb, acc[nt], 0, 0, 0); }
;     }
	v_cvt_pk_bf16_f32 v12, v12, v13
	v_mul_i32_i24_e32 v13, 0x88, v130
	v_lshlrev_b32_e32 v13, 1, v13
	v_add_u32_e32 v14, v101, v13
	v_add3_u32 v13, s37, v13, v124
	ds_write_b16 v14, v12 offset:8192
	ds_write_b16_d16_hi v13, v12 offset:8464
	v_pk_add_f32 v[12:13], v[122:123], 1.0 op_sel_hi:[1,0] neg_lo:[1,0] neg_hi:[1,0]
	v_exp_f32_e32 v0, v0
	v_pk_mul_f32 v[4:5], v[12:13], v[4:5]
	v_exp_f32_e32 v1, v1
	v_cvt_pk_bf16_f32 v12, v4, v5
	v_mul_i32_i24_e32 v4, 0x88, v129
	v_lshlrev_b32_e32 v13, 1, v4
	v_add_u32_e32 v4, v101, v13
	ds_write_b16 v4, v12 offset:8192
	v_sub_f32_e32 v4, v48, v6
	v_sub_f32_e32 v5, v49, v7
	v_exp_f32_e32 v4, v4
	v_exp_f32_e32 v5, v5
	v_add3_u32 v6, s37, v13, v124
	ds_write_b16_d16_hi v6, v12 offset:8464
	v_pk_add_f32 v[6:7], v[140:141], 1.0 op_sel_hi:[1,0] neg_lo:[1,0] neg_hi:[1,0]
	v_exp_f32_e32 v73, v73
	v_pk_mul_f32 v[4:5], v[6:7], v[4:5]
	v_exp_f32_e32 v72, v72
	v_cvt_pk_bf16_f32 v6, v4, v5
	v_mul_i32_i24_e32 v4, 0x88, v128
	v_lshlrev_b32_e32 v7, 1, v4
	v_add_u32_e32 v4, v101, v7
	ds_write_b16 v4, v6 offset:8192
	v_sub_f32_e32 v4, v46, v8
	v_sub_f32_e32 v5, v47, v9
	v_exp_f32_e32 v4, v4
	v_exp_f32_e32 v5, v5
	v_add3_u32 v7, s37, v7, v124
	ds_write_b16_d16_hi v7, v6 offset:8464
	v_pk_add_f32 v[6:7], v[78:79], 1.0 op_sel_hi:[1,0] neg_lo:[1,0] neg_hi:[1,0]
	s_nop 0
	v_pk_mul_f32 v[4:5], v[6:7], v[4:5]
	s_nop 0
	v_cvt_pk_bf16_f32 v6, v4, v5
	v_mul_i32_i24_e32 v4, 0x88, v127
	v_lshlrev_b32_e32 v7, 1, v4
	v_add_u32_e32 v4, v101, v7
	ds_write_b16 v4, v6 offset:8192
	v_sub_f32_e32 v4, v44, v10
	v_sub_f32_e32 v5, v45, v11
	v_exp_f32_e32 v4, v4
	v_exp_f32_e32 v5, v5
	v_add3_u32 v7, s37, v7, v124
	ds_write_b16_d16_hi v7, v6 offset:8464
	v_pk_add_f32 v[6:7], v[76:77], 1.0 op_sel_hi:[1,0] neg_lo:[1,0] neg_hi:[1,0]
	s_nop 0
	v_pk_mul_f32 v[4:5], v[6:7], v[4:5]
	s_nop 0
	v_cvt_pk_bf16_f32 v4, v4, v5
	v_mul_i32_i24_e32 v5, 0x88, v126
	v_lshlrev_b32_e32 v5, 1, v5
	v_add_u32_e32 v6, v101, v5
	v_add3_u32 v5, s37, v5, v124
	ds_write_b16 v6, v4 offset:8192
	ds_write_b16_d16_hi v5, v4 offset:8464
	v_pk_add_f32 v[4:5], v[74:75], 1.0 op_sel_hi:[1,0] neg_lo:[1,0] neg_hi:[1,0]
	s_nop 0
	v_pk_mul_f32 v[0:1], v[4:5], v[0:1]
	s_nop 0
	v_cvt_pk_bf16_f32 v4, v0, v1
	v_mul_i32_i24_e32 v0, 0x88, v125
	v_lshlrev_b32_e32 v5, 1, v0
	v_add_u32_e32 v0, v101, v5
	ds_write_b16 v0, v4 offset:8192
	v_sub_f32_e32 v0, v40, v2
	v_sub_f32_e32 v1, v41, v3
	v_exp_f32_e32 v0, v0
	v_exp_f32_e32 v1, v1
	v_add3_u32 v2, s37, v5, v124
	ds_write_b16_d16_hi v2, v4 offset:8464
	v_pk_add_f32 v[2:3], v[72:73], 1.0 op_sel_hi:[1,0] neg_lo:[1,0] neg_hi:[1,0]
	v_lshlrev_b32_e32 v4, 1, v100
	v_pk_mul_f32 v[0:1], v[2:3], v[0:1]
	v_mul_u32_u24_e32 v5, 0x110, v99
	v_cvt_pk_bf16_f32 v0, v0, v1
	v_mul_i32_i24_e32 v1, 0x88, v34
	v_lshlrev_b32_e32 v1, 1, v1
	v_add_u32_e32 v2, v101, v1
	v_add3_u32 v1, s37, v1, v124
	ds_write_b16 v2, v0 offset:8192
	ds_write_b16_d16_hi v1, v0 offset:8464
	v_or_b32_e32 v0, s3, v99
	v_mul_lo_u32 v0, v0, s30
	v_add3_u32 v34, s35, v0, v4
	s_waitcnt lgkmcnt(0)
	s_barrier
	ds_read_b128 v[0:3], v34
	v_add3_u32 v99, 0, v4, v5
	ds_read_b128 v[4:7], v99 offset:8192
	ds_read_b128 v[8:11], v34 offset:64
	ds_read_b128 v[12:15], v99 offset:8256
	ds_read_b128 v[16:19], v99 offset:12544
	ds_read_b128 v[20:23], v99 offset:12608
	ds_read_b128 v[24:27], v99 offset:16896
	ds_read_b128 v[28:31], v99 offset:16960
	ds_read_b128 v[40:43], v99 offset:21248
	ds_read_b128 v[44:47], v99 offset:21312
	s_waitcnt lgkmcnt(8)
	v_mfma_f32_16x16x32_bf16 v[4:7], v[0:3], v[4:7], 0
	ds_read_b128 v[48:51], v99 offset:25600
	ds_read_b128 v[52:55], v99 offset:25664
	ds_read_b128 v[56:59], v99 offset:29952
	ds_read_b128 v[60:63], v99 offset:30016
	ds_read_b128 v[64:67], v99 offset:34304
	ds_read_b128 v[68:71], v99 offset:34368
	s_waitcnt lgkmcnt(11)
	v_mfma_f32_16x16x32_bf16 v[16:19], v[0:3], v[16:19], 0
	ds_read_b128 v[72:75], v99 offset:38656
	ds_read_b128 v[76:79], v99 offset:38720
	s_waitcnt lgkmcnt(9)
	v_mfma_f32_16x16x32_bf16 v[40:43], v[0:3], v[40:43], 0
	v_mfma_f32_16x16x32_bf16 v[4:7], v[8:11], v[12:15], v[4:7]
	v_mfma_f32_16x16x32_bf16 v[12:15], v[8:11], v[20:23], v[16:19]
	s_waitcnt lgkmcnt(8)
	v_mfma_f32_16x16x32_bf16 v[20:23], v[8:11], v[44:47], v[40:43]
	ds_read_b128 v[44:47], v34 offset:128
	v_mfma_f32_16x16x32_bf16 v[24:27], v[0:3], v[24:27], 0
	s_waitcnt lgkmcnt(8)
	v_mfma_f32_16x16x32_bf16 v[48:51], v[0:3], v[48:51], 0
	s_waitcnt lgkmcnt(6)
	v_mfma_f32_16x16x32_bf16 v[56:59], v[0:3], v[56:59], 0
	s_waitcnt lgkmcnt(4)
	v_mfma_f32_16x16x32_bf16 v[64:67], v[0:3], v[64:67], 0
	s_waitcnt lgkmcnt(2)
	v_mfma_f32_16x16x32_bf16 v[0:3], v[0:3], v[72:75], 0
	v_mfma_f32_16x16x32_bf16 v[16:19], v[8:11], v[28:31], v[24:27]
	v_mfma_f32_16x16x32_bf16 v[24:27], v[8:11], v[52:55], v[48:51]
	v_mfma_f32_16x16x32_bf16 v[28:31], v[8:11], v[60:63], v[56:59]
	v_mfma_f32_16x16x32_bf16 v[40:43], v[8:11], v[68:71], v[64:67]
	s_waitcnt lgkmcnt(1)
	v_mfma_f32_16x16x32_bf16 v[0:3], v[8:11], v[76:79], v[0:3]
	ds_read_b128 v[8:11], v99 offset:8320
	ds_read_b128 v[48:51], v34 offset:192
	ds_read_b128 v[52:55], v99 offset:8384
	v_lshl_or_b32 v34, v98, 2, s3
	s_waitcnt lgkmcnt(2)
	v_mfma_f32_16x16x32_bf16 v[4:7], v[44:47], v[8:11], v[4:7]
	ds_read_b128 v[8:11], v99 offset:12672
	ds_read_b128 v[56:59], v99 offset:12736
	s_waitcnt lgkmcnt(1)
	v_mfma_f32_16x16x32_bf16 v[8:11], v[44:47], v[8:11], v[12:15]
	s_nop 2
	ds_read_b128 v[12:15], v99 offset:17024
	ds_read_b128 v[60:63], v99 offset:17088
	s_waitcnt lgkmcnt(1)
	v_mfma_f32_16x16x32_bf16 v[12:15], v[44:47], v[12:15], v[16:19]
	s_nop 2
	ds_read_b128 v[16:19], v99 offset:21376
	ds_read_b128 v[64:67], v99 offset:21440
	s_waitcnt lgkmcnt(1)
; __device__ __forceinline__ unsigned cvt_pk_c(float lo, float hi) { const f32x2_cv v = {lo, hi}; const bf16x2_cv b = __builtin_convertvector(v, bf16x2_cv); return __builtin_bit_cast(unsigned, b); }
; #define WAVE_LDS_FENCE() do { asm volatile("s_waitcnt lgkmcnt(0)" ::: "memory"); __builtin_amdgcn_wave_barrier(); } while (0)
; template <int DIR> __device__ __forceinline__ void h1_dir(unsigned char* lds, const bf16_t* zrow, int h, bf16_t* slot, float* decp) {
;     ...
;     f32x4 acc[8];
; #pragma unroll
;     for (int nt = 0; nt < 8; ++nt) acc[nt] = (f32x4){0.f, 0.f, 0.f, 0.f};
; #pragma unroll
;     for (int ks = 0; ks < 4; ++ks) {
;         const bf16x8 a = *(const bf16x8*)(VT + (16 * wid + r) * HP + 32 * ks + 8 * kq);
; #pragma unroll
;         for (int nt = 0; nt < 8; ++nt) { const bf16x8 bb = *(const bf16x8*)(KS + (16 * nt + r) * HP + 32 * ks + 8 * kq); acc[nt] = __builtin_amdgcn_mfma_f32_16x16x32_bf16(a, bb, acc[nt], 0, 0, 0); }
;     }
; #pragma unroll
;     for (int nt = 0; nt < 8; ++nt)
; #pragma unroll
;         for (int i = 0; i < 4; i += 2) { const unsigned w = cvt_pk_c(acc[nt][i], acc[nt][i + 1]); STG[(16 * wid + 4 * kq + i) * HP + 16 * nt + r] = (bf16_t)(w & 0xffffu); STG[(16 * wid + 4 * kq + i + 1) * HP + 16 * nt + r] = (bf16_t)(w >> 16); }
;     WAVE_LDS_FENCE();
; #pragma unroll
;     for (int it = 0; it < 4; ++it) { const int p = lane + 64 * it, row = p >> 4, c16 = p & 15; *(u32x4*)(slot + (size_t)(16 * wid + row) * 128 + c16 * 8) = *(const u32x4*)(STG + (16 * wid + row) * HP + c16 * 8); }
;     asm volatile("s_waitcnt lgkmcnt(0)\n\ts_barrier" ::: "memory");
	v_mfma_f32_16x16x32_bf16 v[16:19], v[44:47], v[16:19], v[20:23]
	s_nop 2
	ds_read_b128 v[20:23], v99 offset:25728
	ds_read_b128 v[68:71], v99 offset:25792
	s_waitcnt lgkmcnt(1)
	v_mfma_f32_16x16x32_bf16 v[20:23], v[44:47], v[20:23], v[24:27]
	s_nop 2
	ds_read_b128 v[24:27], v99 offset:30080
	ds_read_b128 v[72:75], v99 offset:30144
	v_mfma_f32_16x16x32_bf16 v[4:7], v[48:51], v[52:55], v[4:7]
	s_waitcnt lgkmcnt(1)
	v_mfma_f32_16x16x32_bf16 v[24:27], v[44:47], v[24:27], v[28:31]
	s_nop 2
	ds_read_b128 v[28:31], v99 offset:34432
	ds_read_b128 v[76:79], v99 offset:34496
	s_nop 0
	v_cvt_pk_bf16_f32 v4, v4, v5
	v_mul_lo_u32 v5, v34, s30
	v_mfma_f32_16x16x32_bf16 v[8:11], v[48:51], v[56:59], v[8:11]
	v_add3_u32 v34, 0, v124, v5
	v_add3_u32 v5, 0, v5, v124
	v_mfma_f32_16x16x32_bf16 v[12:15], v[48:51], v[60:63], v[12:15]
	s_waitcnt lgkmcnt(1)
	v_mfma_f32_16x16x32_bf16 v[28:31], v[44:47], v[28:31], v[40:43]
	s_nop 2
	ds_read_b128 v[40:43], v99 offset:38784
	ds_read_b128 v[100:103], v99 offset:38848
	ds_write_b16 v34, v4 offset:43008
	ds_write_b16_d16_hi v5, v4 offset:43280
	v_cvt_pk_bf16_f32 v4, v6, v7
	v_mfma_f32_16x16x32_bf16 v[16:19], v[48:51], v[64:67], v[16:19]
	ds_write_b16 v34, v4 offset:43552
	ds_write_b16_d16_hi v5, v4 offset:43824
	v_cvt_pk_bf16_f32 v4, v8, v9
	ds_write_b16 v34, v4 offset:43040
	ds_write_b16_d16_hi v5, v4 offset:43312
	v_cvt_pk_bf16_f32 v4, v10, v11
	v_mfma_f32_16x16x32_bf16 v[20:23], v[48:51], v[68:71], v[20:23]
	ds_write_b16 v34, v4 offset:43584
	ds_write_b16_d16_hi v5, v4 offset:43856
	v_cvt_pk_bf16_f32 v4, v12, v13
	ds_write_b16 v34, v4 offset:43072
	ds_write_b16_d16_hi v5, v4 offset:43344
	s_waitcnt lgkmcnt(11)
	v_mfma_f32_16x16x32_bf16 v[0:3], v[44:47], v[40:43], v[0:3]
	v_cvt_pk_bf16_f32 v4, v14, v15
	ds_write_b16 v34, v4 offset:43616
	ds_write_b16_d16_hi v5, v4 offset:43888
	v_cvt_pk_bf16_f32 v4, v16, v17
	v_mfma_f32_16x16x32_bf16 v[24:27], v[48:51], v[72:75], v[24:27]
	ds_write_b16 v34, v4 offset:43104
	ds_write_b16_d16_hi v5, v4 offset:43376
	v_cvt_pk_bf16_f32 v4, v18, v19
	ds_write_b16 v34, v4 offset:43648
	ds_write_b16_d16_hi v5, v4 offset:43920
	v_mfma_f32_16x16x32_bf16 v[28:31], v[48:51], v[76:79], v[28:31]
	v_cvt_pk_bf16_f32 v4, v20, v21
	ds_write_b16 v34, v4 offset:43136
	ds_write_b16_d16_hi v5, v4 offset:43408
	v_cvt_pk_bf16_f32 v4, v22, v23
	s_waitcnt lgkmcnt(14)
	v_mfma_f32_16x16x32_bf16 v[0:3], v[48:51], v[100:103], v[0:3]
	ds_write_b16 v34, v4 offset:43680
	ds_write_b16_d16_hi v5, v4 offset:43952
	v_cvt_pk_bf16_f32 v4, v24, v25
	ds_write_b16 v34, v4 offset:43168
	ds_write_b16_d16_hi v5, v4 offset:43440
	v_cvt_pk_bf16_f32 v4, v26, v27
	ds_write_b16 v34, v4 offset:43712
	ds_write_b16_d16_hi v5, v4 offset:43984
	v_cvt_pk_bf16_f32 v4, v28, v29
	ds_write_b16 v34, v4 offset:43200
	ds_write_b16_d16_hi v5, v4 offset:43472
	v_cvt_pk_bf16_f32 v4, v30, v31
	v_cvt_pk_bf16_f32 v0, v0, v1
	ds_write_b16 v34, v4 offset:43744
	ds_write_b16_d16_hi v5, v4 offset:44016
	ds_write_b16 v34, v0 offset:43232
	ds_write_b16_d16_hi v5, v0 offset:43504
	v_cvt_pk_bf16_f32 v0, v2, v3
	ds_write_b16 v34, v0 offset:43776
	ds_write_b16_d16_hi v5, v0 offset:44048
	v_lshlrev_b32_e32 v0, 4, v97
	v_or_b32_e32 v10, s3, v98
	v_and_b32_e32 v34, 0xf0, v0
	v_mul_lo_u32 v0, v10, s30
	v_add3_u32 v14, 0, v34, v0
	s_waitcnt lgkmcnt(0)
	ds_read_b128 v[0:3], v14 offset:43008
	v_ashrrev_i32_e32 v11, 31, v10
	v_lshl_add_u64 v[8:9], s[18:19], 0, v[34:35]
	v_lshlrev_b64 v[4:5], 8, v[10:11]
	v_lshl_add_u64 v[12:13], v[8:9], 0, v[4:5]
	ds_read_b128 v[4:7], v14 offset:44096
	s_waitcnt lgkmcnt(1)
	global_store_dwordx4 v[12:13], v[0:3], off
	v_and_b32_e32 v79, 63, v254
	v_or_b32_e32 v79, s62, v79
	s_nop 0
	v_or_b32_e32 v0, 4, v10
	v_ashrrev_i32_e32 v1, 31, v0
	v_lshlrev_b64 v[0:1], 8, v[0:1]
	v_lshl_add_u64 v[0:1], v[8:9], 0, v[0:1]
	s_waitcnt lgkmcnt(0)
	global_store_dwordx4 v[0:1], v[4:7], off
	ds_read_b128 v[0:3], v14 offset:45184
	s_nop 0
	v_or_b32_e32 v4, 8, v10
	v_ashrrev_i32_e32 v5, 31, v4
	v_lshlrev_b64 v[4:5], 8, v[4:5]
	v_lshl_add_u64 v[12:13], v[8:9], 0, v[4:5]
	ds_read_b128 v[4:7], v14 offset:46272
	s_waitcnt lgkmcnt(1)
	global_store_dwordx4 v[12:13], v[0:3], off
	s_nop 1
	v_or_b32_e32 v0, 12, v10
	v_ashrrev_i32_e32 v1, 31, v0
	v_lshlrev_b64 v[0:1], 8, v[0:1]
	v_lshl_add_u64 v[0:1], v[8:9], 0, v[0:1]
	s_waitcnt lgkmcnt(0)
	global_store_dwordx4 v[0:1], v[4:7], off
	s_waitcnt lgkmcnt(0)
	s_barrier
; template <int DIR> __device__ __forceinline__ void h1_dir(unsigned char* lds, const bf16_t* zrow, int h, bf16_t* slot, float* decp) {
;     int tid_l = threadIdx.x; asm volatile("" : "+v"(tid_l)); const int tid = tid_l, lane = tid & 63, wid = __builtin_amdgcn_readfirstlane(tid >> 6), r = lane & 15, kq = lane >> 4;
;     float* TOT = (float*)(lds + L_TOT); bf16_t* KS = (bf16_t*)(lds + L_KO); bf16_t* VT = (bf16_t*)(lds + L_VT); bf16_t* STG = (bf16_t*)(lds + L_ST);
;     float bl[32], kk[32];
;     load32(zrow + (size_t)(1 + DIR) * ZSEG + 8 * kq, bl);
; #pragma unroll
;     for (int i = 0; i < 32; ++i) kk[i] = 1.0f - __builtin_amdgcn_exp2f(bl[i]);
;         scan16x8<DIR>(bl); scan16x8<DIR>(bl + 8); scan16x8<DIR>(bl + 16); scan16x8<DIR>(bl + 24);
	s_nop 0
	v_bfe_u32 v78, v79, 4, 2
	v_lshlrev_b32_e32 v34, 4, v78
	v_lshl_add_u64 v[4:5], v[38:39], 0, v[34:35]
	v_add_co_u32_e32 v0, vcc, s31, v4
	v_lshl_add_u64 v[16:17], v[4:5], 0, s[10:11]
	s_nop 0
	v_addc_co_u32_e32 v1, vcc, 0, v5, vcc
	global_load_dwordx4 v[0:3], v[0:1], off
	s_nop 0
	global_load_dwordx4 v[4:7], v[16:17], off offset:64
	global_load_dwordx4 v[8:11], v[16:17], off offset:128
	global_load_dwordx4 v[12:15], v[16:17], off offset:192
	v_readfirstlane_b32 s3, v79
	v_and_b32_e32 v98, 15, v79
	s_ashr_i32 s37, s3, 6
	v_lshlrev_b32_e32 v97, 3, v78
	v_cmp_eq_u32_e32 vcc, 0, v98
	s_waitcnt vmcnt(2)
	v_lshlrev_b32_e32 v107, 16, v4
	v_lshlrev_b32_e32 v99, 16, v0
	v_and_b32_e32 v100, 0xffff0000, v0
	v_lshlrev_b32_e32 v101, 16, v1
	v_and_b32_e32 v102, 0xffff0000, v1
	v_lshlrev_b32_e32 v103, 16, v2
	v_and_b32_e32 v104, 0xffff0000, v2
	v_lshlrev_b32_e32 v105, 16, v3
	v_and_b32_e32 v106, 0xffff0000, v3
	v_mov_b32_e32 v30, v101
	v_mov_b32_e32 v20, v103
	v_mov_b32_e32 v22, v105
	v_mov_b32_e32 v29, v100
	v_mov_b32_e32 v31, v102
	v_mov_b32_e32 v21, v104
	v_mov_b32_e32 v28, v99
	v_mov_b32_e32 v23, v106
	s_nop 1
	v_add_f32_dpp v28, v28, v28 row_shl:1 row_mask:0xf bank_mask:0xf bound_ctrl:1
	v_add_f32_dpp v29, v29, v29 row_shl:1 row_mask:0xf bank_mask:0xf bound_ctrl:1
	v_add_f32_dpp v30, v30, v30 row_shl:1 row_mask:0xf bank_mask:0xf bound_ctrl:1
	v_add_f32_dpp v31, v31, v31 row_shl:1 row_mask:0xf bank_mask:0xf bound_ctrl:1
	v_add_f32_dpp v20, v20, v20 row_shl:1 row_mask:0xf bank_mask:0xf bound_ctrl:1
	v_add_f32_dpp v21, v21, v21 row_shl:1 row_mask:0xf bank_mask:0xf bound_ctrl:1
	v_add_f32_dpp v22, v22, v22 row_shl:1 row_mask:0xf bank_mask:0xf bound_ctrl:1
	v_add_f32_dpp v23, v23, v23 row_shl:1 row_mask:0xf bank_mask:0xf bound_ctrl:1
	v_and_b32_e32 v108, 0xffff0000, v4
	v_lshlrev_b32_e32 v109, 16, v5
	v_and_b32_e32 v110, 0xffff0000, v5
	v_lshlrev_b32_e32 v111, 16, v6
	v_and_b32_e32 v112, 0xffff0000, v6
	v_lshlrev_b32_e32 v113, 16, v7
	v_and_b32_e32 v114, 0xffff0000, v7
	s_nop 1
	v_add_f32_dpp v28, v28, v28 row_shl:2 row_mask:0xf bank_mask:0xf bound_ctrl:1
	v_add_f32_dpp v29, v29, v29 row_shl:2 row_mask:0xf bank_mask:0xf bound_ctrl:1
	v_add_f32_dpp v30, v30, v30 row_shl:2 row_mask:0xf bank_mask:0xf bound_ctrl:1
	v_add_f32_dpp v31, v31, v31 row_shl:2 row_mask:0xf bank_mask:0xf bound_ctrl:1
	v_add_f32_dpp v20, v20, v20 row_shl:2 row_mask:0xf bank_mask:0xf bound_ctrl:1
	v_add_f32_dpp v21, v21, v21 row_shl:2 row_mask:0xf bank_mask:0xf bound_ctrl:1
	v_add_f32_dpp v22, v22, v22 row_shl:2 row_mask:0xf bank_mask:0xf bound_ctrl:1
	v_add_f32_dpp v23, v23, v23 row_shl:2 row_mask:0xf bank_mask:0xf bound_ctrl:1
	s_waitcnt vmcnt(0)
	v_lshlrev_b32_e32 v76, 16, v12
	v_and_b32_e32 v77, 0xffff0000, v12
	v_lshlrev_b32_e32 v74, 16, v13
	v_and_b32_e32 v75, 0xffff0000, v13
	v_lshlrev_b32_e32 v72, 16, v14
	v_and_b32_e32 v73, 0xffff0000, v14
	v_lshlrev_b32_e32 v70, 16, v15
	v_and_b32_e32 v71, 0xffff0000, v15
	s_nop 1
	v_add_f32_dpp v28, v28, v28 row_shl:4 row_mask:0xf bank_mask:0xf bound_ctrl:1
	v_add_f32_dpp v29, v29, v29 row_shl:4 row_mask:0xf bank_mask:0xf bound_ctrl:1
	v_add_f32_dpp v30, v30, v30 row_shl:4 row_mask:0xf bank_mask:0xf bound_ctrl:1
	v_add_f32_dpp v31, v31, v31 row_shl:4 row_mask:0xf bank_mask:0xf bound_ctrl:1
	v_add_f32_dpp v20, v20, v20 row_shl:4 row_mask:0xf bank_mask:0xf bound_ctrl:1
	v_add_f32_dpp v21, v21, v21 row_shl:4 row_mask:0xf bank_mask:0xf bound_ctrl:1
	v_add_f32_dpp v22, v22, v22 row_shl:4 row_mask:0xf bank_mask:0xf bound_ctrl:1
	v_add_f32_dpp v23, v23, v23 row_shl:4 row_mask:0xf bank_mask:0xf bound_ctrl:1
	v_mov_b32_e32 v26, v109
	v_mov_b32_e32 v12, v111
	v_mov_b32_e32 v14, v113
	v_mov_b32_e32 v25, v108
	v_mov_b32_e32 v27, v110
	v_mov_b32_e32 v13, v112
	v_mov_b32_e32 v24, v107
	v_mov_b32_e32 v15, v114
	s_nop 1
	v_add_f32_dpp v28, v28, v28 row_shl:8 row_mask:0xf bank_mask:0xf bound_ctrl:1
	v_add_f32_dpp v29, v29, v29 row_shl:8 row_mask:0xf bank_mask:0xf bound_ctrl:1
	v_add_f32_dpp v30, v30, v30 row_shl:8 row_mask:0xf bank_mask:0xf bound_ctrl:1
	v_add_f32_dpp v31, v31, v31 row_shl:8 row_mask:0xf bank_mask:0xf bound_ctrl:1
	v_add_f32_dpp v20, v20, v20 row_shl:8 row_mask:0xf bank_mask:0xf bound_ctrl:1
	v_add_f32_dpp v21, v21, v21 row_shl:8 row_mask:0xf bank_mask:0xf bound_ctrl:1
	v_add_f32_dpp v22, v22, v22 row_shl:8 row_mask:0xf bank_mask:0xf bound_ctrl:1
	v_add_f32_dpp v23, v23, v23 row_shl:8 row_mask:0xf bank_mask:0xf bound_ctrl:1
	s_nop 1
	v_add_f32_dpp v24, v24, v24 row_shl:1 row_mask:0xf bank_mask:0xf bound_ctrl:1
	v_add_f32_dpp v25, v25, v25 row_shl:1 row_mask:0xf bank_mask:0xf bound_ctrl:1
	v_add_f32_dpp v26, v26, v26 row_shl:1 row_mask:0xf bank_mask:0xf bound_ctrl:1
	v_add_f32_dpp v27, v27, v27 row_shl:1 row_mask:0xf bank_mask:0xf bound_ctrl:1
	v_add_f32_dpp v12, v12, v12 row_shl:1 row_mask:0xf bank_mask:0xf bound_ctrl:1
	v_add_f32_dpp v13, v13, v13 row_shl:1 row_mask:0xf bank_mask:0xf bound_ctrl:1
	v_add_f32_dpp v14, v14, v14 row_shl:1 row_mask:0xf bank_mask:0xf bound_ctrl:1
	v_add_f32_dpp v15, v15, v15 row_shl:1 row_mask:0xf bank_mask:0xf bound_ctrl:1
	v_lshlrev_b32_e32 v115, 16, v8
	v_and_b32_e32 v116, 0xffff0000, v8
	v_lshlrev_b32_e32 v117, 16, v9
	v_and_b32_e32 v118, 0xffff0000, v9
	v_lshlrev_b32_e32 v119, 16, v10
	v_and_b32_e32 v120, 0xffff0000, v10
	v_lshlrev_b32_e32 v121, 16, v11
	v_and_b32_e32 v122, 0xffff0000, v11
	s_nop 1
	v_add_f32_dpp v24, v24, v24 row_shl:2 row_mask:0xf bank_mask:0xf bound_ctrl:1
	v_add_f32_dpp v25, v25, v25 row_shl:2 row_mask:0xf bank_mask:0xf bound_ctrl:1
	v_add_f32_dpp v26, v26, v26 row_shl:2 row_mask:0xf bank_mask:0xf bound_ctrl:1
	v_add_f32_dpp v27, v27, v27 row_shl:2 row_mask:0xf bank_mask:0xf bound_ctrl:1
; template <int DIR> __device__ __forceinline__ void scan16x8(float* v) {
;     if (DIR == 0) { SCAN_STEP("row_shr:", 1); SCAN_STEP("row_shr:", 2); SCAN_STEP("row_shr:", 4); SCAN_STEP("row_shr:", 8); }
;     else          { SCAN_STEP("row_shl:", 1); SCAN_STEP("row_shl:", 2); SCAN_STEP("row_shl:", 4); SCAN_STEP("row_shl:", 8); }
; }
	v_add_f32_dpp v12, v12, v12 row_shl:2 row_mask:0xf bank_mask:0xf bound_ctrl:1
	v_add_f32_dpp v13, v13, v13 row_shl:2 row_mask:0xf bank_mask:0xf bound_ctrl:1
	v_add_f32_dpp v14, v14, v14 row_shl:2 row_mask:0xf bank_mask:0xf bound_ctrl:1
	v_add_f32_dpp v15, v15, v15 row_shl:2 row_mask:0xf bank_mask:0xf bound_ctrl:1
	v_mov_b32_e32 v18, v117
	s_nop 1
	v_add_f32_dpp v24, v24, v24 row_shl:4 row_mask:0xf bank_mask:0xf bound_ctrl:1
	v_add_f32_dpp v25, v25, v25 row_shl:4 row_mask:0xf bank_mask:0xf bound_ctrl:1
	v_add_f32_dpp v26, v26, v26 row_shl:4 row_mask:0xf bank_mask:0xf bound_ctrl:1
	v_add_f32_dpp v27, v27, v27 row_shl:4 row_mask:0xf bank_mask:0xf bound_ctrl:1
	v_add_f32_dpp v12, v12, v12 row_shl:4 row_mask:0xf bank_mask:0xf bound_ctrl:1
	v_add_f32_dpp v13, v13, v13 row_shl:4 row_mask:0xf bank_mask:0xf bound_ctrl:1
	v_add_f32_dpp v14, v14, v14 row_shl:4 row_mask:0xf bank_mask:0xf bound_ctrl:1
	v_add_f32_dpp v15, v15, v15 row_shl:4 row_mask:0xf bank_mask:0xf bound_ctrl:1
	v_mov_b32_e32 v4, v119
	v_mov_b32_e32 v6, v121
	v_mov_b32_e32 v17, v116
	v_mov_b32_e32 v19, v118
	v_mov_b32_e32 v5, v120
	v_mov_b32_e32 v16, v115
	v_mov_b32_e32 v7, v122
	s_nop 1
	v_add_f32_dpp v24, v24, v24 row_shl:8 row_mask:0xf bank_mask:0xf bound_ctrl:1
	v_add_f32_dpp v25, v25, v25 row_shl:8 row_mask:0xf bank_mask:0xf bound_ctrl:1
	v_add_f32_dpp v26, v26, v26 row_shl:8 row_mask:0xf bank_mask:0xf bound_ctrl:1
	v_add_f32_dpp v27, v27, v27 row_shl:8 row_mask:0xf bank_mask:0xf bound_ctrl:1
	v_add_f32_dpp v12, v12, v12 row_shl:8 row_mask:0xf bank_mask:0xf bound_ctrl:1
	v_add_f32_dpp v13, v13, v13 row_shl:8 row_mask:0xf bank_mask:0xf bound_ctrl:1
	v_add_f32_dpp v14, v14, v14 row_shl:8 row_mask:0xf bank_mask:0xf bound_ctrl:1
	v_add_f32_dpp v15, v15, v15 row_shl:8 row_mask:0xf bank_mask:0xf bound_ctrl:1
	s_nop 1
	v_add_f32_dpp v16, v16, v16 row_shl:1 row_mask:0xf bank_mask:0xf bound_ctrl:1
	v_add_f32_dpp v17, v17, v17 row_shl:1 row_mask:0xf bank_mask:0xf bound_ctrl:1
	v_add_f32_dpp v18, v18, v18 row_shl:1 row_mask:0xf bank_mask:0xf bound_ctrl:1
	v_add_f32_dpp v19, v19, v19 row_shl:1 row_mask:0xf bank_mask:0xf bound_ctrl:1
	v_add_f32_dpp v4, v4, v4 row_shl:1 row_mask:0xf bank_mask:0xf bound_ctrl:1
	v_add_f32_dpp v5, v5, v5 row_shl:1 row_mask:0xf bank_mask:0xf bound_ctrl:1
	v_add_f32_dpp v6, v6, v6 row_shl:1 row_mask:0xf bank_mask:0xf bound_ctrl:1
	v_add_f32_dpp v7, v7, v7 row_shl:1 row_mask:0xf bank_mask:0xf bound_ctrl:1
	v_mov_b32_e32 v10, v74
	s_nop 1
	v_add_f32_dpp v16, v16, v16 row_shl:2 row_mask:0xf bank_mask:0xf bound_ctrl:1
	v_add_f32_dpp v17, v17, v17 row_shl:2 row_mask:0xf bank_mask:0xf bound_ctrl:1
	v_add_f32_dpp v18, v18, v18 row_shl:2 row_mask:0xf bank_mask:0xf bound_ctrl:1
	v_add_f32_dpp v19, v19, v19 row_shl:2 row_mask:0xf bank_mask:0xf bound_ctrl:1
	v_add_f32_dpp v4, v4, v4 row_shl:2 row_mask:0xf bank_mask:0xf bound_ctrl:1
	v_add_f32_dpp v5, v5, v5 row_shl:2 row_mask:0xf bank_mask:0xf bound_ctrl:1
	v_add_f32_dpp v6, v6, v6 row_shl:2 row_mask:0xf bank_mask:0xf bound_ctrl:1
	v_add_f32_dpp v7, v7, v7 row_shl:2 row_mask:0xf bank_mask:0xf bound_ctrl:1
	v_mov_b32_e32 v0, v72
	s_nop 1
	v_add_f32_dpp v16, v16, v16 row_shl:4 row_mask:0xf bank_mask:0xf bound_ctrl:1
	v_add_f32_dpp v17, v17, v17 row_shl:4 row_mask:0xf bank_mask:0xf bound_ctrl:1
	v_add_f32_dpp v18, v18, v18 row_shl:4 row_mask:0xf bank_mask:0xf bound_ctrl:1
	v_add_f32_dpp v19, v19, v19 row_shl:4 row_mask:0xf bank_mask:0xf bound_ctrl:1
	v_add_f32_dpp v4, v4, v4 row_shl:4 row_mask:0xf bank_mask:0xf bound_ctrl:1
	v_add_f32_dpp v5, v5, v5 row_shl:4 row_mask:0xf bank_mask:0xf bound_ctrl:1
	v_add_f32_dpp v6, v6, v6 row_shl:4 row_mask:0xf bank_mask:0xf bound_ctrl:1
	v_add_f32_dpp v7, v7, v7 row_shl:4 row_mask:0xf bank_mask:0xf bound_ctrl:1
; template <int DIR> __device__ __forceinline__ void h1_dir(unsigned char* lds, const bf16_t* zrow, int h, bf16_t* slot, float* decp) {
;     ...
;     load32(zrow + (size_t)(1 + DIR) * ZSEG + 8 * kq, bl);
; #pragma unroll
;     for (int i = 0; i < 32; ++i) kk[i] = 1.0f - __builtin_amdgcn_exp2f(bl[i]);
;         scan16x8<DIR>(bl); scan16x8<DIR>(bl + 8); scan16x8<DIR>(bl + 16); scan16x8<DIR>(bl + 24);
;     if (r == (DIR ? 0 : 15)) {
; #pragma unroll
;         for (int ks = 0; ks < 4; ++ks) { *(f32x4*)(TOT + wid * 128 + 32 * ks + 8 * kq) = (f32x4){bl[8 * ks], bl[8 * ks + 1], bl[8 * ks + 2], bl[8 * ks + 3]}; *(f32x4*)(TOT + wid * 128 + 32 * ks + 8 * kq + 4) = (f32x4){bl[8 * ks + 4], bl[8 * ks + 5], bl[8 * ks + 6], bl[8 * ks + 7]}; }
;     }
	v_mov_b32_e32 v2, v70
	v_mov_b32_e32 v9, v77
	v_mov_b32_e32 v11, v75
	v_mov_b32_e32 v1, v73
	v_mov_b32_e32 v8, v76
	v_mov_b32_e32 v3, v71
	s_nop 1
	v_add_f32_dpp v16, v16, v16 row_shl:8 row_mask:0xf bank_mask:0xf bound_ctrl:1
	v_add_f32_dpp v17, v17, v17 row_shl:8 row_mask:0xf bank_mask:0xf bound_ctrl:1
	v_add_f32_dpp v18, v18, v18 row_shl:8 row_mask:0xf bank_mask:0xf bound_ctrl:1
	v_add_f32_dpp v19, v19, v19 row_shl:8 row_mask:0xf bank_mask:0xf bound_ctrl:1
	v_add_f32_dpp v4, v4, v4 row_shl:8 row_mask:0xf bank_mask:0xf bound_ctrl:1
	v_add_f32_dpp v5, v5, v5 row_shl:8 row_mask:0xf bank_mask:0xf bound_ctrl:1
	v_add_f32_dpp v6, v6, v6 row_shl:8 row_mask:0xf bank_mask:0xf bound_ctrl:1
	v_add_f32_dpp v7, v7, v7 row_shl:8 row_mask:0xf bank_mask:0xf bound_ctrl:1
	s_nop 1
	v_add_f32_dpp v8, v8, v8 row_shl:1 row_mask:0xf bank_mask:0xf bound_ctrl:1
	v_add_f32_dpp v9, v9, v9 row_shl:1 row_mask:0xf bank_mask:0xf bound_ctrl:1
	v_add_f32_dpp v10, v10, v10 row_shl:1 row_mask:0xf bank_mask:0xf bound_ctrl:1
	v_add_f32_dpp v11, v11, v11 row_shl:1 row_mask:0xf bank_mask:0xf bound_ctrl:1
	v_add_f32_dpp v0, v0, v0 row_shl:1 row_mask:0xf bank_mask:0xf bound_ctrl:1
	v_add_f32_dpp v1, v1, v1 row_shl:1 row_mask:0xf bank_mask:0xf bound_ctrl:1
	v_add_f32_dpp v2, v2, v2 row_shl:1 row_mask:0xf bank_mask:0xf bound_ctrl:1
	v_add_f32_dpp v3, v3, v3 row_shl:1 row_mask:0xf bank_mask:0xf bound_ctrl:1
	s_nop 0
	s_nop 1
	v_add_f32_dpp v8, v8, v8 row_shl:2 row_mask:0xf bank_mask:0xf bound_ctrl:1
	v_add_f32_dpp v9, v9, v9 row_shl:2 row_mask:0xf bank_mask:0xf bound_ctrl:1
	v_add_f32_dpp v10, v10, v10 row_shl:2 row_mask:0xf bank_mask:0xf bound_ctrl:1
	v_add_f32_dpp v11, v11, v11 row_shl:2 row_mask:0xf bank_mask:0xf bound_ctrl:1
	v_add_f32_dpp v0, v0, v0 row_shl:2 row_mask:0xf bank_mask:0xf bound_ctrl:1
	v_add_f32_dpp v1, v1, v1 row_shl:2 row_mask:0xf bank_mask:0xf bound_ctrl:1
	v_add_f32_dpp v2, v2, v2 row_shl:2 row_mask:0xf bank_mask:0xf bound_ctrl:1
	v_add_f32_dpp v3, v3, v3 row_shl:2 row_mask:0xf bank_mask:0xf bound_ctrl:1
	s_nop 0
	s_nop 1
	v_add_f32_dpp v8, v8, v8 row_shl:4 row_mask:0xf bank_mask:0xf bound_ctrl:1
	v_add_f32_dpp v9, v9, v9 row_shl:4 row_mask:0xf bank_mask:0xf bound_ctrl:1
	v_add_f32_dpp v10, v10, v10 row_shl:4 row_mask:0xf bank_mask:0xf bound_ctrl:1
	v_add_f32_dpp v11, v11, v11 row_shl:4 row_mask:0xf bank_mask:0xf bound_ctrl:1
	v_add_f32_dpp v0, v0, v0 row_shl:4 row_mask:0xf bank_mask:0xf bound_ctrl:1
	v_add_f32_dpp v1, v1, v1 row_shl:4 row_mask:0xf bank_mask:0xf bound_ctrl:1
	v_add_f32_dpp v2, v2, v2 row_shl:4 row_mask:0xf bank_mask:0xf bound_ctrl:1
	v_add_f32_dpp v3, v3, v3 row_shl:4 row_mask:0xf bank_mask:0xf bound_ctrl:1
	s_nop 0
	s_nop 1
	v_add_f32_dpp v8, v8, v8 row_shl:8 row_mask:0xf bank_mask:0xf bound_ctrl:1
	v_add_f32_dpp v9, v9, v9 row_shl:8 row_mask:0xf bank_mask:0xf bound_ctrl:1
	v_add_f32_dpp v10, v10, v10 row_shl:8 row_mask:0xf bank_mask:0xf bound_ctrl:1
	v_add_f32_dpp v11, v11, v11 row_shl:8 row_mask:0xf bank_mask:0xf bound_ctrl:1
	v_add_f32_dpp v0, v0, v0 row_shl:8 row_mask:0xf bank_mask:0xf bound_ctrl:1
	v_add_f32_dpp v1, v1, v1 row_shl:8 row_mask:0xf bank_mask:0xf bound_ctrl:1
	v_add_f32_dpp v2, v2, v2 row_shl:8 row_mask:0xf bank_mask:0xf bound_ctrl:1
	v_add_f32_dpp v3, v3, v3 row_shl:8 row_mask:0xf bank_mask:0xf bound_ctrl:1
	s_and_saveexec_b64 s[18:19], vcc
	s_cbranch_execz .LBB0_2477
	s_lshl_b32 s3, s37, 9
	s_add_i32 s3, s3, 0
	v_lshl_add_u32 v34, v97, 2, s3
	ds_write_b128 v34, v[28:31]
	ds_write_b128 v34, v[20:23] offset:16
	ds_write_b128 v34, v[24:27] offset:128
	ds_write_b128 v34, v[12:15] offset:144
	ds_write_b128 v34, v[16:19] offset:256
	ds_write_b128 v34, v[4:7] offset:272
	ds_write_b128 v34, v[8:11] offset:384
	ds_write_b128 v34, v[0:3] offset:400

; template <bool STORE> __device__ __forceinline__ void h3_phase(unsigned char* lds, unsigned char* ws, const bf16_t* SF, const float* norm_g, int G, int blk) {
;     int tid_l = threadIdx.x; asm volatile("" : "+v"(tid_l)); const int tid = tid_l, lane = tid & 63, wid = __builtin_amdgcn_readfirstlane(tid >> 6), r = lane & 15, kq = lane >> 4;
;     bf16_t* Z = (bf16_t*)(ws + WS_Z); bf16_t* VT = (bf16_t*)(lds + L_VT); float* STGF = (float*)(lds + L_KO) + wid * 16 * 132;
;     for (int unit = blk; unit < 2048; unit += G) {
;         const int b = unit >> 10, c = (unit >> 3) & 127, h = unit & 7, chain = b * 8 + h;
;         const size_t tok0 = (size_t)b * SEQ + c * 128 + 16 * wid;
;         const bf16_t* zrow = Z + ((size_t)h * M + tok0 + r) * 128;
.LBB0_2606:
	s_or_b64 exec, exec, s[4:5]
	s_mov_b32 s16, s74
	s_mov_b64 s[4:5], s[0:1]
	s_mov_b32 s17, s2
	s_waitcnt lgkmcnt(0)
	v_readfirstlane_b32 s62, v254
	s_lshr_b32 s62, s62, 6
	s_sub_u32 s63, 11, s62
	s_cmp_lt_u32 s62, 4
	s_cselect_b32 s62, s62, s63
	s_lshl_b32 s62, s62, 6
	v_and_b32_e32 v0, 63, v254
	v_or_b32_e32 v0, s62, v0
	s_barrier
	s_cmpk_gt_i32 s17, 0x7ff
	v_readfirstlane_b32 s3, v0
	s_cbranch_scc1 .LBB0_2629
	s_load_dwordx4 s[12:15], s[4:5], 0x88
	s_load_dwordx2 s[6:7], s[4:5], 0x38
	v_and_b32_e32 v112, 15, v0
	v_bfe_u32 v114, v0, 4, 2
	v_lshlrev_b32_e32 v0, 3, v0
	s_waitcnt lgkmcnt(0)
	s_add_u32 s18, s12, 0x4000000
	s_addc_u32 s19, s13, 0
	s_add_u32 s10, s14, 0x6800000
	s_addc_u32 s11, s15, 0
	s_ashr_i32 s3, s3, 2
	s_and_b32 s20, s3, -16
	s_mul_i32 s3, s20, 0x210
	s_lshl_b32 s5, s20, 1
	v_and_b32_e32 v0, 0x78, v0
	s_mov_b32 s4, 0
	s_add_i32 s3, s3, 0
	v_mov_b32_e32 v117, 0
	s_add_i32 s5, s5, 0
	v_lshlrev_b32_e32 v116, 2, v0
	v_mul_u32_u24_e32 v5, 0x440, v114
	s_ashr_i32 s21, s20, 31
	s_add_i32 s5, s5, 0x13000
	v_lshlrev_b32_e32 v1, 1, v112
	v_add_u32_e32 v4, s3, v116
	v_lshl_add_u64 v[118:119], s[6:7], 0, v[116:117]
	v_lshlrev_b32_e32 v116, 1, v0
	v_mul_u32_u24_e32 v0, 0x210, v114
	v_lshlrev_b32_e32 v5, 1, v5
	v_or_b32_e32 v122, 4, v114
	s_mov_b32 s6, s4
	s_mov_b32 s7, s4
	v_lshlrev_b32_e32 v2, 3, v114
	s_add_u32 s22, s14, 0x1a800000
	v_lshl_add_u32 v3, v112, 2, s3
	v_add3_u32 v113, s5, v1, v5
	v_add3_u32 v115, s5, v5, v1
	v_mul_u32_u24_e32 v1, 0x840, v114
	v_mul_u32_u24_e32 v5, 0x210, v122
	s_mov_b32 s5, s4
	v_mov_b64_e32 v[186:187], s[6:7]
	v_add_u32_e32 v145, v4, v0
	v_mbcnt_lo_u32_b32 v0, -1, 0
	s_mov_b64 s[8:9], 0x4000000
	s_addc_u32 s23, s15, 0
	v_lshl_add_u64 v[120:121], s[10:11], 0, v[116:117]
	s_movk_i32 s24, 0x440
	v_add_u32_e32 v123, 0x220, v113
	v_add_u32_e32 v125, 0x440, v113
	v_add_u32_e32 v127, 0x660, v113
	v_add_u32_e32 v130, 0x2200, v113
	v_add_u32_e32 v131, 0x2420, v113
	v_add_u32_e32 v132, 0x2640, v113
	v_add_u32_e32 v133, 0x2860, v113
	v_add_u32_e32 v134, 0x4400, v113
	v_add_u32_e32 v135, 0x4620, v113
	v_add_u32_e32 v136, 0x4840, v113
	v_add_u32_e32 v137, 0x4a60, v113
	v_add_u32_e32 v138, 0x6600, v113
	v_add_u32_e32 v139, 0x6820, v113
	v_add_u32_e32 v140, 0x6a40, v113
	v_add_u32_e32 v141, 0x6c60, v113
	v_or_b32_e32 v124, 8, v114
	v_or_b32_e32 v126, 12, v114
	v_lshlrev_b32_e32 v128, 1, v2
	v_mov_b32_e32 v129, v117
	s_mov_b64 s[12:13], 0xc000000
	s_brev_b32 s25, 48
	s_brev_b32 s26, 32
	s_movk_i32 s27, 0x110
	v_mov_b64_e32 v[184:185], s[4:5]
	s_mov_b64 s[14:15], 0x8000000
	s_brev_b32 s28, 16
	v_mov_b32_e32 v142, 0x3727c5ac
	s_mov_b32 s29, 0xf800000
	v_mov_b32_e32 v143, 0x260
	v_add_u32_e32 v144, v3, v1
	s_brev_b32 s30, 8
	v_add_u32_e32 v146, v4, v5
	v_mbcnt_hi_u32_b32 v147, -1, v0
	s_branch .LBB0_2609

; template <int DIR> __device__ __forceinline__ void h3_dir(unsigned char* lds, const bf16_t* zrow, int h, const bf16_t* slot, f32x4 (&o)[8]) {
;     int tid_l = threadIdx.x; asm volatile("" : "+v"(tid_l)); const int tid = tid_l, lane = tid & 63, wid = __builtin_amdgcn_readfirstlane(tid >> 6), r = lane & 15, kq = lane >> 4;
;     float* TOT = (float*)(lds + L_TOT); float* TOTE = (float*)(lds + L_TOTE); bf16_t* KO = (bf16_t*)(lds + L_KO); bf16_t* ST = (bf16_t*)(lds + L_ST); const bf16_t* VT = (const bf16_t*)(lds + L_VT); bf16_t* Pw = (bf16_t*)(lds + L_P) + wid * 16 * HP;
;     float bl[32], qin[32]; bf16x8 kin[4];
;     load32(zrow + (size_t)(1 + DIR) * ZSEG + 8 * kq, bl);
;     load32(zrow + 8 * kq, qin);
; template <bool STORE> __device__ __forceinline__ void h3_phase(unsigned char* lds, unsigned char* ws, const bf16_t* SF, const float* norm_g, int G, int blk) {
;     ...
;     for (int unit = blk; unit < 2048; unit += G) {
;         const int b = unit >> 10, c = (unit >> 3) & 127, h = unit & 7, chain = b * 8 + h;
;         const size_t tok0 = (size_t)b * SEQ + c * 128 + 16 * wid;
;         const bf16_t* zrow = Z + ((size_t)h * M + tok0 + r) * 128;
;         {
; #pragma unroll
;           for (int ks = 0; ks < 4; ++ks) { const u32x4 w = *(const u32x4*)(zrow + 3 * ZSEG + 8 * kq + 32 * ks);
; #pragma unroll
;               for (int e = 0; e < 4; ++e) { VT[(32 * ks + 8 * kq + 2 * e) * HP + 16 * wid + r] = (bf16_t)(w[e] & 0xffffu); VT[(32 * ks + 8 * kq + 2 * e + 1) * HP + 16 * wid + r] = (bf16_t)(w[e] >> 16); } } }
.LBB0_2609:
	s_ashr_i32 s4, s17, 10
	s_bfe_u32 s3, s17, 0x70003
	s_and_b32 s36, s17, 7
	s_ashr_i32 s5, s4, 31
	s_lshl_b64 s[6:7], s[4:5], 14
	s_lshl_b32 s5, s3, 7
	s_lshl_b32 s31, s36, 15
	s_add_u32 s6, s6, s20
	s_addc_u32 s7, s7, s21
	s_add_u32 s6, s6, s31
	s_addc_u32 s7, s7, 0
	s_add_u32 s31, s6, s5
	s_addc_u32 s34, s7, 0
	v_mov_b32_e32 v1, s34
	v_or_b32_e32 v0, s31, v112
	v_lshlrev_b64 v[0:1], 8, v[0:1]
	v_lshl_add_u64 v[80:81], s[10:11], 0, v[0:1]
	v_lshl_add_u64 v[4:5], v[80:81], 0, v[128:129]
	v_add_co_u32_e32 v0, vcc, s25, v4
	v_lshl_add_u64 v[16:17], v[4:5], 0, s[12:13]
	s_nop 0
	v_addc_co_u32_e32 v1, vcc, 0, v5, vcc
	global_load_dwordx4 v[0:3], v[0:1], off
	s_nop 0
	global_load_dwordx4 v[4:7], v[16:17], off offset:64
	global_load_dwordx4 v[8:11], v[16:17], off offset:128
	global_load_dwordx4 v[12:15], v[16:17], off offset:192
	v_bfe_u32 v206, v254, 4, 2
	v_lshlrev_b32_e32 v206, 4, v206
	v_mov_b32_e32 v207, 0
	v_lshl_add_u64 v[222:223], v[80:81], 0, v[206:207]
	v_lshl_add_u64 v[224:225], v[222:223], 0, s[8:9]
	global_load_dwordx4 v[206:209], v[224:225], off
	global_load_dwordx4 v[210:213], v[224:225], off offset:64
	global_load_dwordx4 v[214:217], v[224:225], off offset:128
	global_load_dwordx4 v[218:221], v[224:225], off offset:192
	global_load_dwordx4 v[64:67], v[222:223], off
	global_load_dwordx4 v[52:55], v[222:223], off offset:64
	global_load_dwordx4 v[48:51], v[222:223], off offset:128
	global_load_dwordx4 v[44:47], v[222:223], off offset:192
	v_and_b32_e32 v85, 63, v254
	v_or_b32_e32 v85, s62, v85
	s_waitcnt vmcnt(11)
	ds_write_b16 v113, v0
	ds_write_b16_d16_hi v115, v0 offset:272
	ds_write_b16 v113, v1 offset:544
	ds_write_b16_d16_hi v123, v1 offset:272
	ds_write_b16 v113, v2 offset:1088
	ds_write_b16_d16_hi v125, v2 offset:272
	ds_write_b16 v113, v3 offset:1632
	ds_write_b16_d16_hi v127, v3 offset:272
	s_waitcnt vmcnt(10)
	ds_write_b16 v113, v4 offset:8704
	ds_write_b16_d16_hi v130, v4 offset:272
	ds_write_b16 v113, v5 offset:9248
	ds_write_b16_d16_hi v131, v5 offset:272
	ds_write_b16 v113, v6 offset:9792
	ds_write_b16_d16_hi v132, v6 offset:272
	ds_write_b16 v113, v7 offset:10336
	ds_write_b16_d16_hi v133, v7 offset:272
	s_waitcnt vmcnt(9)
	ds_write_b16 v113, v8 offset:17408
	ds_write_b16_d16_hi v134, v8 offset:272
	ds_write_b16 v113, v9 offset:17952
	ds_write_b16_d16_hi v135, v9 offset:272
	ds_write_b16 v113, v10 offset:18496
	ds_write_b16_d16_hi v136, v10 offset:272
	ds_write_b16 v113, v11 offset:19040
	ds_write_b16_d16_hi v137, v11 offset:272
	s_waitcnt vmcnt(8)
	ds_write_b16 v113, v12 offset:26112
	ds_write_b16_d16_hi v138, v12 offset:272
	ds_write_b16 v113, v13 offset:26656
	ds_write_b16_d16_hi v139, v13 offset:272
	ds_write_b16 v113, v14 offset:27200
	ds_write_b16_d16_hi v140, v14 offset:272
	ds_write_b16 v113, v15 offset:27744
	ds_write_b16_d16_hi v141, v15 offset:272
	s_nop 0
	v_bfe_u32 v84, v85, 4, 2
	v_lshlrev_b32_e32 v116, 4, v84
	v_lshl_add_u64 v[16:17], v[80:81], 0, v[116:117]
	v_lshl_add_u64 v[18:19], v[16:17], 0, s[8:9]
	s_waitcnt vmcnt(4)
	v_mov_b32_e32 v0, v206
	v_mov_b32_e32 v1, v207
	v_mov_b32_e32 v2, v208
	v_mov_b32_e32 v3, v209
	v_mov_b32_e32 v4, v210
	v_mov_b32_e32 v5, v211
	v_mov_b32_e32 v6, v212
	v_mov_b32_e32 v7, v213
	v_mov_b32_e32 v8, v214
	v_mov_b32_e32 v9, v215
	v_mov_b32_e32 v10, v216
	v_mov_b32_e32 v11, v217
	v_mov_b32_e32 v12, v218
	v_mov_b32_e32 v13, v219
	v_mov_b32_e32 v14, v220
	v_mov_b32_e32 v15, v221
	v_readfirstlane_b32 s5, v85
	s_ashr_i32 s35, s5, 6
	v_and_b32_e32 v83, 15, v85
	v_lshlrev_b32_e32 v82, 3, v84
	v_cmp_eq_u32_e32 vcc, 15, v83
	s_lshl_b32 s37, s35, 9
	s_waitcnt vmcnt(6)
	v_lshlrev_b32_e32 v111, 16, v4
	v_lshlrev_b32_e32 v107, 16, v0
	v_and_b32_e32 v106, 0xffff0000, v0
	v_lshlrev_b32_e32 v152, 16, v1
	v_and_b32_e32 v151, 0xffff0000, v1
	v_lshlrev_b32_e32 v150, 16, v2
	v_and_b32_e32 v149, 0xffff0000, v2
	v_lshlrev_b32_e32 v148, 16, v3
	v_and_b32_e32 v116, 0xffff0000, v3
	v_mov_b32_e32 v25, v149
	v_mov_b32_e32 v32, v107
	v_mov_b32_e32 v27, v116
	v_mov_b32_e32 v34, v152
	v_mov_b32_e32 v24, v150
	v_mov_b32_e32 v26, v148
	v_mov_b32_e32 v33, v106
	v_mov_b32_e32 v35, v151
	s_nop 1
	v_add_f32_dpp v32, v32, v32 row_shr:1 row_mask:0xf bank_mask:0xf bound_ctrl:1
	v_add_f32_dpp v33, v33, v33 row_shr:1 row_mask:0xf bank_mask:0xf bound_ctrl:1
	v_add_f32_dpp v34, v34, v34 row_shr:1 row_mask:0xf bank_mask:0xf bound_ctrl:1
	v_add_f32_dpp v35, v35, v35 row_shr:1 row_mask:0xf bank_mask:0xf bound_ctrl:1
	v_add_f32_dpp v24, v24, v24 row_shr:1 row_mask:0xf bank_mask:0xf bound_ctrl:1
	v_add_f32_dpp v25, v25, v25 row_shr:1 row_mask:0xf bank_mask:0xf bound_ctrl:1
	v_add_f32_dpp v26, v26, v26 row_shr:1 row_mask:0xf bank_mask:0xf bound_ctrl:1
	v_add_f32_dpp v27, v27, v27 row_shr:1 row_mask:0xf bank_mask:0xf bound_ctrl:1
	v_and_b32_e32 v110, 0xffff0000, v4
	v_lshlrev_b32_e32 v109, 16, v5
	v_and_b32_e32 v108, 0xffff0000, v5
	v_lshlrev_b32_e32 v102, 16, v6
	v_and_b32_e32 v103, 0xffff0000, v6
	v_lshlrev_b32_e32 v104, 16, v7
	v_and_b32_e32 v105, 0xffff0000, v7
	s_nop 1
	v_add_f32_dpp v32, v32, v32 row_shr:2 row_mask:0xf bank_mask:0xf bound_ctrl:1
	v_add_f32_dpp v33, v33, v33 row_shr:2 row_mask:0xf bank_mask:0xf bound_ctrl:1
	v_add_f32_dpp v34, v34, v34 row_shr:2 row_mask:0xf bank_mask:0xf bound_ctrl:1
	v_add_f32_dpp v35, v35, v35 row_shr:2 row_mask:0xf bank_mask:0xf bound_ctrl:1
	v_add_f32_dpp v24, v24, v24 row_shr:2 row_mask:0xf bank_mask:0xf bound_ctrl:1
	v_add_f32_dpp v25, v25, v25 row_shr:2 row_mask:0xf bank_mask:0xf bound_ctrl:1
	v_add_f32_dpp v26, v26, v26 row_shr:2 row_mask:0xf bank_mask:0xf bound_ctrl:1
	v_add_f32_dpp v27, v27, v27 row_shr:2 row_mask:0xf bank_mask:0xf bound_ctrl:1
	v_mov_b32_e32 v17, v103
	v_mov_b32_e32 v20, v111
	v_mov_b32_e32 v19, v105
	v_mov_b32_e32 v22, v109
	v_mov_b32_e32 v16, v102
	v_mov_b32_e32 v18, v104
	v_mov_b32_e32 v21, v110
	v_mov_b32_e32 v23, v108
	s_nop 1
	v_add_f32_dpp v32, v32, v32 row_shr:4 row_mask:0xf bank_mask:0xf bound_ctrl:1
	v_add_f32_dpp v33, v33, v33 row_shr:4 row_mask:0xf bank_mask:0xf bound_ctrl:1
	v_add_f32_dpp v34, v34, v34 row_shr:4 row_mask:0xf bank_mask:0xf bound_ctrl:1
	v_add_f32_dpp v35, v35, v35 row_shr:4 row_mask:0xf bank_mask:0xf bound_ctrl:1
	v_add_f32_dpp v24, v24, v24 row_shr:4 row_mask:0xf bank_mask:0xf bound_ctrl:1
	v_add_f32_dpp v25, v25, v25 row_shr:4 row_mask:0xf bank_mask:0xf bound_ctrl:1
	v_add_f32_dpp v26, v26, v26 row_shr:4 row_mask:0xf bank_mask:0xf bound_ctrl:1
	v_add_f32_dpp v27, v27, v27 row_shr:4 row_mask:0xf bank_mask:0xf bound_ctrl:1
	s_waitcnt vmcnt(5)
; __device__ __forceinline__ float bf_lo(unsigned w) { return __uint_as_float(w << 16); }
; __device__ __forceinline__ float bf_hi(unsigned w) { return __uint_as_float(w & 0xffff0000u); }
; template <int DIR> __device__ __forceinline__ void scan16x8(float* v) {
;     if (DIR == 0) { SCAN_STEP("row_shr:", 1); SCAN_STEP("row_shr:", 2); SCAN_STEP("row_shr:", 4); SCAN_STEP("row_shr:", 8); }
;     else          { SCAN_STEP("row_shl:", 1); SCAN_STEP("row_shl:", 2); SCAN_STEP("row_shl:", 4); SCAN_STEP("row_shl:", 8); }
; }
; __device__ __forceinline__ void load32(const bf16_t* p, float (&v)[32]) {
; #pragma unroll
;     for (int ks = 0; ks < 4; ++ks) { const u32x4 w = *(const u32x4*)(p + 32 * ks);
;         v[8 * ks + 0] = bf_lo(w.x); v[8 * ks + 1] = bf_hi(w.x); v[8 * ks + 2] = bf_lo(w.y); v[8 * ks + 3] = bf_hi(w.y); v[8 * ks + 4] = bf_lo(w.z); v[8 * ks + 5] = bf_hi(w.z); v[8 * ks + 6] = bf_lo(w.w); v[8 * ks + 7] = bf_hi(w.w); }
	v_lshlrev_b32_e32 v98, 16, v8
	s_nop 1
	v_add_f32_dpp v32, v32, v32 row_shr:8 row_mask:0xf bank_mask:0xf bound_ctrl:1
	v_add_f32_dpp v33, v33, v33 row_shr:8 row_mask:0xf bank_mask:0xf bound_ctrl:1
	v_add_f32_dpp v34, v34, v34 row_shr:8 row_mask:0xf bank_mask:0xf bound_ctrl:1
	v_add_f32_dpp v35, v35, v35 row_shr:8 row_mask:0xf bank_mask:0xf bound_ctrl:1
	v_add_f32_dpp v24, v24, v24 row_shr:8 row_mask:0xf bank_mask:0xf bound_ctrl:1
	v_add_f32_dpp v25, v25, v25 row_shr:8 row_mask:0xf bank_mask:0xf bound_ctrl:1
	v_add_f32_dpp v26, v26, v26 row_shr:8 row_mask:0xf bank_mask:0xf bound_ctrl:1
	v_add_f32_dpp v27, v27, v27 row_shr:8 row_mask:0xf bank_mask:0xf bound_ctrl:1
	s_nop 1
	v_add_f32_dpp v20, v20, v20 row_shr:1 row_mask:0xf bank_mask:0xf bound_ctrl:1
	v_add_f32_dpp v21, v21, v21 row_shr:1 row_mask:0xf bank_mask:0xf bound_ctrl:1
	v_add_f32_dpp v22, v22, v22 row_shr:1 row_mask:0xf bank_mask:0xf bound_ctrl:1
	v_add_f32_dpp v23, v23, v23 row_shr:1 row_mask:0xf bank_mask:0xf bound_ctrl:1
	v_add_f32_dpp v16, v16, v16 row_shr:1 row_mask:0xf bank_mask:0xf bound_ctrl:1
	v_add_f32_dpp v17, v17, v17 row_shr:1 row_mask:0xf bank_mask:0xf bound_ctrl:1
	v_add_f32_dpp v18, v18, v18 row_shr:1 row_mask:0xf bank_mask:0xf bound_ctrl:1
	v_add_f32_dpp v19, v19, v19 row_shr:1 row_mask:0xf bank_mask:0xf bound_ctrl:1
	v_and_b32_e32 v99, 0xffff0000, v8
	v_lshlrev_b32_e32 v100, 16, v9
	v_and_b32_e32 v101, 0xffff0000, v9
	v_lshlrev_b32_e32 v94, 16, v10
	v_and_b32_e32 v95, 0xffff0000, v10
	v_lshlrev_b32_e32 v96, 16, v11
	v_and_b32_e32 v97, 0xffff0000, v11
	s_nop 1
	v_add_f32_dpp v20, v20, v20 row_shr:2 row_mask:0xf bank_mask:0xf bound_ctrl:1
	v_add_f32_dpp v21, v21, v21 row_shr:2 row_mask:0xf bank_mask:0xf bound_ctrl:1
	v_add_f32_dpp v22, v22, v22 row_shr:2 row_mask:0xf bank_mask:0xf bound_ctrl:1
	v_add_f32_dpp v23, v23, v23 row_shr:2 row_mask:0xf bank_mask:0xf bound_ctrl:1
	v_add_f32_dpp v16, v16, v16 row_shr:2 row_mask:0xf bank_mask:0xf bound_ctrl:1
	v_add_f32_dpp v17, v17, v17 row_shr:2 row_mask:0xf bank_mask:0xf bound_ctrl:1
	v_add_f32_dpp v18, v18, v18 row_shr:2 row_mask:0xf bank_mask:0xf bound_ctrl:1
	v_add_f32_dpp v19, v19, v19 row_shr:2 row_mask:0xf bank_mask:0xf bound_ctrl:1
	s_waitcnt vmcnt(4)
	v_lshlrev_b32_e32 v90, 16, v12
	v_and_b32_e32 v91, 0xffff0000, v12
	v_lshlrev_b32_e32 v92, 16, v13
	v_and_b32_e32 v93, 0xffff0000, v13
	v_lshlrev_b32_e32 v86, 16, v14
	v_and_b32_e32 v87, 0xffff0000, v14
	v_lshlrev_b32_e32 v88, 16, v15
	v_and_b32_e32 v89, 0xffff0000, v15
	v_mov_b32_e32 v9, v95
	v_mov_b32_e32 v12, v98
	v_mov_b32_e32 v11, v97
	v_mov_b32_e32 v14, v100
	v_mov_b32_e32 v8, v94
	v_mov_b32_e32 v10, v96
	v_mov_b32_e32 v13, v99
	v_mov_b32_e32 v15, v101
	s_nop 1
	v_add_f32_dpp v20, v20, v20 row_shr:4 row_mask:0xf bank_mask:0xf bound_ctrl:1
	v_add_f32_dpp v21, v21, v21 row_shr:4 row_mask:0xf bank_mask:0xf bound_ctrl:1
	v_add_f32_dpp v22, v22, v22 row_shr:4 row_mask:0xf bank_mask:0xf bound_ctrl:1
	v_add_f32_dpp v23, v23, v23 row_shr:4 row_mask:0xf bank_mask:0xf bound_ctrl:1
	v_add_f32_dpp v16, v16, v16 row_shr:4 row_mask:0xf bank_mask:0xf bound_ctrl:1
	v_add_f32_dpp v17, v17, v17 row_shr:4 row_mask:0xf bank_mask:0xf bound_ctrl:1
	v_add_f32_dpp v18, v18, v18 row_shr:4 row_mask:0xf bank_mask:0xf bound_ctrl:1
	v_add_f32_dpp v19, v19, v19 row_shr:4 row_mask:0xf bank_mask:0xf bound_ctrl:1
	v_mov_b32_e32 v1, v87
	s_nop 1
	v_add_f32_dpp v20, v20, v20 row_shr:8 row_mask:0xf bank_mask:0xf bound_ctrl:1
	v_add_f32_dpp v21, v21, v21 row_shr:8 row_mask:0xf bank_mask:0xf bound_ctrl:1
	v_add_f32_dpp v22, v22, v22 row_shr:8 row_mask:0xf bank_mask:0xf bound_ctrl:1
	v_add_f32_dpp v23, v23, v23 row_shr:8 row_mask:0xf bank_mask:0xf bound_ctrl:1
	v_add_f32_dpp v16, v16, v16 row_shr:8 row_mask:0xf bank_mask:0xf bound_ctrl:1
	v_add_f32_dpp v17, v17, v17 row_shr:8 row_mask:0xf bank_mask:0xf bound_ctrl:1
	v_add_f32_dpp v18, v18, v18 row_shr:8 row_mask:0xf bank_mask:0xf bound_ctrl:1
	v_add_f32_dpp v19, v19, v19 row_shr:8 row_mask:0xf bank_mask:0xf bound_ctrl:1
	s_nop 1
	v_add_f32_dpp v12, v12, v12 row_shr:1 row_mask:0xf bank_mask:0xf bound_ctrl:1
	v_add_f32_dpp v13, v13, v13 row_shr:1 row_mask:0xf bank_mask:0xf bound_ctrl:1
	v_add_f32_dpp v14, v14, v14 row_shr:1 row_mask:0xf bank_mask:0xf bound_ctrl:1
	v_add_f32_dpp v15, v15, v15 row_shr:1 row_mask:0xf bank_mask:0xf bound_ctrl:1
	v_add_f32_dpp v8, v8, v8 row_shr:1 row_mask:0xf bank_mask:0xf bound_ctrl:1
	v_add_f32_dpp v9, v9, v9 row_shr:1 row_mask:0xf bank_mask:0xf bound_ctrl:1
	v_add_f32_dpp v10, v10, v10 row_shr:1 row_mask:0xf bank_mask:0xf bound_ctrl:1
	v_add_f32_dpp v11, v11, v11 row_shr:1 row_mask:0xf bank_mask:0xf bound_ctrl:1
	v_mov_b32_e32 v4, v90
	s_nop 1
	v_add_f32_dpp v12, v12, v12 row_shr:2 row_mask:0xf bank_mask:0xf bound_ctrl:1
	v_add_f32_dpp v13, v13, v13 row_shr:2 row_mask:0xf bank_mask:0xf bound_ctrl:1
	v_add_f32_dpp v14, v14, v14 row_shr:2 row_mask:0xf bank_mask:0xf bound_ctrl:1
	v_add_f32_dpp v15, v15, v15 row_shr:2 row_mask:0xf bank_mask:0xf bound_ctrl:1
	v_add_f32_dpp v8, v8, v8 row_shr:2 row_mask:0xf bank_mask:0xf bound_ctrl:1
	v_add_f32_dpp v9, v9, v9 row_shr:2 row_mask:0xf bank_mask:0xf bound_ctrl:1
	v_add_f32_dpp v10, v10, v10 row_shr:2 row_mask:0xf bank_mask:0xf bound_ctrl:1
	v_add_f32_dpp v11, v11, v11 row_shr:2 row_mask:0xf bank_mask:0xf bound_ctrl:1
	v_mov_b32_e32 v3, v89
	v_mov_b32_e32 v6, v92
	v_mov_b32_e32 v0, v86
; template <int DIR> __device__ __forceinline__ void h3_dir(unsigned char* lds, const bf16_t* zrow, int h, const bf16_t* slot, f32x4 (&o)[8]) {
;     ...
;         for (int i = 0; i < 32; ++i) kk[i] = 1.0f - __builtin_amdgcn_exp2f(bl[i]);
;         scan16x8<DIR>(bl); scan16x8<DIR>(bl + 8); scan16x8<DIR>(bl + 16); scan16x8<DIR>(bl + 24);
;         float eb[32];
; #pragma unroll
;         for (int i = 0; i < 32; ++i) { eb[i] = __builtin_amdgcn_exp2f(bl[i]); qin[i] *= eb[i]; }
;         if (r == (DIR ? 0 : 15)) {
; #pragma unroll
;             for (int ks = 0; ks < 4; ++ks) { *(f32x4*)(TOT + wid * 128 + 32 * ks + 8 * kq) = (f32x4){bl[8 * ks], bl[8 * ks + 1], bl[8 * ks + 2], bl[8 * ks + 3]}; *(f32x4*)(TOT + wid * 128 + 32 * ks + 8 * kq + 4) = (f32x4){bl[8 * ks + 4], bl[8 * ks + 5], bl[8 * ks + 6], bl[8 * ks + 7]}; }
; #pragma unroll
;             for (int ks = 0; ks < 4; ++ks) { *(f32x4*)(TOTE + wid * 128 + 32 * ks + 8 * kq) = (f32x4){eb[8 * ks], eb[8 * ks + 1], eb[8 * ks + 2], eb[8 * ks + 3]}; *(f32x4*)(TOTE + wid * 128 + 32 * ks + 8 * kq + 4) = (f32x4){eb[8 * ks + 4], eb[8 * ks + 5], eb[8 * ks + 6], eb[8 * ks + 7]}; }
;         }
	v_mov_b32_e32 v2, v88
	v_mov_b32_e32 v5, v91
	v_mov_b32_e32 v7, v93
	s_nop 1
	v_add_f32_dpp v12, v12, v12 row_shr:4 row_mask:0xf bank_mask:0xf bound_ctrl:1
	v_add_f32_dpp v13, v13, v13 row_shr:4 row_mask:0xf bank_mask:0xf bound_ctrl:1
	v_add_f32_dpp v14, v14, v14 row_shr:4 row_mask:0xf bank_mask:0xf bound_ctrl:1
	v_add_f32_dpp v15, v15, v15 row_shr:4 row_mask:0xf bank_mask:0xf bound_ctrl:1
	v_add_f32_dpp v8, v8, v8 row_shr:4 row_mask:0xf bank_mask:0xf bound_ctrl:1
	v_add_f32_dpp v9, v9, v9 row_shr:4 row_mask:0xf bank_mask:0xf bound_ctrl:1
	v_add_f32_dpp v10, v10, v10 row_shr:4 row_mask:0xf bank_mask:0xf bound_ctrl:1
	v_add_f32_dpp v11, v11, v11 row_shr:4 row_mask:0xf bank_mask:0xf bound_ctrl:1
	v_exp_f32_e32 v60, v32
	s_nop 1
	v_add_f32_dpp v12, v12, v12 row_shr:8 row_mask:0xf bank_mask:0xf bound_ctrl:1
	v_add_f32_dpp v13, v13, v13 row_shr:8 row_mask:0xf bank_mask:0xf bound_ctrl:1
	v_add_f32_dpp v14, v14, v14 row_shr:8 row_mask:0xf bank_mask:0xf bound_ctrl:1
	v_add_f32_dpp v15, v15, v15 row_shr:8 row_mask:0xf bank_mask:0xf bound_ctrl:1
	v_add_f32_dpp v8, v8, v8 row_shr:8 row_mask:0xf bank_mask:0xf bound_ctrl:1
	v_add_f32_dpp v9, v9, v9 row_shr:8 row_mask:0xf bank_mask:0xf bound_ctrl:1
	v_add_f32_dpp v10, v10, v10 row_shr:8 row_mask:0xf bank_mask:0xf bound_ctrl:1
	v_add_f32_dpp v11, v11, v11 row_shr:8 row_mask:0xf bank_mask:0xf bound_ctrl:1
	s_nop 1
	v_add_f32_dpp v4, v4, v4 row_shr:1 row_mask:0xf bank_mask:0xf bound_ctrl:1
	v_add_f32_dpp v5, v5, v5 row_shr:1 row_mask:0xf bank_mask:0xf bound_ctrl:1
	v_add_f32_dpp v6, v6, v6 row_shr:1 row_mask:0xf bank_mask:0xf bound_ctrl:1
	v_add_f32_dpp v7, v7, v7 row_shr:1 row_mask:0xf bank_mask:0xf bound_ctrl:1
	v_add_f32_dpp v0, v0, v0 row_shr:1 row_mask:0xf bank_mask:0xf bound_ctrl:1
	v_add_f32_dpp v1, v1, v1 row_shr:1 row_mask:0xf bank_mask:0xf bound_ctrl:1
	v_add_f32_dpp v2, v2, v2 row_shr:1 row_mask:0xf bank_mask:0xf bound_ctrl:1
	v_add_f32_dpp v3, v3, v3 row_shr:1 row_mask:0xf bank_mask:0xf bound_ctrl:1
	v_exp_f32_e32 v61, v33
	s_nop 1
	v_add_f32_dpp v4, v4, v4 row_shr:2 row_mask:0xf bank_mask:0xf bound_ctrl:1
	v_add_f32_dpp v5, v5, v5 row_shr:2 row_mask:0xf bank_mask:0xf bound_ctrl:1
	v_add_f32_dpp v6, v6, v6 row_shr:2 row_mask:0xf bank_mask:0xf bound_ctrl:1
	v_add_f32_dpp v7, v7, v7 row_shr:2 row_mask:0xf bank_mask:0xf bound_ctrl:1
	v_add_f32_dpp v0, v0, v0 row_shr:2 row_mask:0xf bank_mask:0xf bound_ctrl:1
	v_add_f32_dpp v1, v1, v1 row_shr:2 row_mask:0xf bank_mask:0xf bound_ctrl:1
	v_add_f32_dpp v2, v2, v2 row_shr:2 row_mask:0xf bank_mask:0xf bound_ctrl:1
	v_add_f32_dpp v3, v3, v3 row_shr:2 row_mask:0xf bank_mask:0xf bound_ctrl:1
	v_exp_f32_e32 v62, v34
	s_nop 1
	v_add_f32_dpp v4, v4, v4 row_shr:4 row_mask:0xf bank_mask:0xf bound_ctrl:1
	v_add_f32_dpp v5, v5, v5 row_shr:4 row_mask:0xf bank_mask:0xf bound_ctrl:1
	v_add_f32_dpp v6, v6, v6 row_shr:4 row_mask:0xf bank_mask:0xf bound_ctrl:1
	v_add_f32_dpp v7, v7, v7 row_shr:4 row_mask:0xf bank_mask:0xf bound_ctrl:1
	v_add_f32_dpp v0, v0, v0 row_shr:4 row_mask:0xf bank_mask:0xf bound_ctrl:1
	v_add_f32_dpp v1, v1, v1 row_shr:4 row_mask:0xf bank_mask:0xf bound_ctrl:1
	v_add_f32_dpp v2, v2, v2 row_shr:4 row_mask:0xf bank_mask:0xf bound_ctrl:1
	v_add_f32_dpp v3, v3, v3 row_shr:4 row_mask:0xf bank_mask:0xf bound_ctrl:1
	v_exp_f32_e32 v63, v35
	v_exp_f32_e32 v56, v24
	v_exp_f32_e32 v57, v25
	v_exp_f32_e32 v58, v26
	v_exp_f32_e32 v59, v27
	v_exp_f32_e32 v72, v20
	v_exp_f32_e32 v73, v21
	v_exp_f32_e32 v74, v22
	v_exp_f32_e32 v75, v23
	v_exp_f32_e32 v68, v16
	v_exp_f32_e32 v69, v17
	v_exp_f32_e32 v70, v18
	v_exp_f32_e32 v71, v19
	v_exp_f32_e32 v76, v12
	v_exp_f32_e32 v77, v13
	v_exp_f32_e32 v78, v14
	v_exp_f32_e32 v79, v15
	v_exp_f32_e32 v40, v8
	v_exp_f32_e32 v41, v9
	v_exp_f32_e32 v42, v10
	v_exp_f32_e32 v43, v11
	s_nop 1
	v_add_f32_dpp v4, v4, v4 row_shr:8 row_mask:0xf bank_mask:0xf bound_ctrl:1
	v_add_f32_dpp v5, v5, v5 row_shr:8 row_mask:0xf bank_mask:0xf bound_ctrl:1
	v_add_f32_dpp v6, v6, v6 row_shr:8 row_mask:0xf bank_mask:0xf bound_ctrl:1
	v_add_f32_dpp v7, v7, v7 row_shr:8 row_mask:0xf bank_mask:0xf bound_ctrl:1
	v_add_f32_dpp v0, v0, v0 row_shr:8 row_mask:0xf bank_mask:0xf bound_ctrl:1
	v_add_f32_dpp v1, v1, v1 row_shr:8 row_mask:0xf bank_mask:0xf bound_ctrl:1
	v_add_f32_dpp v2, v2, v2 row_shr:8 row_mask:0xf bank_mask:0xf bound_ctrl:1
	v_add_f32_dpp v3, v3, v3 row_shr:8 row_mask:0xf bank_mask:0xf bound_ctrl:1
	s_nop 0
	v_exp_f32_e32 v36, v4
	v_exp_f32_e32 v37, v5
	v_exp_f32_e32 v38, v6
	v_exp_f32_e32 v39, v7
	v_exp_f32_e32 v28, v0
	v_exp_f32_e32 v29, v1
	v_exp_f32_e32 v30, v2
	v_exp_f32_e32 v31, v3
	s_and_saveexec_b64 s[6:7], vcc
	s_cbranch_execz .LBB0_2611
	s_add_i32 s5, s37, 0
	v_lshl_add_u32 v153, v82, 2, s5
	ds_write_b128 v153, v[32:35]
	ds_write_b128 v153, v[24:27] offset:16
	ds_write_b128 v153, v[20:23] offset:128
	ds_write_b128 v153, v[16:19] offset:144
	ds_write_b128 v153, v[12:15] offset:256
	ds_write_b128 v153, v[8:11] offset:272
	ds_write_b128 v153, v[4:7] offset:384
	ds_write_b128 v153, v[0:3] offset:400
	ds_write_b128 v153, v[60:63] offset:4096
	ds_write_b128 v153, v[56:59] offset:4112
	ds_write_b128 v153, v[72:75] offset:4224
	ds_write_b128 v153, v[68:71] offset:4240
	ds_write_b128 v153, v[76:79] offset:4352
	ds_write_b128 v153, v[40:43] offset:4368
	ds_write_b128 v153, v[36:39] offset:4480
	ds_write_b128 v153, v[28:31] offset:4496

; __device__ __forceinline__ bf16x8 pk8(const float* v) { u32x4 w; w.x = cvt_pk_bf16(v[0], v[1]); w.y = cvt_pk_bf16(v[2], v[3]); w.z = cvt_pk_bf16(v[4], v[5]); w.w = cvt_pk_bf16(v[6], v[7]); return __builtin_bit_cast(bf16x8, w); }
; #define WAVE_LDS_FENCE() do { asm volatile("s_waitcnt lgkmcnt(0)" ::: "memory"); __builtin_amdgcn_wave_barrier(); } while (0)
; template <int DIR> __device__ __forceinline__ void h3_dir(unsigned char* lds, const bf16_t* zrow, int h, const bf16_t* slot, f32x4 (&o)[8]) {
;     ...
; #pragma unroll
;     for (int i = 0; i < 32; ++i) qin[i] *= run[i];
;     WAVE_LDS_FENCE();
; #pragma unroll
;     for (int ks = 0; ks < 4; ++ks) {
;         const bf16x8 aq = pk8(qin + 8 * ks), ap = *(const bf16x8*)(Pw + r * HP + 32 * ks + 8 * kq);
; #pragma unroll
;         for (int nt = 0; nt < 8; ++nt) {
;             o[nt] = __builtin_amdgcn_mfma_f32_16x16x32_bf16(aq, *(const bf16x8*)(ST + (16 * nt + r) * HP + 32 * ks + 8 * kq), o[nt], 0, 0, 0);
;             o[nt] = __builtin_amdgcn_mfma_f32_16x16x32_bf16(ap, *(const bf16x8*)(VT + (16 * nt + r) * HP + 32 * ks + 8 * kq), o[nt], 0, 0, 0);
;         }
;     }
.LBB0_2619:
	v_mul_u32_u24_e32 v45, 0x88, v83
	v_lshlrev_b32_e32 v45, 1, v45
	v_lshlrev_b32_e32 v44, 1, v82
	v_add_u32_e32 v110, v40, v45
	v_mul_u32_u24_e32 v40, 0x110, v83
	v_mul_f32_e32 v24, v60, v24
	v_mul_f32_e32 v25, v61, v25
	v_mul_f32_e32 v26, v62, v26
	v_mul_f32_e32 v27, v63, v27
	v_mul_f32_e32 v28, v64, v28
	v_mul_f32_e32 v29, v65, v29
	v_mul_f32_e32 v30, v66, v30
	v_mul_f32_e32 v31, v59, v31
	v_add3_u32 v102, s6, v40, v44
	s_waitcnt lgkmcnt(0)
	v_cvt_pk_bf16_f32 v24, v24, v25
	v_cvt_pk_bf16_f32 v25, v26, v27
	v_cvt_pk_bf16_f32 v26, v28, v29
	v_cvt_pk_bf16_f32 v27, v30, v31
	ds_read_b128 v[28:31], v110 offset:43008
	ds_read_b128 v[60:63], v102
	s_add_i32 s35, 0, 0x13000
	v_add3_u32 v111, s35, v44, v45
	ds_read_b128 v[64:67], v111
	s_waitcnt lgkmcnt(2)
	v_mfma_f32_16x16x32_bf16 v[28:31], v[24:27], v[28:31], 0
	v_add_u32_e32 v40, 0xa800, v110
	ds_read_b128 v[68:71], v40 offset:30464
	v_mul_f32_e32 v45, v54, v22
	s_waitcnt lgkmcnt(1)
	v_mfma_f32_16x16x32_bf16 v[28:31], v[60:63], v[64:67], v[28:31]
	ds_read_b128 v[64:67], v110 offset:47360
	ds_read_b128 v[72:75], v110 offset:51712
	ds_read_b128 v[76:79], v111 offset:4352
	ds_read_b128 v[82:85], v111 offset:8704
	v_mul_f32_e32 v54, v55, v23
	s_waitcnt lgkmcnt(3)
	v_mfma_f32_16x16x32_bf16 v[64:67], v[24:27], v[64:67], 0
	v_mul_f32_e32 v55, v56, v16
	v_mul_f32_e32 v51, v51, v17
	v_mul_f32_e32 v56, v52, v18
	s_waitcnt lgkmcnt(2)
	v_mfma_f32_16x16x32_bf16 v[72:75], v[24:27], v[72:75], 0
	v_mul_f32_e32 v44, v58, v21
	v_add_u32_e32 v116, 0xa8c0, v110
	v_and_b32_e32 v151, 63, v254
	v_or_b32_e32 v151, s62, v151
	s_waitcnt lgkmcnt(1)
	v_mfma_f32_16x16x32_bf16 v[64:67], v[60:63], v[76:79], v[64:67]
	s_waitcnt lgkmcnt(0)
	v_mfma_f32_16x16x32_bf16 v[72:75], v[60:63], v[82:85], v[72:75]
	ds_read_b128 v[76:79], v110 offset:56064
	ds_read_b128 v[82:85], v110 offset:60416
	ds_read_b128 v[86:89], v111 offset:13056
	ds_read_b128 v[90:93], v111 offset:17408
	s_waitcnt lgkmcnt(3)
	v_mfma_f32_16x16x32_bf16 v[76:79], v[24:27], v[76:79], 0
	s_waitcnt lgkmcnt(2)
	v_mfma_f32_16x16x32_bf16 v[82:85], v[24:27], v[82:85], 0
	s_waitcnt lgkmcnt(1)
	v_mfma_f32_16x16x32_bf16 v[76:79], v[60:63], v[86:89], v[76:79]
	s_waitcnt lgkmcnt(0)
	v_mfma_f32_16x16x32_bf16 v[82:85], v[60:63], v[90:93], v[82:85]
	ds_read_b128 v[86:89], v110 offset:64768
	ds_read_b128 v[90:93], v40 offset:26112
	ds_read_b128 v[94:97], v111 offset:21760
	ds_read_b128 v[98:101], v111 offset:26112
	v_mul_f32_e32 v40, v57, v20
	s_waitcnt lgkmcnt(3)
	v_mfma_f32_16x16x32_bf16 v[86:89], v[24:27], v[86:89], 0
	v_mul_f32_e32 v57, v53, v19
	s_waitcnt lgkmcnt(2)
	v_mfma_f32_16x16x32_bf16 v[90:93], v[24:27], v[90:93], 0
	v_mfma_f32_16x16x32_bf16 v[16:19], v[24:27], v[68:71], 0
	ds_read_b128 v[24:27], v111 offset:30464
	v_cvt_pk_bf16_f32 v52, v40, v44
	v_cvt_pk_bf16_f32 v53, v45, v54
	v_cvt_pk_bf16_f32 v54, v55, v51
	v_cvt_pk_bf16_f32 v55, v56, v57
	ds_read_b128 v[56:59], v110 offset:43072
	s_waitcnt lgkmcnt(1)
	v_mfma_f32_16x16x32_bf16 v[16:19], v[60:63], v[24:27], v[16:19]
	ds_read_b128 v[24:27], v102 offset:64
	v_mul_f32_e32 v40, v49, v8
	v_mfma_f32_16x16x32_bf16 v[86:89], v[60:63], v[94:97], v[86:89]
	v_mul_f32_e32 v94, v50, v9
	v_mfma_f32_16x16x32_bf16 v[20:23], v[60:63], v[98:101], v[90:93]
	s_waitcnt lgkmcnt(1)
	v_mfma_f32_16x16x32_bf16 v[28:31], v[52:55], v[56:59], v[28:31]
	ds_read_b128 v[56:59], v111 offset:64
	ds_read_b128 v[60:63], v110 offset:64832
	s_waitcnt lgkmcnt(1)
	v_mfma_f32_16x16x32_bf16 v[28:31], v[24:27], v[56:59], v[28:31]
	ds_read_b128 v[56:59], v110 offset:47424
	ds_read_b128 v[68:71], v110 offset:51776
	s_waitcnt lgkmcnt(1)
	v_mfma_f32_16x16x32_bf16 v[56:59], v[52:55], v[56:59], v[64:67]
	s_nop 2
	ds_read_b128 v[64:67], v111 offset:4416
	ds_read_b128 v[90:93], v111 offset:8768
	s_waitcnt lgkmcnt(1)
	v_mfma_f32_16x16x32_bf16 v[56:59], v[24:27], v[64:67], v[56:59]
	v_mfma_f32_16x16x32_bf16 v[64:67], v[52:55], v[68:71], v[72:75]
	s_waitcnt lgkmcnt(0)
	v_mfma_f32_16x16x32_bf16 v[64:67], v[24:27], v[90:93], v[64:67]
	ds_read_b128 v[68:71], v110 offset:56128
	ds_read_b128 v[72:75], v111 offset:13120
	ds_read_b128 v[90:93], v110 offset:60480
	s_waitcnt lgkmcnt(2)
	v_mfma_f32_16x16x32_bf16 v[68:71], v[52:55], v[68:71], v[76:79]
	s_nop 2
	ds_read_b128 v[76:79], v111 offset:17472
	s_waitcnt lgkmcnt(2)
	v_mfma_f32_16x16x32_bf16 v[68:71], v[24:27], v[72:75], v[68:71]
	v_mul_f32_e32 v72, v46, v10
	v_mul_f32_e32 v73, v47, v11
	v_mul_f32_e32 v74, v48, v4
	s_waitcnt lgkmcnt(1)
	v_mfma_f32_16x16x32_bf16 v[8:11], v[52:55], v[90:93], v[82:85]
	v_mul_f32_e32 v90, v32, v12
	v_add_u32_e32 v32, 0xa840, v110
	v_mul_f32_e32 v75, v41, v5
	v_mul_f32_e32 v82, v42, v6
	v_mul_f32_e32 v83, v34, v7
	s_waitcnt lgkmcnt(0)
	v_mfma_f32_16x16x32_bf16 v[4:7], v[24:27], v[76:79], v[8:11]
	v_mul_f32_e32 v91, v33, v13
	v_mul_f32_e32 v92, v43, v1
	v_mul_f32_e32 v93, v38, v2
	ds_read_b128 v[8:11], v111 offset:21824
	v_mfma_f32_16x16x32_bf16 v[44:47], v[52:55], v[60:63], v[86:89]
	ds_read_b128 v[48:51], v32 offset:26112
	ds_read_b128 v[60:63], v111 offset:26176
	s_nop 0
	v_mul_f32_e32 v87, v36, v14
	v_mul_f32_e32 v88, v37, v15
	ds_read_b128 v[12:15], v111 offset:30528
	v_mul_f32_e32 v89, v35, v0
	ds_read_b128 v[32:35], v32 offset:30464
	s_waitcnt lgkmcnt(4)
	v_mfma_f32_16x16x32_bf16 v[8:11], v[24:27], v[8:11], v[44:47]
	v_cvt_pk_bf16_f32 v40, v40, v94
	v_cvt_pk_bf16_f32 v41, v72, v73
	v_cvt_pk_bf16_f32 v42, v74, v75
	s_waitcnt lgkmcnt(0)
; __device__ __forceinline__ float bf_lo(unsigned w) { return __uint_as_float(w << 16); }
; __device__ __forceinline__ float bf_hi(unsigned w) { return __uint_as_float(w & 0xffff0000u); }
; __device__ __forceinline__ bf16x8 pk8(const float* v) { u32x4 w; w.x = cvt_pk_bf16(v[0], v[1]); w.y = cvt_pk_bf16(v[2], v[3]); w.z = cvt_pk_bf16(v[4], v[5]); w.w = cvt_pk_bf16(v[6], v[7]); return __builtin_bit_cast(bf16x8, w); }
; __device__ __forceinline__ void load32(const bf16_t* p, float (&v)[32]) {
; #pragma unroll
;     for (int ks = 0; ks < 4; ++ks) { const u32x4 w = *(const u32x4*)(p + 32 * ks);
;         v[8 * ks + 0] = bf_lo(w.x); v[8 * ks + 1] = bf_hi(w.x); v[8 * ks + 2] = bf_lo(w.y); v[8 * ks + 3] = bf_hi(w.y); v[8 * ks + 4] = bf_lo(w.z); v[8 * ks + 5] = bf_hi(w.z); v[8 * ks + 6] = bf_lo(w.w); v[8 * ks + 7] = bf_hi(w.w); }
; template <int DIR> __device__ __forceinline__ void h3_dir(unsigned char* lds, const bf16_t* zrow, int h, const bf16_t* slot, f32x4 (&o)[8]) {
;     ...
;     for (int ks = 0; ks < 4; ++ks) {
;         const bf16x8 aq = pk8(qin + 8 * ks), ap = *(const bf16x8*)(Pw + r * HP + 32 * ks + 8 * kq);
; #pragma unroll
;         for (int nt = 0; nt < 8; ++nt) {
;             o[nt] = __builtin_amdgcn_mfma_f32_16x16x32_bf16(aq, *(const bf16x8*)(ST + (16 * nt + r) * HP + 32 * ks + 8 * kq), o[nt], 0, 0, 0);
;             o[nt] = __builtin_amdgcn_mfma_f32_16x16x32_bf16(ap, *(const bf16x8*)(VT + (16 * nt + r) * HP + 32 * ks + 8 * kq), o[nt], 0, 0, 0);
;         }
;     }
;     __syncthreads();
	v_mfma_f32_16x16x32_bf16 v[16:19], v[52:55], v[32:35], v[16:19]
	v_cvt_pk_bf16_f32 v43, v82, v83
	ds_read_b128 v[32:35], v102 offset:128
	ds_read_b128 v[44:47], v110 offset:43136
	v_mul_f32_e32 v94, v39, v3
	v_mfma_f32_16x16x32_bf16 v[20:23], v[52:55], v[48:51], v[20:23]
	ds_read_b128 v[0:3], v111 offset:128
	v_add_u32_e32 v82, 0xa880, v110
	v_mfma_f32_16x16x32_bf16 v[20:23], v[24:27], v[60:63], v[20:23]
	v_mfma_f32_16x16x32_bf16 v[12:15], v[24:27], v[12:15], v[16:19]
	s_waitcnt lgkmcnt(1)
	v_mfma_f32_16x16x32_bf16 v[16:19], v[40:43], v[44:47], v[28:31]
	ds_read_b128 v[24:27], v110 offset:47488
	s_nop 1
	ds_read_b128 v[28:31], v110 offset:64896
	s_waitcnt lgkmcnt(2)
	v_mfma_f32_16x16x32_bf16 v[0:3], v[32:35], v[0:3], v[16:19]
	s_nop 2
	ds_read_b128 v[16:19], v110 offset:51840
	ds_read_b128 v[36:39], v111 offset:4480
	ds_read_b128 v[44:47], v111 offset:8832
	s_waitcnt lgkmcnt(4)
	v_mfma_f32_16x16x32_bf16 v[24:27], v[40:43], v[24:27], v[56:59]
	ds_read_b128 v[48:51], v110 offset:56192
	ds_read_b128 v[52:55], v110 offset:60544
	s_nop 0
	ds_read_b128 v[56:59], v111 offset:13184
	ds_read_b128 v[60:63], v111 offset:17536
	s_waitcnt lgkmcnt(2)
	v_mfma_f32_16x16x32_bf16 v[4:7], v[40:43], v[52:55], v[4:7]
	v_mfma_f32_16x16x32_bf16 v[16:19], v[40:43], v[16:19], v[64:67]
	v_mfma_f32_16x16x32_bf16 v[36:39], v[32:35], v[36:39], v[24:27]
	s_nop 2
	ds_read_b128 v[24:27], v111 offset:21888
	ds_read_b128 v[72:75], v111 offset:26240
	ds_read_b128 v[76:79], v82 offset:30464
	ds_read_b128 v[64:67], v82 offset:26112
	ds_read_b128 v[82:85], v111 offset:30592
	v_cvt_pk_bf16_f32 v86, v90, v91
	s_waitcnt lgkmcnt(5)
	v_mfma_f32_16x16x32_bf16 v[60:63], v[32:35], v[60:63], v[4:7]
	v_cvt_pk_bf16_f32 v87, v87, v88
	v_cvt_pk_bf16_f32 v88, v89, v92
	v_cvt_pk_bf16_f32 v89, v93, v94
	v_mfma_f32_16x16x32_bf16 v[4:7], v[40:43], v[28:31], v[8:11]
	v_mfma_f32_16x16x32_bf16 v[16:19], v[32:35], v[44:47], v[16:19]
	v_mfma_f32_16x16x32_bf16 v[44:47], v[40:43], v[48:51], v[68:71]
	ds_read_b128 v[48:51], v102 offset:192
	s_nop 1
	ds_read_b128 v[68:71], v110 offset:43200
	ds_read_b128 v[90:93], v110 offset:47552
	ds_read_b128 v[94:97], v110 offset:51904
	s_waitcnt lgkmcnt(8)
	v_mfma_f32_16x16x32_bf16 v[208:211], v[32:35], v[24:27], v[4:7]
	s_waitcnt lgkmcnt(5)
	v_mfma_f32_16x16x32_bf16 v[4:7], v[40:43], v[64:67], v[20:23]
	v_mfma_f32_16x16x32_bf16 v[44:47], v[32:35], v[56:59], v[44:47]
	ds_read_b128 v[56:59], v111 offset:4544
	ds_read_b128 v[98:101], v111 offset:8896
	ds_read_b128 v[102:105], v110 offset:56256
	ds_read_b128 v[106:109], v110 offset:60608
	ds_read_b128 v[52:55], v111 offset:13248
	ds_read_b128 v[152:155], v111 offset:17600
	ds_read_b128 v[156:159], v111 offset:192
	ds_read_b128 v[188:191], v110 offset:64960
	ds_read_b128 v[192:195], v111 offset:21952
	ds_read_b128 v[196:199], v111 offset:26304
	ds_read_b128 v[200:203], v116 offset:30464
	ds_read_b128 v[28:31], v116 offset:26112
	ds_read_b128 v[204:207], v111 offset:30656
	s_waitcnt lgkmcnt(0)
	s_barrier
	v_mfma_f32_16x16x32_bf16 v[20:23], v[32:35], v[72:75], v[4:7]
	v_bfe_u32 v150, v151, 4, 2
	v_lshlrev_b32_e32 v116, 4, v150
	v_lshl_add_u64 v[80:81], v[80:81], 0, v[116:117]
	v_add_co_u32_e32 v4, vcc, s28, v80
	v_lshl_add_u64 v[24:25], v[80:81], 0, s[14:15]
	s_nop 0
	v_addc_co_u32_e32 v5, vcc, 0, v81, vcc
	s_waitcnt vmcnt(0)
	v_mov_b32_e32 v4, v212
	v_mov_b32_e32 v5, v213
	v_mov_b32_e32 v6, v214
	v_mov_b32_e32 v7, v215
	v_mfma_f32_16x16x32_bf16 v[8:11], v[40:43], v[76:79], v[12:15]
	v_mov_b32_e32 v40, v220
	v_mov_b32_e32 v41, v221
	v_mov_b32_e32 v42, v222
	v_mov_b32_e32 v43, v223
	v_mov_b32_e32 v64, v224
	v_mov_b32_e32 v65, v225
	v_mov_b32_e32 v66, v226
	v_mov_b32_e32 v67, v227
	v_readfirstlane_b32 s3, v151
	v_mov_b32_e32 v12, v216
	v_mov_b32_e32 v13, v217
	v_mov_b32_e32 v14, v218
	v_mov_b32_e32 v15, v219
	v_mfma_f32_16x16x32_bf16 v[32:35], v[32:35], v[82:85], v[8:11]
	s_ashr_i32 s36, s3, 6
	v_and_b32_e32 v149, 15, v151
	v_lshlrev_b32_e32 v148, 3, v150
	v_mfma_f32_16x16x32_bf16 v[8:11], v[86:89], v[102:105], v[44:47]
	v_cmp_eq_u32_e32 vcc, 0, v149
	s_lshl_b32 s3, s36, 9
	s_waitcnt vmcnt(3)
	v_lshlrev_b32_e32 v182, 16, v4
	v_and_b32_e32 v181, 0xffff0000, v4
	v_lshlrev_b32_e32 v180, 16, v5
	v_and_b32_e32 v179, 0xffff0000, v5
	v_lshlrev_b32_e32 v177, 16, v6
	v_and_b32_e32 v178, 0xffff0000, v6
	v_lshlrev_b32_e32 v176, 16, v7
	v_and_b32_e32 v174, 0xffff0000, v7
	v_mfma_f32_16x16x32_bf16 v[4:7], v[86:89], v[94:97], v[16:19]
	s_waitcnt vmcnt(0)
; __device__ __forceinline__ float bf_lo(unsigned w) { return __uint_as_float(w << 16); }
; __device__ __forceinline__ float bf_hi(unsigned w) { return __uint_as_float(w & 0xffff0000u); }
; __device__ __forceinline__ bf16x8 pk8(const float* v) { u32x4 w; w.x = cvt_pk_bf16(v[0], v[1]); w.y = cvt_pk_bf16(v[2], v[3]); w.z = cvt_pk_bf16(v[4], v[5]); w.w = cvt_pk_bf16(v[6], v[7]); return __builtin_bit_cast(bf16x8, w); }
; template <int DIR> __device__ __forceinline__ void scan16x8(float* v) {
;     if (DIR == 0) { SCAN_STEP("row_shr:", 1); SCAN_STEP("row_shr:", 2); SCAN_STEP("row_shr:", 4); SCAN_STEP("row_shr:", 8); }
;     else          { SCAN_STEP("row_shl:", 1); SCAN_STEP("row_shl:", 2); SCAN_STEP("row_shl:", 4); SCAN_STEP("row_shl:", 8); }
; }
; __device__ __forceinline__ void load32(const bf16_t* p, float (&v)[32]) {
; #pragma unroll
;     for (int ks = 0; ks < 4; ++ks) { const u32x4 w = *(const u32x4*)(p + 32 * ks);
;         v[8 * ks + 0] = bf_lo(w.x); v[8 * ks + 1] = bf_hi(w.x); v[8 * ks + 2] = bf_lo(w.y); v[8 * ks + 3] = bf_hi(w.y); v[8 * ks + 4] = bf_lo(w.z); v[8 * ks + 5] = bf_hi(w.z); v[8 * ks + 6] = bf_lo(w.w); v[8 * ks + 7] = bf_hi(w.w); }
; template <int DIR> __device__ __forceinline__ void h3_dir(unsigned char* lds, const bf16_t* zrow, int h, const bf16_t* slot, f32x4 (&o)[8]) {
;     ...
;     for (int ks = 0; ks < 4; ++ks) {
;         const bf16x8 aq = pk8(qin + 8 * ks), ap = *(const bf16x8*)(Pw + r * HP + 32 * ks + 8 * kq);
; #pragma unroll
;         for (int nt = 0; nt < 8; ++nt) {
;             o[nt] = __builtin_amdgcn_mfma_f32_16x16x32_bf16(aq, *(const bf16x8*)(ST + (16 * nt + r) * HP + 32 * ks + 8 * kq), o[nt], 0, 0, 0);
;             o[nt] = __builtin_amdgcn_mfma_f32_16x16x32_bf16(ap, *(const bf16x8*)(VT + (16 * nt + r) * HP + 32 * ks + 8 * kq), o[nt], 0, 0, 0);
;         }
;     }
	v_lshlrev_b32_e32 v175, 16, v12
	v_and_b32_e32 v173, 0xffff0000, v12
	v_lshlrev_b32_e32 v116, 16, v13
	v_mfma_f32_16x16x32_bf16 v[4:7], v[48:51], v[98:101], v[4:7]
	v_and_b32_e32 v172, 0xffff0000, v13
	v_lshlrev_b32_e32 v168, 16, v14
	v_and_b32_e32 v169, 0xffff0000, v14
	v_lshlrev_b32_e32 v170, 16, v15
	v_and_b32_e32 v171, 0xffff0000, v15
	v_mfma_f32_16x16x32_bf16 v[12:15], v[86:89], v[106:109], v[60:63]
	v_mov_b32_e32 v108, v230
	v_mov_b32_e32 v109, v231
	v_mov_b32_e32 v110, v232
	v_mov_b32_e32 v111, v233
	v_mov_b32_e32 v104, v234
	v_mov_b32_e32 v105, v235
	v_mov_b32_e32 v106, v236
	v_mov_b32_e32 v107, v237
	v_mov_b32_e32 v100, v238
	v_mov_b32_e32 v101, v239
	v_mov_b32_e32 v102, v240
	v_mov_b32_e32 v103, v241
	v_mov_b32_e32 v96, v242
	v_mov_b32_e32 v97, v243
	v_mov_b32_e32 v98, v244
	v_mov_b32_e32 v99, v245
	v_mov_b32_e32 v61, v178
	v_mov_b32_e32 v63, v174
	v_mfma_f32_16x16x32_bf16 v[0:3], v[86:89], v[68:71], v[0:3]
	v_mov_b32_e32 v60, v177
	v_mov_b32_e32 v62, v176
	v_lshlrev_b32_e32 v164, 16, v40
	v_mfma_f32_16x16x32_bf16 v[24:27], v[48:51], v[156:159], v[0:3]
	v_lshlrev_b32_e32 v156, 16, v64
	v_and_b32_e32 v157, 0xffff0000, v64
	v_lshlrev_b32_e32 v158, 16, v65
	v_mfma_f32_16x16x32_bf16 v[0:3], v[86:89], v[90:93], v[36:39]
	v_and_b32_e32 v159, 0xffff0000, v65
	v_mov_b32_e32 v64, v182
	v_mov_b32_e32 v65, v181
	v_mfma_f32_16x16x32_bf16 v[16:19], v[86:89], v[188:191], v[208:211]
	v_and_b32_e32 v165, 0xffff0000, v40
	v_lshlrev_b32_e32 v166, 16, v41
	v_and_b32_e32 v167, 0xffff0000, v41
	v_mfma_f32_16x16x32_bf16 v[20:23], v[86:89], v[28:31], v[20:23]
	v_lshlrev_b32_e32 v160, 16, v42
	v_and_b32_e32 v161, 0xffff0000, v42
	v_lshlrev_b32_e32 v162, 16, v43
	v_mfma_f32_16x16x32_bf16 v[28:31], v[86:89], v[200:203], v[32:35]
	v_and_b32_e32 v163, 0xffff0000, v43
	v_mov_b32_e32 v47, v167
	v_mov_b32_e32 v41, v161
	v_mfma_f32_16x16x32_bf16 v[12:15], v[48:51], v[152:155], v[12:15]
	v_lshlrev_b32_e32 v152, 16, v66
	v_and_b32_e32 v153, 0xffff0000, v66
	v_lshlrev_b32_e32 v154, 16, v67
	v_and_b32_e32 v155, 0xffff0000, v67
	v_mov_b32_e32 v67, v179
	v_mov_b32_e32 v66, v180
	s_nop 1
	v_add_f32_dpp v64, v64, v64 row_shl:1 row_mask:0xf bank_mask:0xf bound_ctrl:1
	v_add_f32_dpp v65, v65, v65 row_shl:1 row_mask:0xf bank_mask:0xf bound_ctrl:1
	v_add_f32_dpp v66, v66, v66 row_shl:1 row_mask:0xf bank_mask:0xf bound_ctrl:1
	v_add_f32_dpp v67, v67, v67 row_shl:1 row_mask:0xf bank_mask:0xf bound_ctrl:1
	v_add_f32_dpp v60, v60, v60 row_shl:1 row_mask:0xf bank_mask:0xf bound_ctrl:1
	v_add_f32_dpp v61, v61, v61 row_shl:1 row_mask:0xf bank_mask:0xf bound_ctrl:1
	v_add_f32_dpp v62, v62, v62 row_shl:1 row_mask:0xf bank_mask:0xf bound_ctrl:1
	v_add_f32_dpp v63, v63, v63 row_shl:1 row_mask:0xf bank_mask:0xf bound_ctrl:1
	v_mfma_f32_16x16x32_bf16 v[0:3], v[48:51], v[56:59], v[0:3]
	s_nop 1
	v_add_f32_dpp v64, v64, v64 row_shl:2 row_mask:0xf bank_mask:0xf bound_ctrl:1
	v_add_f32_dpp v65, v65, v65 row_shl:2 row_mask:0xf bank_mask:0xf bound_ctrl:1
	v_add_f32_dpp v66, v66, v66 row_shl:2 row_mask:0xf bank_mask:0xf bound_ctrl:1
	v_add_f32_dpp v67, v67, v67 row_shl:2 row_mask:0xf bank_mask:0xf bound_ctrl:1
	v_add_f32_dpp v60, v60, v60 row_shl:2 row_mask:0xf bank_mask:0xf bound_ctrl:1
	v_add_f32_dpp v61, v61, v61 row_shl:2 row_mask:0xf bank_mask:0xf bound_ctrl:1
	v_add_f32_dpp v62, v62, v62 row_shl:2 row_mask:0xf bank_mask:0xf bound_ctrl:1
	v_add_f32_dpp v63, v63, v63 row_shl:2 row_mask:0xf bank_mask:0xf bound_ctrl:1
	v_mov_b32_e32 v44, v164
	s_nop 1
	v_add_f32_dpp v64, v64, v64 row_shl:4 row_mask:0xf bank_mask:0xf bound_ctrl:1
	v_add_f32_dpp v65, v65, v65 row_shl:4 row_mask:0xf bank_mask:0xf bound_ctrl:1
	v_add_f32_dpp v66, v66, v66 row_shl:4 row_mask:0xf bank_mask:0xf bound_ctrl:1
	v_add_f32_dpp v67, v67, v67 row_shl:4 row_mask:0xf bank_mask:0xf bound_ctrl:1
	v_add_f32_dpp v60, v60, v60 row_shl:4 row_mask:0xf bank_mask:0xf bound_ctrl:1
	v_add_f32_dpp v61, v61, v61 row_shl:4 row_mask:0xf bank_mask:0xf bound_ctrl:1
	v_add_f32_dpp v62, v62, v62 row_shl:4 row_mask:0xf bank_mask:0xf bound_ctrl:1
	v_add_f32_dpp v63, v63, v63 row_shl:4 row_mask:0xf bank_mask:0xf bound_ctrl:1
	v_mfma_f32_16x16x32_bf16 v[8:11], v[48:51], v[52:55], v[8:11]
	v_mov_b32_e32 v55, v172
	v_mov_b32_e32 v52, v175
	v_mov_b32_e32 v54, v116
	v_mfma_f32_16x16x32_bf16 v[16:19], v[48:51], v[192:195], v[16:19]
	v_mov_b32_e32 v53, v173
	s_nop 1
	v_add_f32_dpp v64, v64, v64 row_shl:8 row_mask:0xf bank_mask:0xf bound_ctrl:1
	v_add_f32_dpp v65, v65, v65 row_shl:8 row_mask:0xf bank_mask:0xf bound_ctrl:1
	v_add_f32_dpp v66, v66, v66 row_shl:8 row_mask:0xf bank_mask:0xf bound_ctrl:1
	v_add_f32_dpp v67, v67, v67 row_shl:8 row_mask:0xf bank_mask:0xf bound_ctrl:1
	v_add_f32_dpp v60, v60, v60 row_shl:8 row_mask:0xf bank_mask:0xf bound_ctrl:1
	v_add_f32_dpp v61, v61, v61 row_shl:8 row_mask:0xf bank_mask:0xf bound_ctrl:1
	v_add_f32_dpp v62, v62, v62 row_shl:8 row_mask:0xf bank_mask:0xf bound_ctrl:1
	v_add_f32_dpp v63, v63, v63 row_shl:8 row_mask:0xf bank_mask:0xf bound_ctrl:1
	v_mov_b32_e32 v43, v163
	v_mfma_f32_16x16x32_bf16 v[20:23], v[48:51], v[196:199], v[20:23]
	v_mov_b32_e32 v46, v166
	v_mov_b32_e32 v40, v160
	v_mov_b32_e32 v42, v162
	v_mfma_f32_16x16x32_bf16 v[28:31], v[48:51], v[204:207], v[28:31]
	v_mov_b32_e32 v49, v169
	v_mov_b32_e32 v51, v171
	v_mov_b32_e32 v48, v168
	v_mov_b32_e32 v50, v170
	s_nop 1
	v_add_f32_dpp v52, v52, v52 row_shl:1 row_mask:0xf bank_mask:0xf bound_ctrl:1
	v_add_f32_dpp v53, v53, v53 row_shl:1 row_mask:0xf bank_mask:0xf bound_ctrl:1
	v_add_f32_dpp v54, v54, v54 row_shl:1 row_mask:0xf bank_mask:0xf bound_ctrl:1
	v_add_f32_dpp v55, v55, v55 row_shl:1 row_mask:0xf bank_mask:0xf bound_ctrl:1
; template <int DIR> __device__ __forceinline__ void scan16x8(float* v) {
;     if (DIR == 0) { SCAN_STEP("row_shr:", 1); SCAN_STEP("row_shr:", 2); SCAN_STEP("row_shr:", 4); SCAN_STEP("row_shr:", 8); }
;     else          { SCAN_STEP("row_shl:", 1); SCAN_STEP("row_shl:", 2); SCAN_STEP("row_shl:", 4); SCAN_STEP("row_shl:", 8); }
; }
	v_add_f32_dpp v48, v48, v48 row_shl:1 row_mask:0xf bank_mask:0xf bound_ctrl:1
	v_add_f32_dpp v49, v49, v49 row_shl:1 row_mask:0xf bank_mask:0xf bound_ctrl:1
	v_add_f32_dpp v50, v50, v50 row_shl:1 row_mask:0xf bank_mask:0xf bound_ctrl:1
	v_add_f32_dpp v51, v51, v51 row_shl:1 row_mask:0xf bank_mask:0xf bound_ctrl:1
	v_mov_b32_e32 v45, v165
	s_nop 1
	v_add_f32_dpp v52, v52, v52 row_shl:2 row_mask:0xf bank_mask:0xf bound_ctrl:1
	v_add_f32_dpp v53, v53, v53 row_shl:2 row_mask:0xf bank_mask:0xf bound_ctrl:1
	v_add_f32_dpp v54, v54, v54 row_shl:2 row_mask:0xf bank_mask:0xf bound_ctrl:1
	v_add_f32_dpp v55, v55, v55 row_shl:2 row_mask:0xf bank_mask:0xf bound_ctrl:1
	v_add_f32_dpp v48, v48, v48 row_shl:2 row_mask:0xf bank_mask:0xf bound_ctrl:1
	v_add_f32_dpp v49, v49, v49 row_shl:2 row_mask:0xf bank_mask:0xf bound_ctrl:1
	v_add_f32_dpp v50, v50, v50 row_shl:2 row_mask:0xf bank_mask:0xf bound_ctrl:1
	v_add_f32_dpp v51, v51, v51 row_shl:2 row_mask:0xf bank_mask:0xf bound_ctrl:1
	v_mov_b32_e32 v39, v159
	s_nop 1
	v_add_f32_dpp v52, v52, v52 row_shl:4 row_mask:0xf bank_mask:0xf bound_ctrl:1
	v_add_f32_dpp v53, v53, v53 row_shl:4 row_mask:0xf bank_mask:0xf bound_ctrl:1
	v_add_f32_dpp v54, v54, v54 row_shl:4 row_mask:0xf bank_mask:0xf bound_ctrl:1
	v_add_f32_dpp v55, v55, v55 row_shl:4 row_mask:0xf bank_mask:0xf bound_ctrl:1
	v_add_f32_dpp v48, v48, v48 row_shl:4 row_mask:0xf bank_mask:0xf bound_ctrl:1
	v_add_f32_dpp v49, v49, v49 row_shl:4 row_mask:0xf bank_mask:0xf bound_ctrl:1
	v_add_f32_dpp v50, v50, v50 row_shl:4 row_mask:0xf bank_mask:0xf bound_ctrl:1
	v_add_f32_dpp v51, v51, v51 row_shl:4 row_mask:0xf bank_mask:0xf bound_ctrl:1
	v_mov_b32_e32 v33, v153
	s_nop 1
	v_add_f32_dpp v52, v52, v52 row_shl:8 row_mask:0xf bank_mask:0xf bound_ctrl:1
	v_add_f32_dpp v53, v53, v53 row_shl:8 row_mask:0xf bank_mask:0xf bound_ctrl:1
	v_add_f32_dpp v54, v54, v54 row_shl:8 row_mask:0xf bank_mask:0xf bound_ctrl:1
	v_add_f32_dpp v55, v55, v55 row_shl:8 row_mask:0xf bank_mask:0xf bound_ctrl:1
	v_add_f32_dpp v48, v48, v48 row_shl:8 row_mask:0xf bank_mask:0xf bound_ctrl:1
	v_add_f32_dpp v49, v49, v49 row_shl:8 row_mask:0xf bank_mask:0xf bound_ctrl:1
	v_add_f32_dpp v50, v50, v50 row_shl:8 row_mask:0xf bank_mask:0xf bound_ctrl:1
	v_add_f32_dpp v51, v51, v51 row_shl:8 row_mask:0xf bank_mask:0xf bound_ctrl:1
	s_nop 1
	v_add_f32_dpp v44, v44, v44 row_shl:1 row_mask:0xf bank_mask:0xf bound_ctrl:1
	v_add_f32_dpp v45, v45, v45 row_shl:1 row_mask:0xf bank_mask:0xf bound_ctrl:1
	v_add_f32_dpp v46, v46, v46 row_shl:1 row_mask:0xf bank_mask:0xf bound_ctrl:1
	v_add_f32_dpp v47, v47, v47 row_shl:1 row_mask:0xf bank_mask:0xf bound_ctrl:1
	v_add_f32_dpp v40, v40, v40 row_shl:1 row_mask:0xf bank_mask:0xf bound_ctrl:1
	v_add_f32_dpp v41, v41, v41 row_shl:1 row_mask:0xf bank_mask:0xf bound_ctrl:1
	v_add_f32_dpp v42, v42, v42 row_shl:1 row_mask:0xf bank_mask:0xf bound_ctrl:1
	v_add_f32_dpp v43, v43, v43 row_shl:1 row_mask:0xf bank_mask:0xf bound_ctrl:1
	v_mov_b32_e32 v36, v156
	s_nop 1
	v_add_f32_dpp v44, v44, v44 row_shl:2 row_mask:0xf bank_mask:0xf bound_ctrl:1
	v_add_f32_dpp v45, v45, v45 row_shl:2 row_mask:0xf bank_mask:0xf bound_ctrl:1
	v_add_f32_dpp v46, v46, v46 row_shl:2 row_mask:0xf bank_mask:0xf bound_ctrl:1
	v_add_f32_dpp v47, v47, v47 row_shl:2 row_mask:0xf bank_mask:0xf bound_ctrl:1
	v_add_f32_dpp v40, v40, v40 row_shl:2 row_mask:0xf bank_mask:0xf bound_ctrl:1
	v_add_f32_dpp v41, v41, v41 row_shl:2 row_mask:0xf bank_mask:0xf bound_ctrl:1
	v_add_f32_dpp v42, v42, v42 row_shl:2 row_mask:0xf bank_mask:0xf bound_ctrl:1
	v_add_f32_dpp v43, v43, v43 row_shl:2 row_mask:0xf bank_mask:0xf bound_ctrl:1
	v_mov_b32_e32 v35, v155
	s_nop 1
	v_add_f32_dpp v44, v44, v44 row_shl:4 row_mask:0xf bank_mask:0xf bound_ctrl:1
	v_add_f32_dpp v45, v45, v45 row_shl:4 row_mask:0xf bank_mask:0xf bound_ctrl:1
	v_add_f32_dpp v46, v46, v46 row_shl:4 row_mask:0xf bank_mask:0xf bound_ctrl:1
	v_add_f32_dpp v47, v47, v47 row_shl:4 row_mask:0xf bank_mask:0xf bound_ctrl:1
	v_add_f32_dpp v40, v40, v40 row_shl:4 row_mask:0xf bank_mask:0xf bound_ctrl:1
	v_add_f32_dpp v41, v41, v41 row_shl:4 row_mask:0xf bank_mask:0xf bound_ctrl:1
	v_add_f32_dpp v42, v42, v42 row_shl:4 row_mask:0xf bank_mask:0xf bound_ctrl:1
	v_add_f32_dpp v43, v43, v43 row_shl:4 row_mask:0xf bank_mask:0xf bound_ctrl:1
	v_mov_b32_e32 v38, v158
	v_mov_b32_e32 v32, v152
	v_mov_b32_e32 v34, v154
	v_mov_b32_e32 v37, v157
	s_nop 1
	v_add_f32_dpp v44, v44, v44 row_shl:8 row_mask:0xf bank_mask:0xf bound_ctrl:1
	v_add_f32_dpp v45, v45, v45 row_shl:8 row_mask:0xf bank_mask:0xf bound_ctrl:1
; template <int DIR> __device__ __forceinline__ void h3_dir(unsigned char* lds, const bf16_t* zrow, int h, const bf16_t* slot, f32x4 (&o)[8]) {
;     ...
;         for (int i = 0; i < 32; ++i) kk[i] = 1.0f - __builtin_amdgcn_exp2f(bl[i]);
;         scan16x8<DIR>(bl); scan16x8<DIR>(bl + 8); scan16x8<DIR>(bl + 16); scan16x8<DIR>(bl + 24);
;         float eb[32];
; #pragma unroll
;         for (int i = 0; i < 32; ++i) { eb[i] = __builtin_amdgcn_exp2f(bl[i]); qin[i] *= eb[i]; }
;         if (r == (DIR ? 0 : 15)) {
; #pragma unroll
;             for (int ks = 0; ks < 4; ++ks) { *(f32x4*)(TOT + wid * 128 + 32 * ks + 8 * kq) = (f32x4){bl[8 * ks], bl[8 * ks + 1], bl[8 * ks + 2], bl[8 * ks + 3]}; *(f32x4*)(TOT + wid * 128 + 32 * ks + 8 * kq + 4) = (f32x4){bl[8 * ks + 4], bl[8 * ks + 5], bl[8 * ks + 6], bl[8 * ks + 7]}; }
; #pragma unroll
;             for (int ks = 0; ks < 4; ++ks) { *(f32x4*)(TOTE + wid * 128 + 32 * ks + 8 * kq) = (f32x4){eb[8 * ks], eb[8 * ks + 1], eb[8 * ks + 2], eb[8 * ks + 3]}; *(f32x4*)(TOTE + wid * 128 + 32 * ks + 8 * kq + 4) = (f32x4){eb[8 * ks + 4], eb[8 * ks + 5], eb[8 * ks + 6], eb[8 * ks + 7]}; }
;         }
	v_add_f32_dpp v46, v46, v46 row_shl:8 row_mask:0xf bank_mask:0xf bound_ctrl:1
	v_add_f32_dpp v47, v47, v47 row_shl:8 row_mask:0xf bank_mask:0xf bound_ctrl:1
	v_add_f32_dpp v40, v40, v40 row_shl:8 row_mask:0xf bank_mask:0xf bound_ctrl:1
	v_add_f32_dpp v41, v41, v41 row_shl:8 row_mask:0xf bank_mask:0xf bound_ctrl:1
	v_add_f32_dpp v42, v42, v42 row_shl:8 row_mask:0xf bank_mask:0xf bound_ctrl:1
	v_add_f32_dpp v43, v43, v43 row_shl:8 row_mask:0xf bank_mask:0xf bound_ctrl:1
	s_nop 1
	v_add_f32_dpp v36, v36, v36 row_shl:1 row_mask:0xf bank_mask:0xf bound_ctrl:1
	v_add_f32_dpp v37, v37, v37 row_shl:1 row_mask:0xf bank_mask:0xf bound_ctrl:1
	v_add_f32_dpp v38, v38, v38 row_shl:1 row_mask:0xf bank_mask:0xf bound_ctrl:1
	v_add_f32_dpp v39, v39, v39 row_shl:1 row_mask:0xf bank_mask:0xf bound_ctrl:1
	v_add_f32_dpp v32, v32, v32 row_shl:1 row_mask:0xf bank_mask:0xf bound_ctrl:1
	v_add_f32_dpp v33, v33, v33 row_shl:1 row_mask:0xf bank_mask:0xf bound_ctrl:1
	v_add_f32_dpp v34, v34, v34 row_shl:1 row_mask:0xf bank_mask:0xf bound_ctrl:1
	v_add_f32_dpp v35, v35, v35 row_shl:1 row_mask:0xf bank_mask:0xf bound_ctrl:1
	v_exp_f32_e32 v92, v64
	s_nop 1
	v_add_f32_dpp v36, v36, v36 row_shl:2 row_mask:0xf bank_mask:0xf bound_ctrl:1
	v_add_f32_dpp v37, v37, v37 row_shl:2 row_mask:0xf bank_mask:0xf bound_ctrl:1
	v_add_f32_dpp v38, v38, v38 row_shl:2 row_mask:0xf bank_mask:0xf bound_ctrl:1
	v_add_f32_dpp v39, v39, v39 row_shl:2 row_mask:0xf bank_mask:0xf bound_ctrl:1
	v_add_f32_dpp v32, v32, v32 row_shl:2 row_mask:0xf bank_mask:0xf bound_ctrl:1
	v_add_f32_dpp v33, v33, v33 row_shl:2 row_mask:0xf bank_mask:0xf bound_ctrl:1
	v_add_f32_dpp v34, v34, v34 row_shl:2 row_mask:0xf bank_mask:0xf bound_ctrl:1
	v_add_f32_dpp v35, v35, v35 row_shl:2 row_mask:0xf bank_mask:0xf bound_ctrl:1
	v_exp_f32_e32 v93, v65
	s_nop 1
	v_add_f32_dpp v36, v36, v36 row_shl:4 row_mask:0xf bank_mask:0xf bound_ctrl:1
	v_add_f32_dpp v37, v37, v37 row_shl:4 row_mask:0xf bank_mask:0xf bound_ctrl:1
	v_add_f32_dpp v38, v38, v38 row_shl:4 row_mask:0xf bank_mask:0xf bound_ctrl:1
	v_add_f32_dpp v39, v39, v39 row_shl:4 row_mask:0xf bank_mask:0xf bound_ctrl:1
	v_add_f32_dpp v32, v32, v32 row_shl:4 row_mask:0xf bank_mask:0xf bound_ctrl:1
	v_add_f32_dpp v33, v33, v33 row_shl:4 row_mask:0xf bank_mask:0xf bound_ctrl:1
	v_add_f32_dpp v34, v34, v34 row_shl:4 row_mask:0xf bank_mask:0xf bound_ctrl:1
	v_add_f32_dpp v35, v35, v35 row_shl:4 row_mask:0xf bank_mask:0xf bound_ctrl:1
	v_exp_f32_e32 v94, v66
	s_nop 1
	v_add_f32_dpp v36, v36, v36 row_shl:8 row_mask:0xf bank_mask:0xf bound_ctrl:1
	v_add_f32_dpp v37, v37, v37 row_shl:8 row_mask:0xf bank_mask:0xf bound_ctrl:1
	v_add_f32_dpp v38, v38, v38 row_shl:8 row_mask:0xf bank_mask:0xf bound_ctrl:1
	v_add_f32_dpp v39, v39, v39 row_shl:8 row_mask:0xf bank_mask:0xf bound_ctrl:1
	v_add_f32_dpp v32, v32, v32 row_shl:8 row_mask:0xf bank_mask:0xf bound_ctrl:1
	v_add_f32_dpp v33, v33, v33 row_shl:8 row_mask:0xf bank_mask:0xf bound_ctrl:1
	v_add_f32_dpp v34, v34, v34 row_shl:8 row_mask:0xf bank_mask:0xf bound_ctrl:1
	v_add_f32_dpp v35, v35, v35 row_shl:8 row_mask:0xf bank_mask:0xf bound_ctrl:1
	v_exp_f32_e32 v95, v67
	v_exp_f32_e32 v88, v60
	v_exp_f32_e32 v89, v61
	v_exp_f32_e32 v90, v62
	v_exp_f32_e32 v91, v63
	v_exp_f32_e32 v84, v52
	v_exp_f32_e32 v85, v53
	v_exp_f32_e32 v86, v54
	v_exp_f32_e32 v87, v55
	v_exp_f32_e32 v80, v48
	v_exp_f32_e32 v81, v49
	v_exp_f32_e32 v82, v50
	v_exp_f32_e32 v83, v51
	v_exp_f32_e32 v76, v44
	v_exp_f32_e32 v77, v45
	v_exp_f32_e32 v78, v46
	v_exp_f32_e32 v79, v47
	v_exp_f32_e32 v72, v40
	v_exp_f32_e32 v73, v41
	v_exp_f32_e32 v74, v42
	v_exp_f32_e32 v75, v43
	v_exp_f32_e32 v68, v36
	v_exp_f32_e32 v69, v37
	v_exp_f32_e32 v70, v38
	v_exp_f32_e32 v71, v39
	v_exp_f32_e32 v56, v32
	v_exp_f32_e32 v57, v33
	v_exp_f32_e32 v58, v34
	v_exp_f32_e32 v59, v35
	s_and_saveexec_b64 s[6:7], vcc
	s_cbranch_execz .LBB0_2621
	s_add_i32 s37, s3, 0
	v_lshl_add_u32 v183, v148, 2, s37
	ds_write_b128 v183, v[64:67]
	ds_write_b128 v183, v[60:63] offset:16
	ds_write_b128 v183, v[52:55] offset:128
	ds_write_b128 v183, v[48:51] offset:144
	ds_write_b128 v183, v[44:47] offset:256
	ds_write_b128 v183, v[40:43] offset:272
	ds_write_b128 v183, v[36:39] offset:384
	ds_write_b128 v183, v[32:35] offset:400
	ds_write_b128 v183, v[92:95] offset:4096
	ds_write_b128 v183, v[88:91] offset:4112
	ds_write_b128 v183, v[84:87] offset:4224
	ds_write_b128 v183, v[80:83] offset:4240
	ds_write_b128 v183, v[76:79] offset:4352
	ds_write_b128 v183, v[72:75] offset:4368
	ds_write_b128 v183, v[68:71] offset:4480
	ds_write_b128 v183, v[56:59] offset:4496
